# v65 + non-temporal hint on the mixer's read-once loads (keep weights resident in L2/MALL)
# speedup vs baseline: 1.0031x; 1.0031x over previous
; __device__ __forceinline__ f32x2 un2(unsigned u) { return (f32x2){bf_lo(u), bf_hi(u)}; }
; __device__ __forceinline__ void st2(bf16_t* p, f32x2 v) { *(unsigned*)p = cvt_pk_bf16(v.x, v.y); }
; __device__ __forceinline__ float silu_f(float x) { return x * sigmoid_f(x); }
; #define MIX_ISSUED() asm volatile("" ::: "memory")
; __device__ __forceinline__ void mixer_phase(const Args& a, int l, LAS unsigned char* lds, int tile0, int tstride, int tend) {
;     ...
;             const f32x2 lg = *(const f32x2*)(a.in[I_LNG] + (size_t)l * EW + e0), lb = *(const f32x2*)(a.in[I_LNB] + (size_t)l * EW + e0);
;             unsigned rz[TT];
; #pragma unroll
;             for (int i = 0; i < TT; ++i) rz[i] = *(const unsigned*)(Pt + (size_t)i * NCO + OCZ);
;             MIX_ISSUED();
; #pragma unroll
;             for (int i = 0; i < TT; ++i) {
;                 const float mean = fin[2 * i] * (1.0f / EW);
;                 const float var = fmaxf(fin[2 * i + 1] * (1.0f / EW) - mean * mean, 0.f);
;                 const float rstd = __builtin_amdgcn_rsqf(var + LN_EPS);
;                 f32x2 y = (acc[i] - mean) * rstd * lg + lb;
;                 y.x = silu_f(y.x); y.y = silu_f(y.y);
;                 st2(Y + (size_t)(t0 + i) * YW + 2 * EW + e0, y * un2(rz[i]));
.LBB0_377:
	s_or_b64 exec, exec, s[4:5]
	s_waitcnt lgkmcnt(0)
	s_barrier
	global_load_dwordx2 v[104:105], v[20:21], off nt
	global_load_dwordx2 v[106:107], v[22:23], off nt
	v_add_co_u32_e32 v4, vcc, 0x2000, v2
	s_add_u32 s4, s70, s37
	s_nop 0
	v_addc_co_u32_e32 v5, vcc, 0, v3, vcc
	global_load_dword v145, v[4:5], off offset:2048 nt
	v_add_co_u32_e32 v4, vcc, 0x7000, v2
	s_addc_u32 s5, s71, s36
	s_nop 0
	v_addc_co_u32_e32 v5, vcc, 0, v3, vcc
	global_load_dword v152, v[4:5], off nt
	v_add_co_u32_e32 v4, vcc, 0xb000, v2
	s_nop 1
	v_addc_co_u32_e32 v5, vcc, 0, v3, vcc
	global_load_dword v153, v[4:5], off offset:2048 nt
	v_add_co_u32_e32 v4, vcc, 0x10000, v2
	s_nop 1
	v_addc_co_u32_e32 v5, vcc, 0, v3, vcc
	global_load_dword v144, v[4:5], off nt
	v_add_co_u32_e32 v4, vcc, 0x14000, v2
	s_nop 1
	v_addc_co_u32_e32 v5, vcc, 0, v3, vcc
	global_load_dword v143, v[4:5], off offset:2048 nt
	v_add_co_u32_e32 v4, vcc, 0x19000, v2
	s_nop 1
	v_addc_co_u32_e32 v5, vcc, 0, v3, vcc
	global_load_dword v142, v[4:5], off nt
	v_add_co_u32_e32 v4, vcc, 0x1d000, v2
	s_nop 1
	v_addc_co_u32_e32 v5, vcc, 0, v3, vcc
	global_load_dword v141, v[4:5], off offset:2048 nt
	v_add_co_u32_e32 v4, vcc, 0x22000, v2
	s_nop 1
	v_addc_co_u32_e32 v5, vcc, 0, v3, vcc
	global_load_dword v140, v[4:5], off nt
	v_add_co_u32_e32 v4, vcc, 0x26000, v2
	s_nop 1
	v_addc_co_u32_e32 v5, vcc, 0, v3, vcc
	global_load_dword v139, v[4:5], off offset:2048 nt
	v_add_co_u32_e32 v4, vcc, 0x2b000, v2
	s_nop 1
	v_addc_co_u32_e32 v5, vcc, 0, v3, vcc
	global_load_dword v138, v[4:5], off nt
	v_add_co_u32_e32 v4, vcc, 0x2f000, v2
	s_nop 1
	v_addc_co_u32_e32 v5, vcc, 0, v3, vcc
	global_load_dword v137, v[4:5], off offset:2048 nt
	v_add_co_u32_e32 v4, vcc, 0x34000, v2
	s_nop 1
	v_addc_co_u32_e32 v5, vcc, 0, v3, vcc
	global_load_dword v136, v[4:5], off nt
	v_add_co_u32_e32 v4, vcc, 0x38000, v2
	s_nop 1
	v_addc_co_u32_e32 v5, vcc, 0, v3, vcc
	global_load_dword v135, v[4:5], off offset:2048 nt
	v_add_co_u32_e32 v4, vcc, 0x3d000, v2
	s_nop 1
	v_addc_co_u32_e32 v5, vcc, 0, v3, vcc
	global_load_dword v134, v[4:5], off nt
	v_add_co_u32_e32 v4, vcc, 0x41000, v2
	s_nop 1
	v_addc_co_u32_e32 v5, vcc, 0, v3, vcc
	v_add_co_u32_e32 v2, vcc, 0x46000, v2
	global_load_dword v133, v[4:5], off offset:2048 nt
	s_nop 0
	v_addc_co_u32_e32 v3, vcc, 0, v3, vcc
	global_load_dword v132, v[2:3], off nt
	ds_read_b128 v[146:149], v0 offset:1024
	ds_read_b128 v[10:13], v0 offset:1040
	ds_read_b128 v[6:9], v0 offset:1056
	ds_read_b128 v[2:5], v0 offset:1072
	s_waitcnt lgkmcnt(3)
	v_pk_mul_f32 v[146:147], v[146:147], s[90:91] op_sel_hi:[1,0]
	s_nop 0
	v_fma_f32 v150, -v146, v146, v147
	v_max_f32_e32 v150, 0, v150
	v_add_f32_e32 v150, 0x3727c5ac, v150
	v_rsq_f32_e32 v150, v150
	v_pk_add_f32 v[122:123], v[122:123], v[146:147] op_sel_hi:[1,0] neg_lo:[0,1] neg_hi:[0,1]
	s_waitcnt lgkmcnt(2)
	v_pk_mul_f32 v[10:11], v[10:11], s[90:91] op_sel_hi:[1,0]
	s_waitcnt lgkmcnt(1)
	v_pk_mul_f32 v[6:7], v[6:7], s[90:91] op_sel_hi:[1,0]
	v_pk_mul_f32 v[122:123], v[122:123], v[150:151] op_sel_hi:[1,0]
	s_waitcnt vmcnt(15)
	v_lshlrev_b32_e32 v150, 16, v145
	v_pk_fma_f32 v[122:123], v[104:105], v[122:123], v[106:107]
	v_and_b32_e32 v151, 0xffff0000, v145
	v_mul_f32_e32 v146, 0xbfb8aa3b, v122
	v_mul_f32_e32 v147, 0xbfb8aa3b, v123
	v_exp_f32_e32 v146, v146
	v_exp_f32_e32 v147, v147
	s_waitcnt lgkmcnt(0)
	v_pk_mul_f32 v[2:3], v[2:3], s[90:91] op_sel_hi:[1,0]
	v_add_f32_e32 v146, 1.0, v146
	v_add_f32_e32 v147, 1.0, v147
	v_rcp_f32_e32 v146, v146
	v_rcp_f32_e32 v147, v147
	s_nop 0
	v_pk_mul_f32 v[122:123], v[122:123], v[146:147]
	v_lshl_add_u64 v[146:147], s[4:5], 0, v[24:25]
	v_pk_mul_f32 v[122:123], v[122:123], v[150:151]
	s_add_u32 s4, s70, s35
	v_cvt_pk_bf16_f32 v145, v122, v123
	v_add_co_u32_e32 v122, vcc, s14, v146
	s_addc_u32 s5, s71, s34
	s_nop 0
	v_addc_co_u32_e32 v123, vcc, 0, v147, vcc
	global_store_dword v[122:123], v145, off
	v_pk_mul_f32 v[122:123], v[148:149], s[90:91] op_sel_hi:[1,0]
	s_nop 0
	v_fma_f32 v145, -v122, v122, v123
	v_max_f32_e32 v145, 0, v145
	v_add_f32_e32 v145, 0x3727c5ac, v145
	v_rsq_f32_e32 v146, v145
	v_pk_add_f32 v[120:121], v[120:121], v[122:123] op_sel_hi:[1,0] neg_lo:[0,1] neg_hi:[0,1]
	s_nop 0
	v_pk_mul_f32 v[120:121], v[120:121], v[146:147] op_sel_hi:[1,0]
	s_nop 0
	v_pk_fma_f32 v[120:121], v[104:105], v[120:121], v[106:107]
	s_waitcnt vmcnt(15)
	v_lshlrev_b32_e32 v146, 16, v152
	v_mul_f32_e32 v122, 0xbfb8aa3b, v120
	v_mul_f32_e32 v123, 0xbfb8aa3b, v121
	v_exp_f32_e32 v122, v122
	v_exp_f32_e32 v123, v123
	v_and_b32_e32 v147, 0xffff0000, v152
	v_add_f32_e32 v122, 1.0, v122
	v_add_f32_e32 v123, 1.0, v123
	v_rcp_f32_e32 v122, v122
	v_rcp_f32_e32 v123, v123
	s_nop 0
	v_pk_mul_f32 v[120:121], v[120:121], v[122:123]
	v_lshl_add_u64 v[122:123], s[4:5], 0, v[24:25]
	v_pk_mul_f32 v[120:121], v[120:121], v[146:147]
	s_add_u32 s4, s70, s31
	v_cvt_pk_bf16_f32 v145, v120, v121
	v_add_co_u32_e32 v120, vcc, s14, v122
	s_addc_u32 s5, s71, s30
	s_nop 0
	v_addc_co_u32_e32 v121, vcc, 0, v123, vcc
	global_store_dword v[120:121], v145, off
	v_fma_f32 v120, -v10, v10, v11
	v_max_f32_e32 v120, 0, v120
	v_add_f32_e32 v120, 0x3727c5ac, v120
	v_rsq_f32_e32 v120, v120
	v_pk_add_f32 v[10:11], v[130:131], v[10:11] op_sel_hi:[1,0] neg_lo:[0,1] neg_hi:[0,1]
	s_waitcnt vmcnt(15)
; __device__ __forceinline__ f32x2 un2(unsigned u) { return (f32x2){bf_lo(u), bf_hi(u)}; }
; __device__ __forceinline__ void st2(bf16_t* p, f32x2 v) { *(unsigned*)p = cvt_pk_bf16(v.x, v.y); }
; __device__ __forceinline__ float silu_f(float x) { return x * sigmoid_f(x); }
; __device__ __forceinline__ void mixer_phase(const Args& a, int l, LAS unsigned char* lds, int tile0, int tstride, int tend) {
;     ...
; #pragma unroll
;             for (int i = 0; i < TT; ++i) {
;                 const float mean = fin[2 * i] * (1.0f / EW);
;                 const float var = fmaxf(fin[2 * i + 1] * (1.0f / EW) - mean * mean, 0.f);
;                 const float rstd = __builtin_amdgcn_rsqf(var + LN_EPS);
;                 f32x2 y = (acc[i] - mean) * rstd * lg + lb;
;                 y.x = silu_f(y.x); y.y = silu_f(y.y);
;                 st2(Y + (size_t)(t0 + i) * YW + 2 * EW + e0, y * un2(rz[i]));
;             }
	v_lshlrev_b32_e32 v122, 16, v153
	v_and_b32_e32 v123, 0xffff0000, v153
	v_pk_mul_f32 v[10:11], v[10:11], v[120:121] op_sel_hi:[1,0]
	s_nop 0
	v_pk_fma_f32 v[10:11], v[104:105], v[10:11], v[106:107]
	s_nop 0
	v_mul_f32_e32 v120, 0xbfb8aa3b, v10
	v_mul_f32_e32 v121, 0xbfb8aa3b, v11
	v_exp_f32_e32 v120, v120
	v_exp_f32_e32 v121, v121
	v_add_f32_e32 v120, 1.0, v120
	v_add_f32_e32 v121, 1.0, v121
	v_rcp_f32_e32 v120, v120
	v_rcp_f32_e32 v121, v121
	s_nop 0
	v_pk_mul_f32 v[10:11], v[10:11], v[120:121]
	v_lshl_add_u64 v[120:121], s[4:5], 0, v[24:25]
	v_pk_mul_f32 v[10:11], v[10:11], v[122:123]
	s_add_u32 s4, s70, s95
	v_cvt_pk_bf16_f32 v122, v10, v11
	v_add_co_u32_e32 v10, vcc, s14, v120
	s_addc_u32 s5, s71, s94
	s_nop 0
	v_addc_co_u32_e32 v11, vcc, 0, v121, vcc
	global_store_dword v[10:11], v122, off
	v_pk_mul_f32 v[10:11], v[12:13], s[90:91] op_sel_hi:[1,0]
	s_waitcnt vmcnt(15)
	v_lshlrev_b32_e32 v120, 16, v144
	v_fma_f32 v12, -v10, v10, v11
	v_max_f32_e32 v12, 0, v12
	v_add_f32_e32 v12, 0x3727c5ac, v12
	v_rsq_f32_e32 v12, v12
	v_pk_add_f32 v[10:11], v[128:129], v[10:11] op_sel_hi:[1,0] neg_lo:[0,1] neg_hi:[0,1]
	v_and_b32_e32 v121, 0xffff0000, v144
	v_pk_mul_f32 v[10:11], v[10:11], v[12:13] op_sel_hi:[1,0]
	s_nop 0
	v_pk_fma_f32 v[10:11], v[104:105], v[10:11], v[106:107]
	s_nop 0
	v_mul_f32_e32 v12, 0xbfb8aa3b, v10
	v_mul_f32_e32 v13, 0xbfb8aa3b, v11
	v_exp_f32_e32 v12, v12
	v_exp_f32_e32 v13, v13
	v_add_f32_e32 v12, 1.0, v12
	v_add_f32_e32 v13, 1.0, v13
	v_rcp_f32_e32 v12, v12
	v_rcp_f32_e32 v13, v13
	s_nop 0
	v_pk_mul_f32 v[10:11], v[10:11], v[12:13]
	v_lshl_add_u64 v[12:13], s[4:5], 0, v[24:25]
	v_pk_mul_f32 v[10:11], v[10:11], v[120:121]
	s_add_u32 s4, s70, s93
	v_cvt_pk_bf16_f32 v120, v10, v11
	v_add_co_u32_e32 v10, vcc, s14, v12
	s_addc_u32 s5, s71, s92
	s_nop 0
	v_addc_co_u32_e32 v11, vcc, 0, v13, vcc
	global_store_dword v[10:11], v120, off
	v_fma_f32 v10, -v6, v6, v7
	v_max_f32_e32 v10, 0, v10
	v_add_f32_e32 v10, 0x3727c5ac, v10
	v_rsq_f32_e32 v10, v10
	v_pk_add_f32 v[6:7], v[126:127], v[6:7] op_sel_hi:[1,0] neg_lo:[0,1] neg_hi:[0,1]
	s_waitcnt vmcnt(15)
	v_lshlrev_b32_e32 v12, 16, v143
	v_and_b32_e32 v13, 0xffff0000, v143
	v_pk_mul_f32 v[6:7], v[6:7], v[10:11] op_sel_hi:[1,0]
	s_nop 0
	v_pk_fma_f32 v[6:7], v[104:105], v[6:7], v[106:107]
	s_nop 0
	v_mul_f32_e32 v10, 0xbfb8aa3b, v6
	v_mul_f32_e32 v11, 0xbfb8aa3b, v7
	v_exp_f32_e32 v10, v10
	v_exp_f32_e32 v11, v11
	v_add_f32_e32 v10, 1.0, v10
	v_add_f32_e32 v11, 1.0, v11
	v_rcp_f32_e32 v10, v10
	v_rcp_f32_e32 v11, v11
	s_nop 0
	v_pk_mul_f32 v[6:7], v[6:7], v[10:11]
	v_lshl_add_u64 v[10:11], s[4:5], 0, v[24:25]
	v_pk_mul_f32 v[6:7], v[6:7], v[12:13]
	s_add_u32 s4, s70, s29
	v_cvt_pk_bf16_f32 v12, v6, v7
	v_add_co_u32_e32 v6, vcc, s14, v10
	s_addc_u32 s5, s71, s28
	s_nop 0
	v_addc_co_u32_e32 v7, vcc, 0, v11, vcc
	global_store_dword v[6:7], v12, off
	v_pk_mul_f32 v[6:7], v[8:9], s[90:91] op_sel_hi:[1,0]
	s_waitcnt vmcnt(15)
	v_lshlrev_b32_e32 v10, 16, v142
	v_fma_f32 v8, -v6, v6, v7
	v_max_f32_e32 v8, 0, v8
	v_add_f32_e32 v8, 0x3727c5ac, v8
	v_rsq_f32_e32 v8, v8
	v_pk_add_f32 v[6:7], v[124:125], v[6:7] op_sel_hi:[1,0] neg_lo:[0,1] neg_hi:[0,1]
	v_and_b32_e32 v11, 0xffff0000, v142
	s_waitcnt vmcnt(8)
	v_lshlrev_b32_e32 v12, 16, v135
	v_pk_mul_f32 v[6:7], v[6:7], v[8:9] op_sel_hi:[1,0]
	v_and_b32_e32 v13, 0xffff0000, v135
	v_pk_fma_f32 v[6:7], v[104:105], v[6:7], v[106:107]
	s_nop 0
	v_mul_f32_e32 v8, 0xbfb8aa3b, v6
	v_mul_f32_e32 v9, 0xbfb8aa3b, v7
	v_exp_f32_e32 v8, v8
	v_exp_f32_e32 v9, v9
	v_add_f32_e32 v8, 1.0, v8
	v_add_f32_e32 v9, 1.0, v9
	v_rcp_f32_e32 v8, v8
	v_rcp_f32_e32 v9, v9
	s_nop 0
	v_pk_mul_f32 v[6:7], v[6:7], v[8:9]
	v_lshl_add_u64 v[8:9], s[4:5], 0, v[24:25]
	v_pk_mul_f32 v[6:7], v[6:7], v[10:11]
	s_add_u32 s4, s70, s80
	v_cvt_pk_bf16_f32 v10, v6, v7
	v_add_co_u32_e32 v6, vcc, s14, v8
	s_addc_u32 s5, s71, s63
	s_nop 0
	v_addc_co_u32_e32 v7, vcc, 0, v9, vcc
	global_store_dword v[6:7], v10, off
	v_fma_f32 v6, -v2, v2, v3
	v_max_f32_e32 v6, 0, v6
	v_add_f32_e32 v6, 0x3727c5ac, v6
	v_rsq_f32_e32 v6, v6
	v_pk_add_f32 v[2:3], v[118:119], v[2:3] op_sel_hi:[1,0] neg_lo:[0,1] neg_hi:[0,1]
	v_lshlrev_b32_e32 v8, 16, v141
	v_and_b32_e32 v9, 0xffff0000, v141
	v_pk_mul_f32 v[2:3], v[2:3], v[6:7] op_sel_hi:[1,0]
	s_nop 0
	v_pk_fma_f32 v[2:3], v[104:105], v[2:3], v[106:107]
	s_nop 0
	v_mul_f32_e32 v6, 0xbfb8aa3b, v2
	v_mul_f32_e32 v7, 0xbfb8aa3b, v3
	v_exp_f32_e32 v6, v6
	v_exp_f32_e32 v7, v7
	v_add_f32_e32 v6, 1.0, v6
	v_add_f32_e32 v7, 1.0, v7
	v_rcp_f32_e32 v6, v6
	v_rcp_f32_e32 v7, v7
	s_nop 0
	v_pk_mul_f32 v[2:3], v[2:3], v[6:7]
	v_lshl_add_u64 v[6:7], s[4:5], 0, v[24:25]
	v_pk_mul_f32 v[2:3], v[2:3], v[8:9]
	s_add_u32 s4, s70, s62
	v_cvt_pk_bf16_f32 v8, v2, v3
	v_add_co_u32_e32 v2, vcc, s14, v6
	s_addc_u32 s5, s71, s56
	s_nop 0
	v_addc_co_u32_e32 v3, vcc, 0, v7, vcc
	global_store_dword v[2:3], v8, off
	v_pk_mul_f32 v[2:3], v[4:5], s[90:91] op_sel_hi:[1,0]
	v_lshlrev_b32_e32 v6, 16, v140
	v_fma_f32 v4, -v2, v2, v3
	v_max_f32_e32 v4, 0, v4
	v_add_f32_e32 v4, 0x3727c5ac, v4
	v_rsq_f32_e32 v4, v4
	v_pk_add_f32 v[2:3], v[116:117], v[2:3] op_sel_hi:[1,0] neg_lo:[0,1] neg_hi:[0,1]
	v_and_b32_e32 v7, 0xffff0000, v140
	v_lshlrev_b32_e32 v8, 16, v139
	v_pk_mul_f32 v[2:3], v[2:3], v[4:5] op_sel_hi:[1,0]
	v_and_b32_e32 v9, 0xffff0000, v139
	v_pk_fma_f32 v[2:3], v[104:105], v[2:3], v[106:107]
	s_nop 0
	v_mul_f32_e32 v4, 0xbfb8aa3b, v2
	v_mul_f32_e32 v5, 0xbfb8aa3b, v3
	v_exp_f32_e32 v4, v4
	v_exp_f32_e32 v5, v5
	v_add_f32_e32 v4, 1.0, v4
	v_add_f32_e32 v5, 1.0, v5
	v_rcp_f32_e32 v4, v4
	v_rcp_f32_e32 v5, v5
	s_nop 0
	v_pk_mul_f32 v[2:3], v[2:3], v[4:5]
	v_lshl_add_u64 v[4:5], s[4:5], 0, v[24:25]
	v_pk_mul_f32 v[2:3], v[2:3], v[6:7]
	s_add_u32 s4, s70, s55
	v_cvt_pk_bf16_f32 v6, v2, v3
	v_add_co_u32_e32 v2, vcc, s14, v4
	s_addc_u32 s5, s71, s54
	s_nop 0
	v_addc_co_u32_e32 v3, vcc, 0, v5, vcc
	global_store_dword v[2:3], v6, off
	ds_read_b128 v[2:5], v0 offset:1088
	s_waitcnt lgkmcnt(0)
; __device__ __forceinline__ f32x2 un2(unsigned u) { return (f32x2){bf_lo(u), bf_hi(u)}; }
; __device__ __forceinline__ void st2(bf16_t* p, f32x2 v) { *(unsigned*)p = cvt_pk_bf16(v.x, v.y); }
; __device__ __forceinline__ float silu_f(float x) { return x * sigmoid_f(x); }
; __device__ __forceinline__ void mixer_phase(const Args& a, int l, LAS unsigned char* lds, int tile0, int tstride, int tend) {
;     ...
; #pragma unroll
;             for (int i = 0; i < TT; ++i) {
;                 const float mean = fin[2 * i] * (1.0f / EW);
;                 const float var = fmaxf(fin[2 * i + 1] * (1.0f / EW) - mean * mean, 0.f);
;                 const float rstd = __builtin_amdgcn_rsqf(var + LN_EPS);
;                 f32x2 y = (acc[i] - mean) * rstd * lg + lb;
;                 y.x = silu_f(y.x); y.y = silu_f(y.y);
;                 st2(Y + (size_t)(t0 + i) * YW + 2 * EW + e0, y * un2(rz[i]));
;             }
	v_pk_mul_f32 v[2:3], v[2:3], s[90:91] op_sel_hi:[1,0]
	s_nop 0
	v_fma_f32 v6, -v2, v2, v3
	v_max_f32_e32 v6, 0, v6
	v_add_f32_e32 v6, 0x3727c5ac, v6
	v_rsq_f32_e32 v6, v6
	v_pk_add_f32 v[2:3], v[114:115], v[2:3] op_sel_hi:[1,0] neg_lo:[0,1] neg_hi:[0,1]
	s_nop 0
	v_pk_mul_f32 v[2:3], v[2:3], v[6:7] op_sel_hi:[1,0]
	s_nop 0
	v_pk_fma_f32 v[2:3], v[104:105], v[2:3], v[106:107]
	s_nop 0
	v_mul_f32_e32 v6, 0xbfb8aa3b, v2
	v_mul_f32_e32 v7, 0xbfb8aa3b, v3
	v_exp_f32_e32 v6, v6
	v_exp_f32_e32 v7, v7
	v_add_f32_e32 v6, 1.0, v6
	v_add_f32_e32 v7, 1.0, v7
	v_rcp_f32_e32 v6, v6
	v_rcp_f32_e32 v7, v7
	s_nop 0
	v_pk_mul_f32 v[2:3], v[2:3], v[6:7]
	v_lshl_add_u64 v[6:7], s[4:5], 0, v[24:25]
	v_pk_mul_f32 v[2:3], v[2:3], v[8:9]
	s_add_u32 s4, s70, s27
	v_cvt_pk_bf16_f32 v8, v2, v3
	v_add_co_u32_e32 v2, vcc, s14, v6
	s_addc_u32 s5, s71, s26
	s_nop 0
	v_addc_co_u32_e32 v3, vcc, 0, v7, vcc
	global_store_dword v[2:3], v8, off
	v_pk_mul_f32 v[2:3], v[4:5], s[90:91] op_sel_hi:[1,0]
	v_lshlrev_b32_e32 v6, 16, v138
	v_fma_f32 v4, -v2, v2, v3
	v_max_f32_e32 v4, 0, v4
	v_add_f32_e32 v4, 0x3727c5ac, v4
	v_rsq_f32_e32 v4, v4
	v_pk_add_f32 v[2:3], v[112:113], v[2:3] op_sel_hi:[1,0] neg_lo:[0,1] neg_hi:[0,1]
	v_and_b32_e32 v7, 0xffff0000, v138
	v_lshlrev_b32_e32 v8, 16, v137
	v_pk_mul_f32 v[2:3], v[2:3], v[4:5] op_sel_hi:[1,0]
	v_and_b32_e32 v9, 0xffff0000, v137
	v_pk_fma_f32 v[2:3], v[104:105], v[2:3], v[106:107]
	s_nop 0
	v_mul_f32_e32 v4, 0xbfb8aa3b, v2
	v_mul_f32_e32 v5, 0xbfb8aa3b, v3
	v_exp_f32_e32 v4, v4
	v_exp_f32_e32 v5, v5
	v_add_f32_e32 v4, 1.0, v4
	v_add_f32_e32 v5, 1.0, v5
	v_rcp_f32_e32 v4, v4
	v_rcp_f32_e32 v5, v5
	s_nop 0
	v_pk_mul_f32 v[2:3], v[2:3], v[4:5]
	v_lshl_add_u64 v[4:5], s[4:5], 0, v[24:25]
	v_pk_mul_f32 v[2:3], v[2:3], v[6:7]
	s_add_u32 s4, s70, s25
	v_cvt_pk_bf16_f32 v6, v2, v3
	v_add_co_u32_e32 v2, vcc, s14, v4
	s_addc_u32 s5, s71, s24
	s_nop 0
	v_addc_co_u32_e32 v3, vcc, 0, v5, vcc
	global_store_dword v[2:3], v6, off
	ds_read_b128 v[2:5], v0 offset:1104
	s_waitcnt lgkmcnt(0)
	v_pk_mul_f32 v[2:3], v[2:3], s[90:91] op_sel_hi:[1,0]
	s_nop 0
	v_fma_f32 v6, -v2, v2, v3
	v_max_f32_e32 v6, 0, v6
	v_add_f32_e32 v6, 0x3727c5ac, v6
	v_rsq_f32_e32 v6, v6
	v_pk_add_f32 v[2:3], v[110:111], v[2:3] op_sel_hi:[1,0] neg_lo:[0,1] neg_hi:[0,1]
	s_nop 0
	v_pk_mul_f32 v[2:3], v[2:3], v[6:7] op_sel_hi:[1,0]
	s_nop 0
	v_pk_fma_f32 v[2:3], v[104:105], v[2:3], v[106:107]
	s_nop 0
	v_mul_f32_e32 v6, 0xbfb8aa3b, v2
	v_mul_f32_e32 v7, 0xbfb8aa3b, v3
	v_exp_f32_e32 v6, v6
	v_exp_f32_e32 v7, v7
	v_add_f32_e32 v6, 1.0, v6
	v_add_f32_e32 v7, 1.0, v7
	v_rcp_f32_e32 v6, v6
	v_rcp_f32_e32 v7, v7
	s_nop 0
	v_pk_mul_f32 v[2:3], v[2:3], v[6:7]
	v_lshl_add_u64 v[6:7], s[4:5], 0, v[24:25]
	v_pk_mul_f32 v[2:3], v[2:3], v[8:9]
	s_add_u32 s4, s70, s23
	v_cvt_pk_bf16_f32 v8, v2, v3
	v_add_co_u32_e32 v2, vcc, s14, v6
	s_addc_u32 s5, s71, s19
	s_nop 0
	v_addc_co_u32_e32 v3, vcc, 0, v7, vcc
	global_store_dword v[2:3], v8, off
	v_pk_mul_f32 v[2:3], v[4:5], s[90:91] op_sel_hi:[1,0]
	v_lshlrev_b32_e32 v6, 16, v136
	v_fma_f32 v4, -v2, v2, v3
	v_max_f32_e32 v4, 0, v4
	v_add_f32_e32 v4, 0x3727c5ac, v4
	v_rsq_f32_e32 v4, v4
	v_pk_add_f32 v[2:3], v[108:109], v[2:3] op_sel_hi:[1,0] neg_lo:[0,1] neg_hi:[0,1]
	v_and_b32_e32 v7, 0xffff0000, v136
	v_pk_mul_f32 v[2:3], v[2:3], v[4:5] op_sel_hi:[1,0]
	s_nop 0
	v_pk_fma_f32 v[2:3], v[104:105], v[2:3], v[106:107]
	s_nop 0
	v_mul_f32_e32 v4, 0xbfb8aa3b, v2
	v_mul_f32_e32 v5, 0xbfb8aa3b, v3
	v_exp_f32_e32 v4, v4
	v_exp_f32_e32 v5, v5
	v_add_f32_e32 v4, 1.0, v4
	v_add_f32_e32 v5, 1.0, v5
	v_rcp_f32_e32 v4, v4
	v_rcp_f32_e32 v5, v5
	s_nop 0
	v_pk_mul_f32 v[2:3], v[2:3], v[4:5]
	v_lshl_add_u64 v[4:5], s[4:5], 0, v[24:25]
	v_pk_mul_f32 v[2:3], v[2:3], v[6:7]
	s_add_u32 s4, s70, s18
	v_cvt_pk_bf16_f32 v6, v2, v3
	v_add_co_u32_e32 v2, vcc, s14, v4
	s_addc_u32 s5, s71, s17
	s_nop 0
	v_addc_co_u32_e32 v3, vcc, 0, v5, vcc
	global_store_dword v[2:3], v6, off
	ds_read_b128 v[6:9], v0 offset:1120
	ds_read_b128 v[2:5], v0 offset:1136
	s_waitcnt lgkmcnt(1)
	v_pk_mul_f32 v[6:7], v[6:7], s[90:91] op_sel_hi:[1,0]
	s_nop 0
	v_fma_f32 v10, -v6, v6, v7
	v_max_f32_e32 v10, 0, v10
	v_add_f32_e32 v10, 0x3727c5ac, v10
	v_rsq_f32_e32 v10, v10
	v_pk_add_f32 v[6:7], v[102:103], v[6:7] op_sel_hi:[1,0] neg_lo:[0,1] neg_hi:[0,1]
	s_waitcnt lgkmcnt(0)
	v_pk_mul_f32 v[2:3], v[2:3], s[90:91] op_sel_hi:[1,0]
	v_pk_mul_f32 v[6:7], v[6:7], v[10:11] op_sel_hi:[1,0]
	s_nop 0
	v_pk_fma_f32 v[6:7], v[104:105], v[6:7], v[106:107]
	s_nop 0
	v_mul_f32_e32 v10, 0xbfb8aa3b, v6
	v_mul_f32_e32 v11, 0xbfb8aa3b, v7
	v_exp_f32_e32 v10, v10
	v_exp_f32_e32 v11, v11
	v_add_f32_e32 v10, 1.0, v10
	v_add_f32_e32 v11, 1.0, v11
	v_rcp_f32_e32 v10, v10
	v_rcp_f32_e32 v11, v11
	s_nop 0
	v_pk_mul_f32 v[6:7], v[6:7], v[10:11]
	v_lshl_add_u64 v[10:11], s[4:5], 0, v[24:25]
	v_pk_mul_f32 v[6:7], v[6:7], v[12:13]
	s_add_u32 s4, s70, s16
	v_cvt_pk_bf16_f32 v12, v6, v7
	v_add_co_u32_e32 v6, vcc, s14, v10
	s_addc_u32 s5, s71, s15
	s_nop 0
	v_addc_co_u32_e32 v7, vcc, 0, v11, vcc
	global_store_dword v[6:7], v12, off
	v_pk_mul_f32 v[6:7], v[8:9], s[90:91] op_sel_hi:[1,0]
	s_waitcnt vmcnt(15)
; __device__ __forceinline__ f32x2 ld2(const bf16_t* p) { const unsigned u = *(const unsigned*)p; return (f32x2){bf_lo(u), bf_hi(u)}; }
; __device__ __forceinline__ f32x2 un2(unsigned u) { return (f32x2){bf_lo(u), bf_hi(u)}; }
; __device__ __forceinline__ void st2(bf16_t* p, f32x2 v) { *(unsigned*)p = cvt_pk_bf16(v.x, v.y); }
; __device__ __forceinline__ float silu_f(float x) { return x * sigmoid_f(x); }
; __device__ __forceinline__ void mixer_phase(const Args& a, int l, LAS unsigned char* lds, int tile0, int tstride, int tend) {
;     ...
;     for (int ti = tile0; ti < tend; ti += tstride) {
;         const int t0 = ti * TT, s0 = t0 % SEQ; const bool first = (s0 == 0);
;         const bf16_t* Pt = P + (size_t)t0 * NCO + e0;
;         {
;             const float* cw = a.in[I_CAW] + (size_t)l * 3 * EW + e0;
;             const f32x2 w0 = *(const f32x2*)cw, w1 = *(const f32x2*)(cw + EW), w2 = *(const f32x2*)(cw + 2 * EW);
;             f32x2 q2 = (f32x2){0.f, 0.f}, q1 = (f32x2){0.f, 0.f};
;             if (!first) { q2 = ld2(Pt - 2 * (ptrdiff_t)NCO + OQ); q1 = ld2(Pt - (ptrdiff_t)NCO + OQ); }
;             unsigned rA[TT][2];
; #pragma unroll
;             for (int i = 0; i < TT; ++i) { const bf16_t* pr = Pt + (size_t)i * NCO; rA[i][0] = *(const unsigned*)(pr + OQ); rA[i][1] = *(const unsigned*)(pr + OAB); }
;     ...
; #pragma unroll
;             for (int i = 0; i < TT; ++i) {
;                 const float mean = fin[2 * i] * (1.0f / EW);
;                 const float var = fmaxf(fin[2 * i + 1] * (1.0f / EW) - mean * mean, 0.f);
;                 const float rstd = __builtin_amdgcn_rsqf(var + LN_EPS);
;                 f32x2 y = (acc[i] - mean) * rstd * lg + lb;
;                 y.x = silu_f(y.x); y.y = silu_f(y.y);
;                 st2(Y + (size_t)(t0 + i) * YW + 2 * EW + e0, y * un2(rz[i]));
;             }
	v_lshlrev_b32_e32 v10, 16, v134
	v_fma_f32 v8, -v6, v6, v7
	v_max_f32_e32 v8, 0, v8
	v_add_f32_e32 v8, 0x3727c5ac, v8
	v_rsq_f32_e32 v8, v8
	v_pk_add_f32 v[6:7], v[100:101], v[6:7] op_sel_hi:[1,0] neg_lo:[0,1] neg_hi:[0,1]
	v_and_b32_e32 v11, 0xffff0000, v134
	v_pk_mul_f32 v[6:7], v[6:7], v[8:9] op_sel_hi:[1,0]
	s_nop 0
	v_pk_fma_f32 v[6:7], v[104:105], v[6:7], v[106:107]
	s_nop 0
	v_mul_f32_e32 v8, 0xbfb8aa3b, v6
	v_mul_f32_e32 v9, 0xbfb8aa3b, v7
	v_exp_f32_e32 v8, v8
	v_exp_f32_e32 v9, v9
	v_add_f32_e32 v8, 1.0, v8
	v_add_f32_e32 v9, 1.0, v9
	v_rcp_f32_e32 v8, v8
	v_rcp_f32_e32 v9, v9
	s_nop 0
	v_pk_mul_f32 v[6:7], v[6:7], v[8:9]
	v_lshl_add_u64 v[8:9], s[4:5], 0, v[24:25]
	v_pk_mul_f32 v[6:7], v[6:7], v[10:11]
	s_add_u32 s4, s70, s11
	v_cvt_pk_bf16_f32 v10, v6, v7
	v_add_co_u32_e32 v6, vcc, s14, v8
	s_addc_u32 s5, s71, s7
	s_nop 0
	v_addc_co_u32_e32 v7, vcc, 0, v9, vcc
	global_store_dword v[6:7], v10, off
	v_fma_f32 v6, -v2, v2, v3
	v_max_f32_e32 v6, 0, v6
	v_add_f32_e32 v6, 0x3727c5ac, v6
	v_rsq_f32_e32 v6, v6
	v_pk_add_f32 v[2:3], v[98:99], v[2:3] op_sel_hi:[1,0] neg_lo:[0,1] neg_hi:[0,1]
	s_waitcnt vmcnt(15)
	v_lshlrev_b32_e32 v8, 16, v133
	v_and_b32_e32 v9, 0xffff0000, v133
	v_pk_mul_f32 v[2:3], v[2:3], v[6:7] op_sel_hi:[1,0]
	s_nop 0
	v_pk_fma_f32 v[2:3], v[104:105], v[2:3], v[106:107]
	s_nop 0
	v_mul_f32_e32 v6, 0xbfb8aa3b, v2
	v_mul_f32_e32 v7, 0xbfb8aa3b, v3
	v_exp_f32_e32 v6, v6
	v_exp_f32_e32 v7, v7
	v_add_f32_e32 v6, 1.0, v6
	v_add_f32_e32 v7, 1.0, v7
	v_rcp_f32_e32 v6, v6
	v_rcp_f32_e32 v7, v7
	s_nop 0
	v_pk_mul_f32 v[2:3], v[2:3], v[6:7]
	v_lshl_add_u64 v[6:7], s[4:5], 0, v[24:25]
	v_pk_mul_f32 v[2:3], v[2:3], v[8:9]
	s_add_u32 s4, s70, s6
	v_cvt_pk_bf16_f32 v8, v2, v3
	v_add_co_u32_e32 v2, vcc, s14, v6
	s_mul_hi_i32 s5, s9, 0x1800
	s_nop 0
	v_addc_co_u32_e32 v3, vcc, 0, v7, vcc
	global_store_dword v[2:3], v8, off
	v_pk_mul_f32 v[2:3], v[4:5], s[90:91] op_sel_hi:[1,0]
	s_addc_u32 s5, s71, s5
	v_fma_f32 v4, -v2, v2, v3
	v_max_f32_e32 v4, 0, v4
	v_add_f32_e32 v4, 0x3727c5ac, v4
	v_rsq_f32_e32 v4, v4
	v_pk_add_f32 v[2:3], v[96:97], v[2:3] op_sel_hi:[1,0] neg_lo:[0,1] neg_hi:[0,1]
	s_waitcnt vmcnt(15)
	v_lshlrev_b32_e32 v6, 16, v132
	v_and_b32_e32 v7, 0xffff0000, v132
	v_pk_mul_f32 v[2:3], v[2:3], v[4:5] op_sel_hi:[1,0]
	s_add_i32 s10, s10, 32
	v_pk_fma_f32 v[2:3], v[104:105], v[2:3], v[106:107]
	s_addk_i32 s9, 0x200
	v_mul_f32_e32 v4, 0xbfb8aa3b, v2
	v_mul_f32_e32 v5, 0xbfb8aa3b, v3
	v_exp_f32_e32 v4, v4
	v_exp_f32_e32 v5, v5
	v_add_f32_e32 v4, 1.0, v4
	v_add_f32_e32 v5, 1.0, v5
	v_rcp_f32_e32 v4, v4
	v_rcp_f32_e32 v5, v5
	s_nop 0
	v_pk_mul_f32 v[2:3], v[2:3], v[4:5]
	v_lshl_add_u64 v[4:5], s[4:5], 0, v[24:25]
	v_pk_mul_f32 v[2:3], v[2:3], v[6:7]
	v_readlane_b32 s4, v251, 8
	v_cvt_pk_bf16_f32 v6, v2, v3
	v_add_co_u32_e32 v2, vcc, 0x1000, v4
	s_cmp_ge_i32 s10, s4
	s_nop 0
	v_addc_co_u32_e32 v3, vcc, 0, v5, vcc
	global_store_dword v[2:3], v6, off
	s_cbranch_scc1 .LBB0_406
.LBB0_378:
	global_load_dwordx2 v[4:5], v[14:15], off nt
	global_load_dwordx2 v[104:105], v[32:33], off nt
	global_load_dwordx2 v[6:7], v[34:35], off nt
	s_add_i32 s92, s9, -15
	s_ashr_i32 s93, s92, 31
	s_lshr_b32 s4, s93, 21
	s_add_i32 s4, s92, s4
	s_and_b32 s4, s4, 0xfffff800
	s_sub_i32 s23, s92, s4
	s_cmp_eq_u32 s23, 0
	s_cselect_b64 s[54:55], -1, 0
	s_cmp_lg_u32 s23, 0
	s_cselect_b64 s[94:95], -1, 0
	v_mad_i64_i32 v[2:3], s[4:5], s92, v192, v[26:27]
	v_mov_b32_e32 v106, 0
	s_and_b64 vcc, exec, s[54:55]
	v_mov_b32_e32 v107, 0
	v_mov_b32_e32 v108, 0
	v_mov_b32_e32 v109, 0
	s_cbranch_vccnz .LBB0_380
	v_add_co_u32_e32 v8, vcc, 0xffff7000, v2
	s_nop 1
	v_addc_co_u32_e32 v9, vcc, -1, v3, vcc
	global_load_dword v10, v[8:9], off nt
	v_add_co_u32_e32 v8, vcc, 0xffffc000, v2
	s_waitcnt vmcnt(0)
	v_lshlrev_b32_e32 v108, 16, v10
	v_addc_co_u32_e32 v9, vcc, -1, v3, vcc
	global_load_dword v8, v[8:9], off offset:-2048 nt
	v_and_b32_e32 v109, 0xffff0000, v10
	s_waitcnt vmcnt(0)
	v_lshlrev_b32_e32 v106, 16, v8
	v_and_b32_e32 v107, 0xffff0000, v8
.LBB0_380:
	global_load_dword v111, v[2:3], off nt
	global_load_dword v113, v[2:3], off offset:2048 nt
	v_add_co_u32_e32 v8, vcc, 0x4000, v2
	s_mov_b32 s4, 0xe000
	s_nop 0
	v_addc_co_u32_e32 v9, vcc, 0, v3, vcc
	global_load_dword v116, v[8:9], off offset:2048 nt
	v_add_co_u32_e32 v8, vcc, 0x5000, v2
	s_waitcnt vmcnt(0)
	v_pk_mul_f32 v[108:109], v[4:5], v[108:109]
	v_addc_co_u32_e32 v9, vcc, 0, v3, vcc
	global_load_dword v117, v[8:9], off nt
	v_add_co_u32_e32 v8, vcc, 0x9000, v2
	s_waitcnt vmcnt(5)
; __device__ __forceinline__ f32x2 un2(unsigned u) { return (f32x2){bf_lo(u), bf_hi(u)}; }
; __device__ __forceinline__ void st2(bf16_t* p, f32x2 v) { *(unsigned*)p = cvt_pk_bf16(v.x, v.y); }
; #define MIX_ISSUED() asm volatile("" ::: "memory")
; __device__ __forceinline__ void mixer_phase(const Args& a, int l, LAS unsigned char* lds, int tile0, int tstride, int tend) {
;     ...
;             for (int i = 0; i < TT; ++i) { const bf16_t* pr = Pt + (size_t)i * NCO; rA[i][0] = *(const unsigned*)(pr + OQ); rA[i][1] = *(const unsigned*)(pr + OAB); }
;             MIX_ISSUED();
; #pragma unroll
;             for (int i = 0; i < TT; ++i) {
;                 const f32x2 q = un2(rA[i][0]), abz = un2(rA[i][1]);
;                 const f32x2 cv = w0 * q2 + w1 * q1 + w2 * q;
;                 st2(Y + (size_t)(t0 + i) * YW + e0, abz * cv);
;                 q2 = q1; q1 = q;
;             }
	v_pk_fma_f32 v[108:109], v[104:105], v[106:107], v[108:109]
	v_addc_co_u32_e32 v9, vcc, 0, v3, vcc
	global_load_dword v118, v[8:9], off nt
	global_load_dword v119, v[8:9], off offset:2048 nt
	v_add_co_u32_e32 v8, vcc, 0xd000, v2
	s_add_i32 s11, s9, -14
	s_nop 0
	v_addc_co_u32_e32 v9, vcc, 0, v3, vcc
	global_load_dword v120, v[8:9], off offset:2048 nt
	v_add_co_u32_e32 v8, vcc, s4, v2
	s_mov_b32 s4, 0x12000
	s_nop 0
	v_addc_co_u32_e32 v9, vcc, 0, v3, vcc
	global_load_dword v121, v[8:9], off nt
	v_add_co_u32_e32 v10, vcc, s4, v2
	s_mov_b32 s4, 0x16000
	s_nop 0
	v_addc_co_u32_e32 v11, vcc, 0, v3, vcc
	global_load_dword v122, v[10:11], off nt
	global_load_dword v123, v[10:11], off offset:2048 nt
	v_add_co_u32_e32 v10, vcc, s4, v2
	s_mov_b32 s4, 0x17000
	s_nop 0
	v_addc_co_u32_e32 v11, vcc, 0, v3, vcc
	v_add_co_u32_e32 v12, vcc, s4, v2
	global_load_dword v124, v[10:11], off offset:2048 nt
	s_nop 0
	v_addc_co_u32_e32 v13, vcc, 0, v3, vcc
	global_load_dword v125, v[12:13], off nt
	s_mov_b32 s4, 0x1b000
	v_add_co_u32_e32 v10, vcc, s4, v2
	s_mov_b32 s4, 0x1f000
	s_nop 0
	v_addc_co_u32_e32 v11, vcc, 0, v3, vcc
	global_load_dword v126, v[10:11], off nt
	global_load_dword v127, v[10:11], off offset:2048 nt
	v_add_co_u32_e32 v10, vcc, s4, v2
	s_mov_b32 s4, 0x20000
	s_nop 0
	v_addc_co_u32_e32 v11, vcc, 0, v3, vcc
	global_load_dword v128, v[10:11], off offset:2048 nt
	v_add_co_u32_e32 v10, vcc, s4, v2
	s_mov_b32 s4, 0x24000
	s_nop 0
	v_addc_co_u32_e32 v11, vcc, 0, v3, vcc
	global_load_dword v129, v[10:11], off nt
	v_add_co_u32_e32 v96, vcc, s4, v2
	s_mov_b32 s4, 0x28000
	s_nop 0
	v_addc_co_u32_e32 v97, vcc, 0, v3, vcc
	global_load_dword v130, v[96:97], off nt
	global_load_dword v131, v[96:97], off offset:2048 nt
	v_add_co_u32_e32 v96, vcc, s4, v2
	s_mov_b32 s4, 0x29000
	s_nop 0
	v_addc_co_u32_e32 v97, vcc, 0, v3, vcc
	global_load_dword v132, v[96:97], off offset:2048 nt
	v_add_co_u32_e32 v96, vcc, s4, v2
	s_mov_b32 s4, 0x2d000
	s_nop 0
	v_addc_co_u32_e32 v97, vcc, 0, v3, vcc
	global_load_dword v133, v[96:97], off nt
	v_add_co_u32_e32 v98, vcc, s4, v2
	s_mov_b32 s4, 0x31000
	s_nop 0
	v_addc_co_u32_e32 v99, vcc, 0, v3, vcc
	global_load_dword v134, v[98:99], off nt
	global_load_dword v135, v[98:99], off offset:2048 nt
	v_add_co_u32_e32 v98, vcc, s4, v2
	s_mov_b32 s4, 0x32000
	s_nop 0
	v_addc_co_u32_e32 v99, vcc, 0, v3, vcc
	global_load_dword v136, v[98:99], off offset:2048 nt
	v_add_co_u32_e32 v98, vcc, s4, v2
	s_mov_b32 s4, 0x36000
	s_nop 0
	v_addc_co_u32_e32 v99, vcc, 0, v3, vcc
	global_load_dword v137, v[98:99], off nt
	v_add_co_u32_e32 v100, vcc, s4, v2
	s_mov_b32 s4, 0x3a000
	s_nop 0
	v_addc_co_u32_e32 v101, vcc, 0, v3, vcc
	global_load_dword v138, v[100:101], off nt
	global_load_dword v139, v[100:101], off offset:2048 nt
	v_add_co_u32_e32 v100, vcc, s4, v2
	s_mov_b32 s4, 0x3b000
	s_nop 0
	v_addc_co_u32_e32 v101, vcc, 0, v3, vcc
	global_load_dword v140, v[100:101], off offset:2048 nt
	v_add_co_u32_e32 v100, vcc, s4, v2
	s_mov_b32 s4, 0x3f000
	s_nop 0
	v_addc_co_u32_e32 v101, vcc, 0, v3, vcc
	global_load_dword v141, v[100:101], off nt
	v_add_co_u32_e32 v102, vcc, s4, v2
	s_mov_b32 s4, 0x43000
	s_nop 0
	v_addc_co_u32_e32 v103, vcc, 0, v3, vcc
	global_load_dword v142, v[102:103], off nt
	global_load_dword v143, v[102:103], off offset:2048 nt
	v_add_co_u32_e32 v102, vcc, s4, v2
	s_mov_b32 s4, 0x44000
	s_nop 0
	v_addc_co_u32_e32 v103, vcc, 0, v3, vcc
	global_load_dword v144, v[102:103], off offset:2048 nt
	v_add_co_u32_e32 v102, vcc, s4, v2
	s_waitcnt vmcnt(30)
	v_lshlrev_b32_e32 v110, 16, v111
	v_addc_co_u32_e32 v103, vcc, 0, v3, vcc
	global_load_dword v145, v[102:103], off nt
	v_and_b32_e32 v111, 0xffff0000, v111
	s_waitcnt vmcnt(30)
	v_lshlrev_b32_e32 v112, 16, v113
	v_and_b32_e32 v113, 0xffff0000, v113
	v_pk_fma_f32 v[108:109], v[6:7], v[110:111], v[108:109]
	v_mad_i64_i32 v[114:115], s[4:5], s92, v193, v[28:29]
	v_pk_mul_f32 v[108:109], v[108:109], v[112:113]
	s_waitcnt vmcnt(28)
	v_lshlrev_b32_e32 v112, 16, v117
	v_cvt_pk_bf16_f32 v108, v108, v109
	global_store_dword v[114:115], v108, off
	v_pk_mul_f32 v[114:115], v[104:105], v[110:111]
	v_lshlrev_b32_e32 v108, 16, v116
	v_and_b32_e32 v109, 0xffff0000, v116
	v_pk_fma_f32 v[106:107], v[4:5], v[106:107], v[114:115]
	v_and_b32_e32 v113, 0xffff0000, v117
	v_pk_fma_f32 v[106:107], v[6:7], v[108:109], v[106:107]
	v_mad_i64_i32 v[114:115], s[4:5], s11, v193, v[28:29]
	v_pk_mul_f32 v[106:107], v[106:107], v[112:113]
	s_waitcnt vmcnt(27)
	v_lshlrev_b32_e32 v112, 16, v119
	v_cvt_pk_bf16_f32 v106, v106, v107
	global_store_dword v[114:115], v106, off
	v_pk_mul_f32 v[114:115], v[104:105], v[108:109]
	v_lshlrev_b32_e32 v106, 16, v118
	v_and_b32_e32 v107, 0xffff0000, v118
	v_pk_fma_f32 v[110:111], v[4:5], v[110:111], v[114:115]
	v_and_b32_e32 v113, 0xffff0000, v119
	v_pk_fma_f32 v[110:111], v[6:7], v[106:107], v[110:111]
	s_add_i32 s15, s9, -13
	v_pk_mul_f32 v[110:111], v[110:111], v[112:113]
	v_mad_i64_i32 v[114:115], s[4:5], s15, v193, v[28:29]
	v_cvt_pk_bf16_f32 v110, v110, v111
	global_store_dword v[114:115], v110, off
	v_pk_mul_f32 v[114:115], v[104:105], v[106:107]
	s_waitcnt vmcnt(28)
	v_lshlrev_b32_e32 v110, 16, v120
	v_and_b32_e32 v111, 0xffff0000, v120
	v_pk_fma_f32 v[108:109], v[4:5], v[108:109], v[114:115]
	s_waitcnt vmcnt(27)
	v_lshlrev_b32_e32 v112, 16, v121
	v_and_b32_e32 v113, 0xffff0000, v121
	v_pk_fma_f32 v[108:109], v[6:7], v[110:111], v[108:109]
	s_add_i32 s16, s9, -12
	v_pk_mul_f32 v[108:109], v[108:109], v[112:113]
	v_mad_i64_i32 v[114:115], s[4:5], s16, v193, v[28:29]
	v_cvt_pk_bf16_f32 v108, v108, v109
	global_store_dword v[114:115], v108, off
	v_pk_mul_f32 v[114:115], v[104:105], v[110:111]
	s_waitcnt vmcnt(27)
; __device__ __forceinline__ f32x2 un2(unsigned u) { return (f32x2){bf_lo(u), bf_hi(u)}; }
; __device__ __forceinline__ void st2(bf16_t* p, f32x2 v) { *(unsigned*)p = cvt_pk_bf16(v.x, v.y); }
; __device__ __forceinline__ void mixer_phase(const Args& a, int l, LAS unsigned char* lds, int tile0, int tstride, int tend) {
;     ...
; #pragma unroll
;             for (int i = 0; i < TT; ++i) {
;                 const f32x2 q = un2(rA[i][0]), abz = un2(rA[i][1]);
;                 const f32x2 cv = w0 * q2 + w1 * q1 + w2 * q;
;                 st2(Y + (size_t)(t0 + i) * YW + e0, abz * cv);
;                 q2 = q1; q1 = q;
;             }
;         }
;         asm volatile("" ::: "memory");
;         {
;             const bf16_t* Pb = Pt + OBIN; bf16_t* po = PO + (size_t)t0 * EW + e0;
;             const int grp = wave >> 1;
;             if (grp == 0) pool_branch<2>(Pb, po, first);
;             else if (grp == 1) pool_branch<4>(Pb, po, first);
;             else if (grp == 2) pool_branch<8>(Pb, po, first);
;             else pool_branch<16>(Pb, po, first);
	v_lshlrev_b32_e32 v108, 16, v122
	v_and_b32_e32 v109, 0xffff0000, v122
	v_pk_fma_f32 v[106:107], v[4:5], v[106:107], v[114:115]
	s_waitcnt vmcnt(26)
	v_lshlrev_b32_e32 v112, 16, v123
	v_and_b32_e32 v113, 0xffff0000, v123
	v_pk_fma_f32 v[106:107], v[6:7], v[108:109], v[106:107]
	s_add_i32 s17, s9, -11
	v_pk_mul_f32 v[106:107], v[106:107], v[112:113]
	v_mad_i64_i32 v[114:115], s[4:5], s17, v193, v[28:29]
	v_cvt_pk_bf16_f32 v106, v106, v107
	global_store_dword v[114:115], v106, off
	v_pk_mul_f32 v[114:115], v[104:105], v[108:109]
	s_waitcnt vmcnt(26)
	v_lshlrev_b32_e32 v106, 16, v124
	v_and_b32_e32 v107, 0xffff0000, v124
	v_pk_fma_f32 v[110:111], v[4:5], v[110:111], v[114:115]
	s_waitcnt vmcnt(25)
	v_lshlrev_b32_e32 v112, 16, v125
	v_and_b32_e32 v113, 0xffff0000, v125
	v_pk_fma_f32 v[110:111], v[6:7], v[106:107], v[110:111]
	s_add_i32 s80, s9, -10
	v_pk_mul_f32 v[110:111], v[110:111], v[112:113]
	v_mad_i64_i32 v[114:115], s[4:5], s80, v193, v[28:29]
	v_cvt_pk_bf16_f32 v110, v110, v111
	global_store_dword v[114:115], v110, off
	v_pk_mul_f32 v[114:115], v[104:105], v[106:107]
	s_waitcnt vmcnt(25)
	v_lshlrev_b32_e32 v110, 16, v126
	v_and_b32_e32 v111, 0xffff0000, v126
	v_pk_fma_f32 v[108:109], v[4:5], v[108:109], v[114:115]
	s_waitcnt vmcnt(24)
	v_lshlrev_b32_e32 v112, 16, v127
	v_and_b32_e32 v113, 0xffff0000, v127
	v_pk_fma_f32 v[108:109], v[6:7], v[110:111], v[108:109]
	s_add_i32 s81, s9, -9
	v_pk_mul_f32 v[108:109], v[108:109], v[112:113]
	v_mad_i64_i32 v[114:115], s[4:5], s81, v193, v[28:29]
	v_cvt_pk_bf16_f32 v108, v108, v109
	global_store_dword v[114:115], v108, off
	v_pk_mul_f32 v[114:115], v[104:105], v[110:111]
	s_waitcnt vmcnt(24)
	v_lshlrev_b32_e32 v108, 16, v128
	v_and_b32_e32 v109, 0xffff0000, v128
	v_pk_fma_f32 v[106:107], v[4:5], v[106:107], v[114:115]
	s_waitcnt vmcnt(23)
	v_lshlrev_b32_e32 v112, 16, v129
	v_and_b32_e32 v113, 0xffff0000, v129
	v_pk_fma_f32 v[106:107], v[6:7], v[108:109], v[106:107]
	s_add_i32 s82, s9, -8
	v_pk_mul_f32 v[106:107], v[106:107], v[112:113]
	v_mad_i64_i32 v[114:115], s[4:5], s82, v193, v[28:29]
	v_cvt_pk_bf16_f32 v106, v106, v107
	global_store_dword v[114:115], v106, off
	v_pk_mul_f32 v[114:115], v[104:105], v[108:109]
	s_waitcnt vmcnt(23)
	v_lshlrev_b32_e32 v106, 16, v130
	v_and_b32_e32 v107, 0xffff0000, v130
	v_pk_fma_f32 v[110:111], v[4:5], v[110:111], v[114:115]
	s_waitcnt vmcnt(22)
	v_lshlrev_b32_e32 v112, 16, v131
	v_and_b32_e32 v113, 0xffff0000, v131
	v_pk_fma_f32 v[110:111], v[6:7], v[106:107], v[110:111]
	s_add_i32 s83, s9, -7
	v_pk_mul_f32 v[110:111], v[110:111], v[112:113]
	v_mad_i64_i32 v[114:115], s[4:5], s83, v193, v[28:29]
	v_cvt_pk_bf16_f32 v110, v110, v111
	global_store_dword v[114:115], v110, off
	v_pk_mul_f32 v[114:115], v[104:105], v[106:107]
	s_waitcnt vmcnt(22)
	v_lshlrev_b32_e32 v110, 16, v132
	v_and_b32_e32 v111, 0xffff0000, v132
	v_pk_fma_f32 v[108:109], v[4:5], v[108:109], v[114:115]
	s_waitcnt vmcnt(21)
	v_lshlrev_b32_e32 v112, 16, v133
	v_and_b32_e32 v113, 0xffff0000, v133
	v_pk_fma_f32 v[108:109], v[6:7], v[110:111], v[108:109]
	s_add_i32 s89, s9, -6
	v_pk_mul_f32 v[108:109], v[108:109], v[112:113]
	v_mad_i64_i32 v[114:115], s[4:5], s89, v193, v[28:29]
	v_cvt_pk_bf16_f32 v108, v108, v109
	global_store_dword v[114:115], v108, off
	v_pk_mul_f32 v[114:115], v[104:105], v[110:111]
	s_waitcnt vmcnt(21)
	v_lshlrev_b32_e32 v108, 16, v134
	v_and_b32_e32 v109, 0xffff0000, v134
	v_pk_fma_f32 v[106:107], v[4:5], v[106:107], v[114:115]
	s_waitcnt vmcnt(20)
	v_lshlrev_b32_e32 v112, 16, v135
	v_and_b32_e32 v113, 0xffff0000, v135
	v_pk_fma_f32 v[106:107], v[6:7], v[108:109], v[106:107]
	s_add_i32 s18, s9, -5
	v_pk_mul_f32 v[106:107], v[106:107], v[112:113]
	v_mad_i64_i32 v[114:115], s[4:5], s18, v193, v[28:29]
	v_cvt_pk_bf16_f32 v106, v106, v107
	global_store_dword v[114:115], v106, off
	v_pk_mul_f32 v[114:115], v[104:105], v[108:109]
	s_waitcnt vmcnt(20)
	v_lshlrev_b32_e32 v106, 16, v136
	v_and_b32_e32 v107, 0xffff0000, v136
	v_pk_fma_f32 v[110:111], v[4:5], v[110:111], v[114:115]
	s_waitcnt vmcnt(19)
	v_lshlrev_b32_e32 v112, 16, v137
	v_and_b32_e32 v113, 0xffff0000, v137
	v_pk_fma_f32 v[110:111], v[6:7], v[106:107], v[110:111]
	s_add_i32 s19, s9, -4
	v_pk_mul_f32 v[110:111], v[110:111], v[112:113]
	v_mad_i64_i32 v[114:115], s[4:5], s19, v193, v[28:29]
	v_cvt_pk_bf16_f32 v110, v110, v111
	global_store_dword v[114:115], v110, off
	v_pk_mul_f32 v[114:115], v[104:105], v[106:107]
	s_waitcnt vmcnt(19)
	v_lshlrev_b32_e32 v110, 16, v138
	v_and_b32_e32 v111, 0xffff0000, v138
	v_pk_fma_f32 v[108:109], v[4:5], v[108:109], v[114:115]
	s_waitcnt vmcnt(18)
	v_lshlrev_b32_e32 v112, 16, v139
	v_and_b32_e32 v113, 0xffff0000, v139
	v_pk_fma_f32 v[108:109], v[6:7], v[110:111], v[108:109]
	s_add_i32 s20, s9, -3
	v_pk_mul_f32 v[108:109], v[108:109], v[112:113]
	v_mad_i64_i32 v[114:115], s[4:5], s20, v193, v[28:29]
	v_cvt_pk_bf16_f32 v108, v108, v109
	global_store_dword v[114:115], v108, off
	v_pk_mul_f32 v[114:115], v[104:105], v[110:111]
	s_waitcnt vmcnt(18)
	v_lshlrev_b32_e32 v108, 16, v140
	v_and_b32_e32 v109, 0xffff0000, v140
	v_pk_fma_f32 v[106:107], v[4:5], v[106:107], v[114:115]
	s_waitcnt vmcnt(17)
	v_lshlrev_b32_e32 v112, 16, v141
	v_and_b32_e32 v113, 0xffff0000, v141
	v_pk_fma_f32 v[106:107], v[6:7], v[108:109], v[106:107]
	s_add_i32 s21, s9, -2
	v_pk_mul_f32 v[106:107], v[106:107], v[112:113]
	v_mad_i64_i32 v[114:115], s[4:5], s21, v193, v[28:29]
	v_cvt_pk_bf16_f32 v106, v106, v107
	global_store_dword v[114:115], v106, off
	v_pk_mul_f32 v[114:115], v[104:105], v[108:109]
	s_waitcnt vmcnt(17)
	v_lshlrev_b32_e32 v106, 16, v142
	v_and_b32_e32 v107, 0xffff0000, v142
	v_pk_fma_f32 v[110:111], v[4:5], v[110:111], v[114:115]
	s_waitcnt vmcnt(16)
	v_lshlrev_b32_e32 v112, 16, v143
	v_and_b32_e32 v113, 0xffff0000, v143
	v_pk_fma_f32 v[110:111], v[6:7], v[106:107], v[110:111]
	s_add_i32 s22, s9, -1
	v_pk_mul_f32 v[110:111], v[110:111], v[112:113]
	v_mad_i64_i32 v[114:115], s[4:5], s22, v193, v[28:29]
	v_cvt_pk_bf16_f32 v110, v110, v111
	v_pk_mul_f32 v[104:105], v[104:105], v[106:107]
	global_store_dword v[114:115], v110, off
	s_waitcnt vmcnt(16)
	v_lshlrev_b32_e32 v110, 16, v144
	v_and_b32_e32 v111, 0xffff0000, v144
	v_pk_fma_f32 v[4:5], v[4:5], v[108:109], v[104:105]
	s_waitcnt vmcnt(15)
	v_lshlrev_b32_e32 v112, 16, v145
	v_and_b32_e32 v113, 0xffff0000, v145
	v_pk_fma_f32 v[4:5], v[6:7], v[110:111], v[4:5]
	v_mad_i64_i32 v[6:7], s[4:5], s9, v193, v[28:29]
	v_pk_mul_f32 v[4:5], v[4:5], v[112:113]
	s_lshl_b64 s[4:5], s[92:93], 11
	v_cvt_pk_bf16_f32 v4, v4, v5
	global_store_dword v[6:7], v4, off
	v_lshl_add_u64 v[6:7], v[2:3], 0, s[78:79]
	v_lshl_add_u64 v[4:5], v[30:31], 0, s[4:5]
	s_mov_b64 s[4:5], -1
	s_and_b64 vcc, exec, s[74:75]
	s_cbranch_vccz .LBB0_387
	s_mov_b64 s[6:7], -1
	s_mov_b64 s[62:63], 0
	s_cmp_lt_i32 s8, 2
	s_mov_b64 s[4:5], 0
	s_cbranch_scc0 .LBB0_401
	s_and_b64 vcc, exec, s[6:7]
	s_cbranch_vccnz .LBB0_404

; __device__ __forceinline__ f32x2 un2(unsigned u) { return (f32x2){bf_lo(u), bf_hi(u)}; }
; __device__ __forceinline__ void st2(bf16_t* p, f32x2 v) { *(unsigned*)p = cvt_pk_bf16(v.x, v.y); }
; template <int W>
; __device__ __forceinline__ void pool_branch(const bf16_t* __restrict__ Pb, bf16_t* __restrict__ out, bool first) {
;     unsigned raw[W - 1 + TT];
; #pragma unroll
;     for (int j = 0; j < W - 1 + TT; ++j) { const int off = j - (W - 1); const int offc = (off < 0 && first) ? 0 : off;
;         unsigned r = *(const unsigned*)(Pb + (ptrdiff_t)offc * NCO); if (off < 0 && first) r = 0u; raw[j] = r; }
;     asm volatile("" ::: "memory");
;     f32x2 S = (f32x2){0.f, 0.f};
; #pragma unroll
;     for (int j = 0; j < W - 1; ++j) S += un2(raw[j]);
; #pragma unroll
;     for (int i = 0; i < TT; ++i) {
;         const f32x2 ui = un2(raw[i + W - 1]);
;         S += ui;
;         const float inv = (first && (i + 1 < W)) ? 1.0f / (float)(i + 1) : 1.0f / (float)W;
;         st2(out + (size_t)i * EW, S * inv - ui);
;         S -= un2(raw[i]);
;     }
.LBB0_385:
	s_and_b64 s[4:5], exec, s[54:55]
	s_cselect_b32 s5, 0, -1
	s_cselect_b32 s4, 0, 0xffff2800
	v_lshl_add_u64 v[104:105], v[6:7], 0, s[4:5]
	global_load_dword v104, v[104:105], off nt
	s_cselect_b32 s4, 0, 0xffffb800
	global_load_dword v110, v[6:7], off nt
	s_mov_b32 s56, 0x3e800000
	s_waitcnt vmcnt(1)
	v_cndmask_b32_e64 v107, v104, 0, s[54:55]
	v_lshl_add_u64 v[104:105], s[4:5], 1, v[6:7]
	global_load_dword v104, v[104:105], off nt
	s_waitcnt vmcnt(0)
	v_cndmask_b32_e64 v108, v104, 0, s[54:55]
	v_lshl_add_u64 v[104:105], v[6:7], 0, s[4:5]
	global_load_dword v104, v[104:105], off nt
	s_movk_i32 s5, 0x5000
	s_mov_b32 s4, 0xa000
	s_waitcnt vmcnt(0)
	v_cndmask_b32_e64 v109, v104, 0, s[54:55]
	v_add_co_u32_e32 v104, vcc, s5, v2
	s_nop 1
	v_addc_co_u32_e32 v105, vcc, 0, v3, vcc
	global_load_dword v111, v[104:105], off offset:2048 nt
	v_add_co_u32_e32 v104, vcc, s4, v2
	s_mov_b32 s4, 0x13000
	s_nop 0
	v_addc_co_u32_e32 v105, vcc, 0, v3, vcc
	global_load_dword v112, v[104:105], off nt
	global_load_dword v113, v[8:9], off offset:2048 nt
	v_add_co_u32_e32 v8, vcc, s4, v2
	s_mov_b32 s4, 0x1c000
	s_nop 0
	v_addc_co_u32_e32 v9, vcc, 0, v3, vcc
	global_load_dword v105, v[8:9], off nt
	global_load_dword v104, v[12:13], off offset:2048 nt
	v_add_co_u32_e32 v8, vcc, s4, v2
	s_mov_b32 s4, 0x25000
	s_nop 0
	v_addc_co_u32_e32 v9, vcc, 0, v3, vcc
	global_load_dword v114, v[8:9], off nt
	global_load_dword v115, v[10:11], off offset:2048 nt
	v_add_co_u32_e32 v8, vcc, s4, v2
	s_mov_b32 s4, 0x2e000
	s_nop 0
	v_addc_co_u32_e32 v9, vcc, 0, v3, vcc
	global_load_dword v116, v[8:9], off nt
	global_load_dword v117, v[96:97], off offset:2048 nt
	v_add_co_u32_e32 v8, vcc, s4, v2
	s_mov_b32 s4, 0x37000
	s_nop 0
	v_addc_co_u32_e32 v9, vcc, 0, v3, vcc
	global_load_dword v118, v[8:9], off nt
	global_load_dword v119, v[98:99], off offset:2048 nt
	v_add_co_u32_e32 v8, vcc, s4, v2
	s_mov_b32 s4, 0x40000
	s_nop 0
	v_addc_co_u32_e32 v9, vcc, 0, v3, vcc
	global_load_dword v120, v[8:9], off nt
	global_load_dword v121, v[100:101], off offset:2048 nt
	v_add_co_u32_e32 v8, vcc, s4, v2
	v_lshlrev_b32_e32 v96, 16, v107
	s_nop 0
	v_addc_co_u32_e32 v9, vcc, 0, v3, vcc
	global_load_dword v122, v[8:9], off nt
	global_load_dword v106, v[102:103], off offset:2048 nt
	v_and_b32_e32 v97, 0xffff0000, v107
	v_pk_add_f32 v[8:9], v[96:97], 0 op_sel_hi:[1,0]
	v_lshlrev_b32_e32 v12, 16, v108
	v_and_b32_e32 v13, 0xffff0000, v108
	v_pk_add_f32 v[8:9], v[8:9], v[12:13]
	v_lshlrev_b32_e32 v10, 16, v109
	v_and_b32_e32 v11, 0xffff0000, v109
	v_pk_add_f32 v[98:99], v[8:9], v[10:11]
	v_lshlrev_b32_e32 v8, 16, v110
	v_and_b32_e32 v9, 0xffff0000, v110
	v_pk_add_f32 v[98:99], v[98:99], v[8:9]
	v_cndmask_b32_e64 v100, v196, 1.0, s[54:55]
	v_pk_fma_f32 v[100:101], v[100:101], v[98:99], v[8:9] op_sel_hi:[0,1,1] neg_lo:[0,0,1] neg_hi:[0,0,1]
	v_cvt_pk_bf16_f32 v100, v100, v101
	v_pk_add_f32 v[98:99], v[98:99], v[96:97] neg_lo:[0,1] neg_hi:[0,1]
	global_store_dword v[4:5], v100, off
	v_cndmask_b32_e64 v100, v196, 0.5, s[54:55]
	s_movk_i32 s4, 0x2000
	s_waitcnt vmcnt(15)
	v_lshlrev_b32_e32 v96, 16, v111
	v_and_b32_e32 v97, 0xffff0000, v111
	v_pk_add_f32 v[98:99], v[98:99], v[96:97]
	s_waitcnt vmcnt(13)
	v_lshlrev_b32_e32 v108, 16, v113
	v_pk_fma_f32 v[100:101], v[100:101], v[98:99], v[96:97] op_sel_hi:[0,1,1] neg_lo:[0,0,1] neg_hi:[0,0,1]
	v_pk_add_f32 v[12:13], v[98:99], v[12:13] neg_lo:[0,1] neg_hi:[0,1]
	v_lshlrev_b32_e32 v98, 16, v112
	v_and_b32_e32 v99, 0xffff0000, v112
	v_cvt_pk_bf16_f32 v100, v100, v101
	v_pk_add_f32 v[12:13], v[12:13], v[98:99]
	global_store_dword v[4:5], v100, off offset:2048
	v_cndmask_b32_e64 v100, v196, v195, s[54:55]
	v_and_b32_e32 v109, 0xffff0000, v113
	v_pk_add_f32 v[10:11], v[12:13], v[10:11] neg_lo:[0,1] neg_hi:[0,1]
	v_pk_fma_f32 v[100:101], v[100:101], v[12:13], v[98:99] op_sel_hi:[0,1,1] neg_lo:[0,0,1] neg_hi:[0,0,1]
	v_pk_add_f32 v[10:11], v[10:11], v[108:109]
	v_cvt_pk_bf16_f32 v107, v100, v101
	v_add_co_u32_e32 v100, vcc, s14, v4
	v_pk_fma_f32 v[12:13], v[10:11], s[56:57], v[108:109] op_sel_hi:[1,0,1] neg_lo:[0,0,1] neg_hi:[0,0,1]
	s_nop 0
	v_addc_co_u32_e32 v101, vcc, 0, v5, vcc
	v_cvt_pk_bf16_f32 v12, v12, v13
	global_store_dword v[100:101], v12, off offset:2048
	s_waitcnt vmcnt(14)
	v_lshlrev_b32_e32 v12, 16, v105
	v_and_b32_e32 v13, 0xffff0000, v105
	v_pk_add_f32 v[8:9], v[10:11], v[8:9] neg_lo:[0,1] neg_hi:[0,1]
	v_add_co_u32_e32 v102, vcc, s4, v4
	v_pk_add_f32 v[8:9], v[8:9], v[12:13]
	s_nop 0
	v_addc_co_u32_e32 v103, vcc, 0, v5, vcc
	v_pk_fma_f32 v[10:11], v[8:9], s[56:57], v[12:13] op_sel_hi:[1,0,1] neg_lo:[0,0,1] neg_hi:[0,0,1]
	v_pk_add_f32 v[8:9], v[8:9], v[96:97] neg_lo:[0,1] neg_hi:[0,1]
	v_cvt_pk_bf16_f32 v10, v10, v11
	global_store_dword v[102:103], v10, off
	s_waitcnt vmcnt(14)
; __device__ __forceinline__ f32x2 un2(unsigned u) { return (f32x2){bf_lo(u), bf_hi(u)}; }
; __device__ __forceinline__ void st2(bf16_t* p, f32x2 v) { *(unsigned*)p = cvt_pk_bf16(v.x, v.y); }
; template <int W>
; __device__ __forceinline__ void pool_branch(const bf16_t* __restrict__ Pb, bf16_t* __restrict__ out, bool first) {
;     ...
;     f32x2 S = (f32x2){0.f, 0.f};
; #pragma unroll
;     for (int j = 0; j < W - 1; ++j) S += un2(raw[j]);
; #pragma unroll
;     for (int i = 0; i < TT; ++i) {
;         const f32x2 ui = un2(raw[i + W - 1]);
;         S += ui;
;         const float inv = (first && (i + 1 < W)) ? 1.0f / (float)(i + 1) : 1.0f / (float)W;
;         st2(out + (size_t)i * EW, S * inv - ui);
;         S -= un2(raw[i]);
;     }
	v_lshlrev_b32_e32 v10, 16, v104
	v_and_b32_e32 v11, 0xffff0000, v104
	v_pk_add_f32 v[8:9], v[8:9], v[10:11]
	global_store_dword v[102:103], v107, off offset:-4096
	v_pk_fma_f32 v[96:97], v[8:9], s[56:57], v[10:11] op_sel_hi:[1,0,1] neg_lo:[0,0,1] neg_hi:[0,0,1]
	v_pk_add_f32 v[8:9], v[8:9], v[98:99] neg_lo:[0,1] neg_hi:[0,1]
	v_cvt_pk_bf16_f32 v96, v96, v97
	global_store_dword v[102:103], v96, off offset:2048
	s_waitcnt vmcnt(15)
	v_lshlrev_b32_e32 v96, 16, v114
	v_and_b32_e32 v97, 0xffff0000, v114
	v_pk_add_f32 v[8:9], v[8:9], v[96:97]
	s_movk_i32 s4, 0x4000
	v_pk_fma_f32 v[98:99], v[8:9], s[56:57], v[96:97] op_sel_hi:[1,0,1] neg_lo:[0,0,1] neg_hi:[0,0,1]
	s_waitcnt vmcnt(14)
	v_and_b32_e32 v103, 0xffff0000, v115
	v_cvt_pk_bf16_f32 v102, v98, v99
	v_add_co_u32_e32 v98, vcc, s12, v4
	v_pk_add_f32 v[8:9], v[8:9], v[108:109] neg_lo:[0,1] neg_hi:[0,1]
	s_nop 0
	v_addc_co_u32_e32 v99, vcc, 0, v5, vcc
	v_add_co_u32_e32 v100, vcc, s4, v4
	s_movk_i32 s4, 0x6000
	s_nop 0
	v_addc_co_u32_e32 v101, vcc, 0, v5, vcc
	global_store_dword v[100:101], v102, off offset:-4096
	v_lshlrev_b32_e32 v102, 16, v115
	v_pk_add_f32 v[8:9], v[8:9], v[102:103]
	s_nop 0
	v_pk_fma_f32 v[104:105], v[8:9], s[56:57], v[102:103] op_sel_hi:[1,0,1] neg_lo:[0,0,1] neg_hi:[0,0,1]
	v_pk_add_f32 v[8:9], v[8:9], v[12:13] neg_lo:[0,1] neg_hi:[0,1]
	v_cvt_pk_bf16_f32 v104, v104, v105
	global_store_dword v[98:99], v104, off offset:2048
	s_waitcnt vmcnt(15)
	v_lshlrev_b32_e32 v98, 16, v116
	v_and_b32_e32 v99, 0xffff0000, v116
	v_pk_add_f32 v[8:9], v[8:9], v[98:99]
	s_waitcnt vmcnt(12)
	v_and_b32_e32 v105, 0xffff0000, v119
	v_pk_fma_f32 v[12:13], v[8:9], s[56:57], v[98:99] op_sel_hi:[1,0,1] neg_lo:[0,0,1] neg_hi:[0,0,1]
	v_pk_add_f32 v[8:9], v[8:9], v[10:11] neg_lo:[0,1] neg_hi:[0,1]
	v_cvt_pk_bf16_f32 v12, v12, v13
	global_store_dword v[100:101], v12, off
	v_lshlrev_b32_e32 v12, 16, v117
	v_and_b32_e32 v13, 0xffff0000, v117
	v_pk_add_f32 v[8:9], v[8:9], v[12:13]
	s_nop 0
	v_pk_fma_f32 v[10:11], v[8:9], s[56:57], v[12:13] op_sel_hi:[1,0,1] neg_lo:[0,0,1] neg_hi:[0,0,1]
	v_pk_add_f32 v[8:9], v[8:9], v[96:97] neg_lo:[0,1] neg_hi:[0,1]
	v_cvt_pk_bf16_f32 v10, v10, v11
	global_store_dword v[100:101], v10, off offset:2048
	v_lshlrev_b32_e32 v10, 16, v118
	v_and_b32_e32 v11, 0xffff0000, v118
	v_pk_add_f32 v[8:9], v[8:9], v[10:11]
	s_nop 0
	v_pk_fma_f32 v[96:97], v[8:9], s[56:57], v[10:11] op_sel_hi:[1,0,1] neg_lo:[0,0,1] neg_hi:[0,0,1]
	v_pk_add_f32 v[8:9], v[8:9], v[102:103] neg_lo:[0,1] neg_hi:[0,1]
	v_cvt_pk_bf16_f32 v104, v96, v97
	v_add_co_u32_e32 v96, vcc, s5, v4
	s_nop 1
	v_addc_co_u32_e32 v97, vcc, 0, v5, vcc
	v_add_co_u32_e32 v100, vcc, s4, v4
	s_nop 1
	v_addc_co_u32_e32 v101, vcc, 0, v5, vcc
	global_store_dword v[100:101], v104, off offset:-4096
	v_lshlrev_b32_e32 v104, 16, v119
	v_pk_add_f32 v[8:9], v[8:9], v[104:105]
	s_nop 0
	v_pk_fma_f32 v[102:103], v[8:9], s[56:57], v[104:105] op_sel_hi:[1,0,1] neg_lo:[0,0,1] neg_hi:[0,0,1]
	v_pk_add_f32 v[8:9], v[8:9], v[98:99] neg_lo:[0,1] neg_hi:[0,1]
	v_cvt_pk_bf16_f32 v102, v102, v103
	global_store_dword v[96:97], v102, off offset:2048
	s_waitcnt vmcnt(15)
	v_lshlrev_b32_e32 v96, 16, v120
	v_and_b32_e32 v97, 0xffff0000, v120
	v_pk_add_f32 v[8:9], v[8:9], v[96:97]
	s_nop 0
	v_pk_fma_f32 v[96:97], v[8:9], s[56:57], v[96:97] op_sel_hi:[1,0,1] neg_lo:[0,0,1] neg_hi:[0,0,1]
	v_pk_add_f32 v[8:9], v[8:9], v[12:13] neg_lo:[0,1] neg_hi:[0,1]
	s_waitcnt vmcnt(14)
	v_lshlrev_b32_e32 v12, 16, v121
	v_and_b32_e32 v13, 0xffff0000, v121
	v_pk_add_f32 v[8:9], v[8:9], v[12:13]
	v_cvt_pk_bf16_f32 v96, v96, v97
	v_pk_fma_f32 v[12:13], v[8:9], s[56:57], v[12:13] op_sel_hi:[1,0,1] neg_lo:[0,0,1] neg_hi:[0,0,1]
	v_pk_add_f32 v[8:9], v[8:9], v[10:11] neg_lo:[0,1] neg_hi:[0,1]
	s_waitcnt vmcnt(13)
	v_lshlrev_b32_e32 v10, 16, v122
	v_and_b32_e32 v11, 0xffff0000, v122
	v_pk_add_f32 v[8:9], v[8:9], v[10:11]
	v_cvt_pk_bf16_f32 v12, v12, v13
	v_pk_fma_f32 v[10:11], v[8:9], s[56:57], v[10:11] op_sel_hi:[1,0,1] neg_lo:[0,0,1] neg_hi:[0,0,1]
	global_store_dword v[100:101], v12, off offset:2048
	v_cvt_pk_bf16_f32 v12, v10, v11
	v_add_co_u32_e32 v10, vcc, 0x7000, v4
	v_pk_add_f32 v[104:105], v[8:9], v[104:105] neg_lo:[0,1] neg_hi:[0,1]
	s_nop 0
	v_addc_co_u32_e32 v11, vcc, 0, v5, vcc
	global_store_dword v[100:101], v96, off
	global_store_dword v[10:11], v12, off

; __device__ __forceinline__ f32x2 un2(unsigned u) { return (f32x2){bf_lo(u), bf_hi(u)}; }
; __device__ __forceinline__ void st2(bf16_t* p, f32x2 v) { *(unsigned*)p = cvt_pk_bf16(v.x, v.y); }
; template <int W>
; __device__ __forceinline__ void pool_branch(const bf16_t* __restrict__ Pb, bf16_t* __restrict__ out, bool first) {
;     unsigned raw[W - 1 + TT];
; #pragma unroll
;     for (int j = 0; j < W - 1 + TT; ++j) { const int off = j - (W - 1); const int offc = (off < 0 && first) ? 0 : off;
;         unsigned r = *(const unsigned*)(Pb + (ptrdiff_t)offc * NCO); if (off < 0 && first) r = 0u; raw[j] = r; }
;     asm volatile("" ::: "memory");
;     f32x2 S = (f32x2){0.f, 0.f};
; #pragma unroll
;     for (int j = 0; j < W - 1; ++j) S += un2(raw[j]);
; #pragma unroll
;     for (int i = 0; i < TT; ++i) {
;         const f32x2 ui = un2(raw[i + W - 1]);
;         S += ui;
;         const float inv = (first && (i + 1 < W)) ? 1.0f / (float)(i + 1) : 1.0f / (float)W;
;         st2(out + (size_t)i * EW, S * inv - ui);
;         S -= un2(raw[i]);
;     }
.LBB0_387:
	s_and_b64 vcc, exec, s[4:5]
	s_cbranch_vccz .LBB0_389
	s_and_b64 s[4:5], exec, s[54:55]
	s_cselect_b32 s5, 0, -1
	s_cselect_b32 s4, 0, 0xffffb800
	v_lshl_add_u64 v[8:9], v[6:7], 0, s[4:5]
	global_load_dword v8, v[8:9], off nt
	s_mov_b32 s4, 0x1c000
	global_load_dword v11, v[6:7], off nt
	v_add_co_u32_e32 v6, vcc, 0x5000, v2
	v_cndmask_b32_e64 v12, 0.5, 1.0, s[54:55]
	s_nop 0
	v_addc_co_u32_e32 v7, vcc, 0, v3, vcc
	global_load_dword v96, v[6:7], off offset:2048 nt
	v_add_co_u32_e32 v6, vcc, 0xa000, v2
	s_mov_b32 s56, 0.5
	s_nop 0
	v_addc_co_u32_e32 v7, vcc, 0, v3, vcc
	global_load_dword v97, v[6:7], off nt
	v_add_co_u32_e32 v6, vcc, 0xe000, v2
	s_waitcnt vmcnt(3)
	v_cndmask_b32_e64 v8, v8, 0, s[54:55]
	v_addc_co_u32_e32 v7, vcc, 0, v3, vcc
	global_load_dword v98, v[6:7], off offset:2048 nt
	v_add_co_u32_e32 v6, vcc, 0x13000, v2
	s_waitcnt vmcnt(3)
	v_lshlrev_b32_e32 v10, 16, v11
	v_addc_co_u32_e32 v7, vcc, 0, v3, vcc
	global_load_dword v100, v[6:7], off nt
	v_add_co_u32_e32 v6, vcc, 0x17000, v2
	v_and_b32_e32 v11, 0xffff0000, v11
	s_nop 0
	v_addc_co_u32_e32 v7, vcc, 0, v3, vcc
	global_load_dword v101, v[6:7], off offset:2048 nt
	v_add_co_u32_e32 v6, vcc, s4, v2
	s_movk_i32 s4, 0x2000
	s_nop 0
	v_addc_co_u32_e32 v7, vcc, 0, v3, vcc
	global_load_dword v102, v[6:7], off nt
	v_add_co_u32_e32 v6, vcc, 0x20000, v2
	s_nop 1
	v_addc_co_u32_e32 v7, vcc, 0, v3, vcc
	global_load_dword v103, v[6:7], off offset:2048 nt
	v_add_co_u32_e32 v6, vcc, 0x25000, v2
	s_nop 1
	v_addc_co_u32_e32 v7, vcc, 0, v3, vcc
	global_load_dword v104, v[6:7], off nt
	v_add_co_u32_e32 v6, vcc, 0x29000, v2
	s_nop 1
	v_addc_co_u32_e32 v7, vcc, 0, v3, vcc
	global_load_dword v105, v[6:7], off offset:2048 nt
	v_add_co_u32_e32 v6, vcc, 0x2e000, v2
	s_nop 1
	v_addc_co_u32_e32 v7, vcc, 0, v3, vcc
	global_load_dword v107, v[6:7], off nt
	v_add_co_u32_e32 v6, vcc, 0x32000, v2
	s_nop 1
	v_addc_co_u32_e32 v7, vcc, 0, v3, vcc
	global_load_dword v108, v[6:7], off offset:2048 nt
	v_add_co_u32_e32 v6, vcc, 0x37000, v2
	s_nop 1
	v_addc_co_u32_e32 v7, vcc, 0, v3, vcc
	global_load_dword v109, v[6:7], off nt
	v_add_co_u32_e32 v6, vcc, 0x3b000, v2
	s_nop 1
	v_addc_co_u32_e32 v7, vcc, 0, v3, vcc
	global_load_dword v110, v[6:7], off offset:2048 nt
	v_add_co_u32_e32 v6, vcc, 0x40000, v2
	s_nop 1
	v_addc_co_u32_e32 v7, vcc, 0, v3, vcc
	global_load_dword v111, v[6:7], off nt
	v_add_co_u32_e32 v6, vcc, 0x44000, v2
	s_nop 1
	v_addc_co_u32_e32 v7, vcc, 0, v3, vcc
	global_load_dword v106, v[6:7], off offset:2048 nt
	v_lshlrev_b32_e32 v6, 16, v8
	v_and_b32_e32 v7, 0xffff0000, v8
	v_pk_add_f32 v[8:9], v[6:7], 0 op_sel_hi:[1,0]
	s_nop 0
	v_pk_add_f32 v[8:9], v[8:9], v[10:11]
	s_nop 0
	v_pk_fma_f32 v[12:13], v[12:13], v[8:9], v[10:11] op_sel_hi:[0,1,1] neg_lo:[0,0,1] neg_hi:[0,0,1]
	v_pk_add_f32 v[6:7], v[8:9], v[6:7] neg_lo:[0,1] neg_hi:[0,1]
	s_waitcnt vmcnt(14)
	v_lshlrev_b32_e32 v8, 16, v96
	v_and_b32_e32 v9, 0xffff0000, v96
	v_cvt_pk_bf16_f32 v12, v12, v13
	v_pk_add_f32 v[6:7], v[6:7], v[8:9]
	global_store_dword v[4:5], v12, off
	v_pk_fma_f32 v[12:13], v[6:7], 0.5, v[8:9] op_sel_hi:[1,0,1] neg_lo:[0,0,1] neg_hi:[0,0,1]
	v_pk_add_f32 v[6:7], v[6:7], v[10:11] neg_lo:[0,1] neg_hi:[0,1]
	s_waitcnt vmcnt(14)
	v_lshlrev_b32_e32 v10, 16, v97
	v_and_b32_e32 v11, 0xffff0000, v97
	v_cvt_pk_bf16_f32 v12, v12, v13
	v_pk_add_f32 v[6:7], v[6:7], v[10:11]
	global_store_dword v[4:5], v12, off offset:2048
	v_pk_fma_f32 v[12:13], v[6:7], 0.5, v[10:11] op_sel_hi:[1,0,1] neg_lo:[0,0,1] neg_hi:[0,0,1]
	v_pk_add_f32 v[6:7], v[6:7], v[8:9] neg_lo:[0,1] neg_hi:[0,1]
	v_cvt_pk_bf16_f32 v99, v12, v13
	v_add_co_u32_e32 v12, vcc, s14, v4
	s_waitcnt vmcnt(14)
	v_lshlrev_b32_e32 v8, 16, v98
	v_addc_co_u32_e32 v13, vcc, 0, v5, vcc
	v_add_co_u32_e32 v96, vcc, s4, v4
	v_and_b32_e32 v9, 0xffff0000, v98
	s_nop 0
	v_addc_co_u32_e32 v97, vcc, 0, v5, vcc
	v_pk_add_f32 v[6:7], v[6:7], v[8:9]
	global_store_dword v[96:97], v99, off offset:-4096
	v_pk_fma_f32 v[98:99], v[6:7], 0.5, v[8:9] op_sel_hi:[1,0,1] neg_lo:[0,0,1] neg_hi:[0,0,1]
	v_pk_add_f32 v[6:7], v[6:7], v[10:11] neg_lo:[0,1] neg_hi:[0,1]
	s_waitcnt vmcnt(14)
	v_lshlrev_b32_e32 v10, 16, v100
	v_and_b32_e32 v11, 0xffff0000, v100
	v_cvt_pk_bf16_f32 v98, v98, v99
	v_pk_add_f32 v[6:7], v[6:7], v[10:11]
	global_store_dword v[12:13], v98, off offset:2048
	v_pk_fma_f32 v[12:13], v[6:7], 0.5, v[10:11] op_sel_hi:[1,0,1] neg_lo:[0,0,1] neg_hi:[0,0,1]
	v_pk_add_f32 v[6:7], v[6:7], v[8:9] neg_lo:[0,1] neg_hi:[0,1]
	s_waitcnt vmcnt(14)
	v_lshlrev_b32_e32 v8, 16, v101
	v_and_b32_e32 v9, 0xffff0000, v101
	v_cvt_pk_bf16_f32 v12, v12, v13
	v_pk_add_f32 v[6:7], v[6:7], v[8:9]
	global_store_dword v[96:97], v12, off
	v_pk_fma_f32 v[12:13], v[6:7], 0.5, v[8:9] op_sel_hi:[1,0,1] neg_lo:[0,0,1] neg_hi:[0,0,1]
	v_pk_add_f32 v[6:7], v[6:7], v[10:11] neg_lo:[0,1] neg_hi:[0,1]
	s_waitcnt vmcnt(14)
	v_lshlrev_b32_e32 v10, 16, v102
	v_and_b32_e32 v11, 0xffff0000, v102
	v_cvt_pk_bf16_f32 v12, v12, v13
	v_pk_add_f32 v[6:7], v[6:7], v[10:11]
	global_store_dword v[96:97], v12, off offset:2048
	v_pk_fma_f32 v[12:13], v[6:7], 0.5, v[10:11] op_sel_hi:[1,0,1] neg_lo:[0,0,1] neg_hi:[0,0,1]
	s_movk_i32 s4, 0x4000
	v_cvt_pk_bf16_f32 v98, v12, v13
	v_add_co_u32_e32 v12, vcc, s12, v4
	v_pk_add_f32 v[6:7], v[6:7], v[8:9] neg_lo:[0,1] neg_hi:[0,1]
	s_nop 0
	v_addc_co_u32_e32 v13, vcc, 0, v5, vcc
	v_add_co_u32_e32 v96, vcc, s4, v4
	s_waitcnt vmcnt(14)
	v_lshlrev_b32_e32 v8, 16, v103
	v_and_b32_e32 v9, 0xffff0000, v103
	v_addc_co_u32_e32 v97, vcc, 0, v5, vcc
	v_pk_add_f32 v[6:7], v[6:7], v[8:9]
	global_store_dword v[96:97], v98, off offset:-4096
	v_pk_fma_f32 v[98:99], v[6:7], 0.5, v[8:9] op_sel_hi:[1,0,1] neg_lo:[0,0,1] neg_hi:[0,0,1]
	v_pk_add_f32 v[6:7], v[6:7], v[10:11] neg_lo:[0,1] neg_hi:[0,1]
	s_waitcnt vmcnt(14)
; __device__ __forceinline__ f32x2 un2(unsigned u) { return (f32x2){bf_lo(u), bf_hi(u)}; }
; __device__ __forceinline__ void st2(bf16_t* p, f32x2 v) { *(unsigned*)p = cvt_pk_bf16(v.x, v.y); }
; template <int W>
; __device__ __forceinline__ void pool_branch(const bf16_t* __restrict__ Pb, bf16_t* __restrict__ out, bool first) {
;     ...
;     for (int i = 0; i < TT; ++i) {
;         const f32x2 ui = un2(raw[i + W - 1]);
;         S += ui;
;         const float inv = (first && (i + 1 < W)) ? 1.0f / (float)(i + 1) : 1.0f / (float)W;
;         st2(out + (size_t)i * EW, S * inv - ui);
;         S -= un2(raw[i]);
;     }
; __device__ __forceinline__ void mixer_phase(const Args& a, int l, LAS unsigned char* lds, int tile0, int tstride, int tend) {
;     ...
;             const float* cw = a.in[I_CCW] + (size_t)l * 31 * EW + e0;
;             f32x2 wk[31];
; #pragma unroll
;             for (int k = 0; k < 31; ++k) wk[k] = *(const f32x2*)(cw + (size_t)k * EW);
;             const f32x2 bias = *(const f32x2*)(a.in[I_CCB] + (size_t)l * EW + e0);
;             f32x2 acc[TT];
; #pragma unroll
;             for (int i = 0; i < TT; ++i) acc[i] = bias;
;             if (s0 == 0) conv31_all<30>(Pt, wk, acc);
;             else if (s0 == TT) conv31_all<30 - TT>(Pt, wk, acc);
;             else conv31_all<0>(Pt, wk, acc);
	v_lshlrev_b32_e32 v10, 16, v104
	v_and_b32_e32 v11, 0xffff0000, v104
	v_cvt_pk_bf16_f32 v98, v98, v99
	v_pk_add_f32 v[6:7], v[6:7], v[10:11]
	global_store_dword v[12:13], v98, off offset:2048
	v_pk_fma_f32 v[12:13], v[6:7], 0.5, v[10:11] op_sel_hi:[1,0,1] neg_lo:[0,0,1] neg_hi:[0,0,1]
	v_pk_add_f32 v[6:7], v[6:7], v[8:9] neg_lo:[0,1] neg_hi:[0,1]
	s_waitcnt vmcnt(14)
	v_lshlrev_b32_e32 v8, 16, v105
	v_and_b32_e32 v9, 0xffff0000, v105
	v_cvt_pk_bf16_f32 v12, v12, v13
	v_pk_add_f32 v[6:7], v[6:7], v[8:9]
	global_store_dword v[96:97], v12, off
	v_pk_fma_f32 v[12:13], v[6:7], 0.5, v[8:9] op_sel_hi:[1,0,1] neg_lo:[0,0,1] neg_hi:[0,0,1]
	v_pk_add_f32 v[6:7], v[6:7], v[10:11] neg_lo:[0,1] neg_hi:[0,1]
	s_waitcnt vmcnt(14)
	v_lshlrev_b32_e32 v10, 16, v107
	v_and_b32_e32 v11, 0xffff0000, v107
	v_cvt_pk_bf16_f32 v12, v12, v13
	v_pk_add_f32 v[6:7], v[6:7], v[10:11]
	global_store_dword v[96:97], v12, off offset:2048
	v_pk_fma_f32 v[12:13], v[6:7], 0.5, v[10:11] op_sel_hi:[1,0,1] neg_lo:[0,0,1] neg_hi:[0,0,1]
	s_movk_i32 s4, 0x5000
	v_cvt_pk_bf16_f32 v98, v12, v13
	v_add_co_u32_e32 v12, vcc, s4, v4
	s_movk_i32 s4, 0x6000
	s_nop 0
	v_addc_co_u32_e32 v13, vcc, 0, v5, vcc
	v_add_co_u32_e32 v96, vcc, s4, v4
	v_pk_add_f32 v[6:7], v[6:7], v[8:9] neg_lo:[0,1] neg_hi:[0,1]
	s_waitcnt vmcnt(14)
	v_lshlrev_b32_e32 v8, 16, v108
	v_and_b32_e32 v9, 0xffff0000, v108
	v_addc_co_u32_e32 v97, vcc, 0, v5, vcc
	v_pk_add_f32 v[6:7], v[6:7], v[8:9]
	global_store_dword v[96:97], v98, off offset:-4096
	v_pk_fma_f32 v[98:99], v[6:7], 0.5, v[8:9] op_sel_hi:[1,0,1] neg_lo:[0,0,1] neg_hi:[0,0,1]
	v_pk_add_f32 v[6:7], v[6:7], v[10:11] neg_lo:[0,1] neg_hi:[0,1]
	s_waitcnt vmcnt(14)
	v_lshlrev_b32_e32 v10, 16, v109
	v_and_b32_e32 v11, 0xffff0000, v109
	v_cvt_pk_bf16_f32 v98, v98, v99
	v_pk_add_f32 v[6:7], v[6:7], v[10:11]
	global_store_dword v[12:13], v98, off offset:2048
	v_pk_fma_f32 v[12:13], v[6:7], 0.5, v[10:11] op_sel_hi:[1,0,1] neg_lo:[0,0,1] neg_hi:[0,0,1]
	v_pk_add_f32 v[6:7], v[6:7], v[8:9] neg_lo:[0,1] neg_hi:[0,1]
	s_waitcnt vmcnt(14)
	v_lshlrev_b32_e32 v8, 16, v110
	v_and_b32_e32 v9, 0xffff0000, v110
	v_cvt_pk_bf16_f32 v12, v12, v13
	v_pk_add_f32 v[6:7], v[6:7], v[8:9]
	global_store_dword v[96:97], v12, off
	v_pk_fma_f32 v[12:13], v[6:7], 0.5, v[8:9] op_sel_hi:[1,0,1] neg_lo:[0,0,1] neg_hi:[0,0,1]
	v_pk_add_f32 v[6:7], v[6:7], v[10:11] neg_lo:[0,1] neg_hi:[0,1]
	s_waitcnt vmcnt(14)
	v_lshlrev_b32_e32 v10, 16, v111
	v_and_b32_e32 v11, 0xffff0000, v111
	v_pk_add_f32 v[6:7], v[6:7], v[10:11]
	v_cvt_pk_bf16_f32 v12, v12, v13
	v_pk_fma_f32 v[10:11], v[6:7], 0.5, v[10:11] op_sel_hi:[1,0,1] neg_lo:[0,0,1] neg_hi:[0,0,1]
	global_store_dword v[96:97], v12, off offset:2048
	v_cvt_pk_bf16_f32 v12, v10, v11
	v_add_co_u32_e32 v10, vcc, 0x7000, v4
	v_pk_add_f32 v[104:105], v[6:7], v[8:9] neg_lo:[0,1] neg_hi:[0,1]
	s_nop 0
	v_addc_co_u32_e32 v11, vcc, 0, v5, vcc
	global_store_dword v[10:11], v12, off
.LBB0_389:
	s_waitcnt vmcnt(15)
	v_lshlrev_b32_e32 v6, 16, v106
	v_and_b32_e32 v7, 0xffff0000, v106
	v_pk_add_f32 v[8:9], v[104:105], v[6:7]
	v_add_co_u32_e32 v4, vcc, 0x7000, v4
	v_pk_fma_f32 v[6:7], s[56:57], v[8:9], v[6:7] op_sel_hi:[0,1,1] neg_lo:[0,0,1] neg_hi:[0,0,1]
	v_cvt_pk_bf16_f32 v6, v6, v7
	v_addc_co_u32_e32 v5, vcc, 0, v5, vcc
	global_store_dword v[4:5], v6, off offset:2048
	global_load_dwordx2 v[116:117], v[64:65], off nt
	global_load_dwordx2 v[114:115], v[66:67], off nt
	global_load_dwordx2 v[112:113], v[68:69], off nt
	global_load_dwordx2 v[110:111], v[70:71], off nt
	global_load_dwordx2 v[108:109], v[72:73], off nt
	global_load_dwordx2 v[106:107], v[74:75], off nt
	global_load_dwordx2 v[104:105], v[76:77], off nt
	global_load_dwordx2 v[102:103], v[78:79], off nt
	global_load_dwordx2 v[100:101], v[80:81], off nt
	global_load_dwordx2 v[98:99], v[82:83], off nt
	global_load_dwordx2 v[96:97], v[84:85], off nt
	global_load_dwordx2 v[12:13], v[86:87], off nt
	global_load_dwordx2 v[10:11], v[88:89], off nt
	global_load_dwordx2 v[8:9], v[90:91], off nt
	global_load_dwordx2 v[6:7], v[92:93], off nt
	global_load_dwordx2 v[4:5], v[94:95], off nt
	global_load_dwordx2 v[118:119], v[18:19], off nt
	s_mov_b64 s[4:5], -1
	s_and_b64 vcc, exec, s[94:95]
	s_cbranch_vccz .LBB0_395
	global_load_dwordx2 v[186:187], v[16:17], off nt
	global_load_dwordx2 v[150:151], v[36:37], off nt
	global_load_dwordx2 v[148:149], v[38:39], off nt
	global_load_dwordx2 v[146:147], v[40:41], off nt
	global_load_dwordx2 v[144:145], v[42:43], off nt
	global_load_dwordx2 v[142:143], v[44:45], off nt
	global_load_dwordx2 v[140:141], v[46:47], off nt
	global_load_dwordx2 v[138:139], v[48:49], off nt
	global_load_dwordx2 v[136:137], v[50:51], off nt
	global_load_dwordx2 v[134:135], v[52:53], off nt
	global_load_dwordx2 v[132:133], v[54:55], off nt
	global_load_dwordx2 v[130:131], v[56:57], off nt
	global_load_dwordx2 v[128:129], v[58:59], off nt
	global_load_dwordx2 v[126:127], v[60:61], off nt
	global_load_dwordx2 v[124:125], v[62:63], off nt
	s_cmp_lg_u32 s23, 16
	s_cbranch_scc0 .LBB0_392
; __device__ __forceinline__ f32x2 un2(unsigned u) { return (f32x2){bf_lo(u), bf_hi(u)}; }
; #define MIX_ISSUED() asm volatile("" ::: "memory")
; template <int NDEAD, int B>
; __device__ __forceinline__ void conv31_load(const bf16_t* __restrict__ Pt, unsigned (&cv)[8]) {
; #pragma unroll
;     for (int q = 0; q < 8; ++q) { const int JJ = 8 * B + q; if (JJ >= NDEAD && JJ < CSTEPS) cv[q] = *(const unsigned*)(Pt + (ptrdiff_t)(JJ - 30) * NCO + OV); }
; }
; template <int NDEAD, int B>
; __device__ __forceinline__ void conv31_comp(const unsigned (&cv)[8], const f32x2 (&wk)[31], f32x2 (&acc)[TT]) {
; #pragma unroll
;     for (int q = 0; q < 8; ++q) { const int JJ = 8 * B + q; if (JJ >= NDEAD && JJ < CSTEPS) { const f32x2 v = un2(cv[q]);
; #pragma unroll
;         for (int i = 0; i < TT; ++i) { const int k = JJ - i; if (k >= 0 && k <= 30) acc[i] += wk[k] * v; } } }
; }
; template <int NDEAD>
; __device__ __forceinline__ void conv31_all(const bf16_t* __restrict__ Pt, const f32x2 (&wk)[31], f32x2 (&acc)[TT]) {
;     static_assert(CSTEPS <= 48, "six batches of eight steps");
;     unsigned cA[8], cB[8];
;     conv31_load<NDEAD, 0>(Pt, cA); conv31_load<NDEAD, 1>(Pt, cB); MIX_ISSUED();
;     conv31_comp<NDEAD, 0>(cA, wk, acc); conv31_load<NDEAD, 2>(Pt, cA); MIX_ISSUED();
;     conv31_comp<NDEAD, 1>(cB, wk, acc); conv31_load<NDEAD, 3>(Pt, cB); MIX_ISSUED();
;     conv31_comp<NDEAD, 2>(cA, wk, acc); conv31_load<NDEAD, 4>(Pt, cA); MIX_ISSUED();
;     conv31_comp<NDEAD, 3>(cB, wk, acc); conv31_load<NDEAD, 5>(Pt, cB); MIX_ISSUED();
;     conv31_comp<NDEAD, 4>(cA, wk, acc);
;     conv31_comp<NDEAD, 5>(cB, wk, acc);
; }
	v_add_co_u32_e32 v120, vcc, 0xfff7b000, v2
	s_mov_b32 s4, 0xfffc3000
	s_nop 0
	v_addc_co_u32_e32 v121, vcc, -1, v3, vcc
	global_load_dword v122, v[120:121], off nt
	v_add_co_u32_e32 v120, vcc, 0xfff80000, v2
	s_nop 1
	v_addc_co_u32_e32 v121, vcc, -1, v3, vcc
	global_load_dword v123, v[120:121], off offset:-2048 nt
	v_add_co_u32_e32 v120, vcc, 0xfff84000, v2
	s_nop 1
	v_addc_co_u32_e32 v121, vcc, -1, v3, vcc
	global_load_dword v153, v[120:121], off nt
	v_add_co_u32_e32 v120, vcc, 0xfff89000, v2
	s_waitcnt vmcnt(0)
	v_lshlrev_b32_e32 v152, 16, v153
	v_addc_co_u32_e32 v121, vcc, -1, v3, vcc
	global_load_dword v155, v[120:121], off offset:-2048 nt
	v_add_co_u32_e32 v120, vcc, 0xfff8d000, v2
	v_and_b32_e32 v153, 0xffff0000, v153
	s_nop 0
	v_addc_co_u32_e32 v121, vcc, -1, v3, vcc
	global_load_dword v157, v[120:121], off nt
	v_add_co_u32_e32 v120, vcc, 0xfff92000, v2
	s_waitcnt vmcnt(1)
	v_lshlrev_b32_e32 v154, 16, v155
	v_addc_co_u32_e32 v121, vcc, -1, v3, vcc
	global_load_dword v159, v[120:121], off offset:-2048 nt
	v_add_co_u32_e32 v120, vcc, 0xfff96000, v2
	v_and_b32_e32 v155, 0xffff0000, v155
	s_nop 0
	v_addc_co_u32_e32 v121, vcc, -1, v3, vcc
	global_load_dword v161, v[120:121], off nt
	v_add_co_u32_e32 v120, vcc, 0xfff9b000, v2
	s_waitcnt vmcnt(2)
	v_lshlrev_b32_e32 v156, 16, v157
	v_addc_co_u32_e32 v121, vcc, -1, v3, vcc
	global_load_dword v169, v[120:121], off offset:-2048 nt
	v_add_co_u32_e32 v120, vcc, 0xfff9f000, v2
	v_and_b32_e32 v157, 0xffff0000, v157
	s_nop 0
	v_addc_co_u32_e32 v121, vcc, -1, v3, vcc
	global_load_dword v172, v[120:121], off nt
	v_add_co_u32_e32 v120, vcc, 0xfffa4000, v2
	s_waitcnt vmcnt(3)
	v_lshlrev_b32_e32 v158, 16, v159
	v_addc_co_u32_e32 v121, vcc, -1, v3, vcc
	global_load_dword v173, v[120:121], off offset:-2048 nt
	v_add_co_u32_e32 v120, vcc, 0xfffa8000, v2
	v_and_b32_e32 v159, 0xffff0000, v159
	s_nop 0
	v_addc_co_u32_e32 v121, vcc, -1, v3, vcc
	global_load_dword v175, v[120:121], off nt
	v_add_co_u32_e32 v120, vcc, 0xfffad000, v2
	s_waitcnt vmcnt(4)
	v_lshlrev_b32_e32 v160, 16, v161
	v_addc_co_u32_e32 v121, vcc, -1, v3, vcc
	global_load_dword v177, v[120:121], off offset:-2048 nt
	v_add_co_u32_e32 v120, vcc, 0xfffb1000, v2
	v_and_b32_e32 v161, 0xffff0000, v161
	s_nop 0
	v_addc_co_u32_e32 v121, vcc, -1, v3, vcc
	global_load_dword v179, v[120:121], off nt
	v_add_co_u32_e32 v120, vcc, 0xfffb6000, v2
	s_waitcnt vmcnt(5)
	v_lshlrev_b32_e32 v168, 16, v169
	v_addc_co_u32_e32 v121, vcc, -1, v3, vcc
	global_load_dword v181, v[120:121], off offset:-2048 nt
	v_add_co_u32_e32 v120, vcc, 0xfffba000, v2
	v_and_b32_e32 v169, 0xffff0000, v169
	s_nop 0
	v_addc_co_u32_e32 v121, vcc, -1, v3, vcc
	global_load_dword v183, v[120:121], off nt
	v_add_co_u32_e32 v120, vcc, 0xfffbf000, v2
	s_waitcnt vmcnt(4)
	v_lshlrev_b32_e32 v174, 16, v175
	v_addc_co_u32_e32 v121, vcc, -1, v3, vcc
	v_add_co_u32_e32 v170, vcc, s4, v2
	global_load_dword v185, v[120:121], off offset:-2048 nt
	s_nop 0
	v_addc_co_u32_e32 v171, vcc, -1, v3, vcc
	s_mov_b32 s4, 0xfffc8000
	global_load_dword v209, v[170:171], off nt
	v_add_co_u32_e32 v170, vcc, s4, v2
	s_mov_b32 s4, 0xfffcc000
	s_nop 0
	v_addc_co_u32_e32 v171, vcc, -1, v3, vcc
	global_load_dword v212, v[170:171], off offset:-2048 nt
	v_add_co_u32_e32 v170, vcc, s4, v2
	s_mov_b32 s4, 0xfffd1000
	s_nop 0
	v_addc_co_u32_e32 v171, vcc, -1, v3, vcc
	global_load_dword v213, v[170:171], off nt
	v_add_co_u32_e32 v170, vcc, s4, v2
	s_mov_b32 s4, 0xfffd5000
	s_nop 0
	v_addc_co_u32_e32 v171, vcc, -1, v3, vcc
	global_load_dword v214, v[170:171], off offset:-2048 nt
	v_add_co_u32_e32 v170, vcc, s4, v2
	s_mov_b32 s4, 0xfffda000
	s_nop 0
	v_addc_co_u32_e32 v171, vcc, -1, v3, vcc
	global_load_dword v215, v[170:171], off nt
	v_add_co_u32_e32 v170, vcc, s4, v2
	s_mov_b32 s4, 0xfffde000
	s_nop 0
	v_addc_co_u32_e32 v171, vcc, -1, v3, vcc
	global_load_dword v216, v[170:171], off offset:-2048 nt
	v_add_co_u32_e32 v170, vcc, s4, v2
	s_mov_b32 s4, 0xfffe3000
	s_nop 0
	v_addc_co_u32_e32 v171, vcc, -1, v3, vcc
	global_load_dword v217, v[170:171], off nt
	v_add_co_u32_e32 v170, vcc, s4, v2
	s_mov_b32 s4, 0xfffe7000
	s_nop 0
	v_addc_co_u32_e32 v171, vcc, -1, v3, vcc
	global_load_dword v218, v[170:171], off offset:-2048 nt
	v_add_co_u32_e32 v210, vcc, s4, v2
	s_mov_b32 s4, 0xfffec000
	s_nop 0
	v_addc_co_u32_e32 v211, vcc, -1, v3, vcc
	global_load_dword v219, v[210:211], off nt
	v_add_co_u32_e32 v210, vcc, s4, v2
	s_mov_b32 s4, 0xffff0000
	s_nop 0
	v_addc_co_u32_e32 v211, vcc, -1, v3, vcc
	global_load_dword v220, v[210:211], off offset:-2048 nt
	v_add_co_u32_e32 v210, vcc, s4, v2
	s_mov_b32 s4, 0xffff5000
	s_nop 0
	v_addc_co_u32_e32 v211, vcc, -1, v3, vcc
	global_load_dword v221, v[210:211], off nt
	v_add_co_u32_e32 v210, vcc, s4, v2
	s_movk_i32 s4, 0x9000
	s_nop 0
	v_addc_co_u32_e32 v211, vcc, -1, v3, vcc
	global_load_dword v222, v[210:211], off offset:-2048 nt
	v_add_co_u32_e32 v210, vcc, s4, v2
	s_movk_i32 s4, 0xe000
	s_nop 0
	v_addc_co_u32_e32 v211, vcc, -1, v3, vcc
	global_load_dword v223, v[210:211], off nt
	v_add_co_u32_e32 v210, vcc, s4, v2
	s_movk_i32 s4, 0x2000
	s_nop 0
	v_addc_co_u32_e32 v211, vcc, -1, v3, vcc
	global_load_dword v224, v[210:211], off offset:-2048 nt
	v_add_co_u32_e32 v210, vcc, s4, v2
	s_movk_i32 s4, 0x6000
	s_nop 0
	v_addc_co_u32_e32 v211, vcc, 0, v3, vcc
	global_load_dword v225, v[210:211], off nt
	v_add_co_u32_e32 v210, vcc, s4, v2
	v_lshlrev_b32_e32 v120, 16, v122
	s_nop 0
	v_addc_co_u32_e32 v211, vcc, 0, v3, vcc
	global_load_dword v226, v[210:211], off offset:2048 nt
	v_and_b32_e32 v121, 0xffff0000, v122
	v_pk_fma_f32 v[120:121], v[186:187], v[120:121], v[118:119]
	v_lshlrev_b32_e32 v122, 16, v123
; __device__ __forceinline__ f32x2 un2(unsigned u) { return (f32x2){bf_lo(u), bf_hi(u)}; }
; template <int NDEAD, int B>
; __device__ __forceinline__ void conv31_comp(const unsigned (&cv)[8], const f32x2 (&wk)[31], f32x2 (&acc)[TT]) {
; #pragma unroll
;     for (int q = 0; q < 8; ++q) { const int JJ = 8 * B + q; if (JJ >= NDEAD && JJ < CSTEPS) { const f32x2 v = un2(cv[q]);
; #pragma unroll
;         for (int i = 0; i < TT; ++i) { const int k = JJ - i; if (k >= 0 && k <= 30) acc[i] += wk[k] * v; } } }
; }
	v_and_b32_e32 v123, 0xffff0000, v123
	v_pk_fma_f32 v[120:121], v[150:151], v[122:123], v[120:121]
	v_pk_fma_f32 v[122:123], v[186:187], v[122:123], v[118:119]
	v_pk_fma_f32 v[120:121], v[148:149], v[152:153], v[120:121]
	v_pk_fma_f32 v[122:123], v[150:151], v[152:153], v[122:123]
	v_pk_fma_f32 v[152:153], v[186:187], v[152:153], v[118:119]
	v_pk_fma_f32 v[120:121], v[146:147], v[154:155], v[120:121]
	v_pk_fma_f32 v[122:123], v[148:149], v[154:155], v[122:123]
	v_pk_fma_f32 v[152:153], v[150:151], v[154:155], v[152:153]
	v_pk_fma_f32 v[154:155], v[186:187], v[154:155], v[118:119]
	v_pk_fma_f32 v[120:121], v[144:145], v[156:157], v[120:121]
	v_pk_fma_f32 v[122:123], v[146:147], v[156:157], v[122:123]
	v_pk_fma_f32 v[152:153], v[148:149], v[156:157], v[152:153]
	v_pk_fma_f32 v[154:155], v[150:151], v[156:157], v[154:155]
	v_pk_fma_f32 v[156:157], v[186:187], v[156:157], v[118:119]
	v_pk_fma_f32 v[120:121], v[142:143], v[158:159], v[120:121]
	v_pk_fma_f32 v[122:123], v[144:145], v[158:159], v[122:123]
	v_pk_fma_f32 v[152:153], v[146:147], v[158:159], v[152:153]
	v_pk_fma_f32 v[154:155], v[148:149], v[158:159], v[154:155]
	v_pk_fma_f32 v[156:157], v[150:151], v[158:159], v[156:157]
	v_pk_fma_f32 v[158:159], v[186:187], v[158:159], v[118:119]
	v_pk_fma_f32 v[120:121], v[140:141], v[160:161], v[120:121]
	v_pk_fma_f32 v[122:123], v[142:143], v[160:161], v[122:123]
	v_pk_fma_f32 v[152:153], v[144:145], v[160:161], v[152:153]
	v_pk_fma_f32 v[154:155], v[146:147], v[160:161], v[154:155]
	v_pk_fma_f32 v[156:157], v[148:149], v[160:161], v[156:157]
	v_pk_fma_f32 v[158:159], v[150:151], v[160:161], v[158:159]
	v_pk_fma_f32 v[160:161], v[186:187], v[160:161], v[118:119]
	v_pk_fma_f32 v[120:121], v[138:139], v[168:169], v[120:121]
	v_pk_fma_f32 v[122:123], v[140:141], v[168:169], v[122:123]
	v_pk_fma_f32 v[152:153], v[142:143], v[168:169], v[152:153]
	v_pk_fma_f32 v[154:155], v[144:145], v[168:169], v[154:155]
	v_pk_fma_f32 v[156:157], v[146:147], v[168:169], v[156:157]
	v_pk_fma_f32 v[158:159], v[148:149], v[168:169], v[158:159]
	v_pk_fma_f32 v[160:161], v[150:151], v[168:169], v[160:161]
	v_pk_fma_f32 v[168:169], v[186:187], v[168:169], v[118:119]
	v_lshlrev_b32_e32 v170, 16, v172
	v_and_b32_e32 v171, 0xffff0000, v172
	v_pk_fma_f32 v[120:121], v[136:137], v[170:171], v[120:121]
	v_pk_fma_f32 v[122:123], v[138:139], v[170:171], v[122:123]
	v_pk_fma_f32 v[152:153], v[140:141], v[170:171], v[152:153]
	v_pk_fma_f32 v[154:155], v[142:143], v[170:171], v[154:155]
	v_pk_fma_f32 v[156:157], v[144:145], v[170:171], v[156:157]
	v_pk_fma_f32 v[158:159], v[146:147], v[170:171], v[158:159]
	v_pk_fma_f32 v[160:161], v[148:149], v[170:171], v[160:161]
	v_pk_fma_f32 v[168:169], v[150:151], v[170:171], v[168:169]
	v_pk_fma_f32 v[170:171], v[186:187], v[170:171], v[118:119]
	v_lshlrev_b32_e32 v172, 16, v173
	v_and_b32_e32 v173, 0xffff0000, v173
	v_pk_fma_f32 v[120:121], v[134:135], v[172:173], v[120:121]
	v_pk_fma_f32 v[122:123], v[136:137], v[172:173], v[122:123]
	v_pk_fma_f32 v[152:153], v[138:139], v[172:173], v[152:153]
	v_pk_fma_f32 v[154:155], v[140:141], v[172:173], v[154:155]
	v_pk_fma_f32 v[156:157], v[142:143], v[172:173], v[156:157]
	v_pk_fma_f32 v[158:159], v[144:145], v[172:173], v[158:159]
	v_pk_fma_f32 v[160:161], v[146:147], v[172:173], v[160:161]
	v_pk_fma_f32 v[168:169], v[148:149], v[172:173], v[168:169]
	v_pk_fma_f32 v[170:171], v[150:151], v[172:173], v[170:171]
	v_pk_fma_f32 v[172:173], v[186:187], v[172:173], v[118:119]
	v_and_b32_e32 v175, 0xffff0000, v175
	v_pk_fma_f32 v[120:121], v[132:133], v[174:175], v[120:121]
	v_pk_fma_f32 v[122:123], v[134:135], v[174:175], v[122:123]
	v_pk_fma_f32 v[152:153], v[136:137], v[174:175], v[152:153]
	v_pk_fma_f32 v[154:155], v[138:139], v[174:175], v[154:155]
	v_pk_fma_f32 v[156:157], v[140:141], v[174:175], v[156:157]
	v_pk_fma_f32 v[158:159], v[142:143], v[174:175], v[158:159]
	v_pk_fma_f32 v[160:161], v[144:145], v[174:175], v[160:161]
	v_pk_fma_f32 v[168:169], v[146:147], v[174:175], v[168:169]
	v_pk_fma_f32 v[170:171], v[148:149], v[174:175], v[170:171]
	v_pk_fma_f32 v[172:173], v[150:151], v[174:175], v[172:173]
	v_pk_fma_f32 v[174:175], v[186:187], v[174:175], v[118:119]
	s_waitcnt vmcnt(20)
	v_lshlrev_b32_e32 v176, 16, v177
	v_and_b32_e32 v177, 0xffff0000, v177
	v_pk_fma_f32 v[120:121], v[130:131], v[176:177], v[120:121]
	v_pk_fma_f32 v[122:123], v[132:133], v[176:177], v[122:123]
	v_pk_fma_f32 v[152:153], v[134:135], v[176:177], v[152:153]
	v_pk_fma_f32 v[154:155], v[136:137], v[176:177], v[154:155]
	v_pk_fma_f32 v[156:157], v[138:139], v[176:177], v[156:157]
	v_pk_fma_f32 v[158:159], v[140:141], v[176:177], v[158:159]
	v_pk_fma_f32 v[160:161], v[142:143], v[176:177], v[160:161]
	v_pk_fma_f32 v[168:169], v[144:145], v[176:177], v[168:169]
	v_pk_fma_f32 v[170:171], v[146:147], v[176:177], v[170:171]
	v_pk_fma_f32 v[172:173], v[148:149], v[176:177], v[172:173]
	v_pk_fma_f32 v[174:175], v[150:151], v[176:177], v[174:175]
	v_pk_fma_f32 v[176:177], v[186:187], v[176:177], v[118:119]
	s_waitcnt vmcnt(19)
	v_lshlrev_b32_e32 v178, 16, v179
	v_and_b32_e32 v179, 0xffff0000, v179
	v_pk_fma_f32 v[120:121], v[128:129], v[178:179], v[120:121]
	v_pk_fma_f32 v[122:123], v[130:131], v[178:179], v[122:123]
	v_pk_fma_f32 v[152:153], v[132:133], v[178:179], v[152:153]
	v_pk_fma_f32 v[154:155], v[134:135], v[178:179], v[154:155]
	v_pk_fma_f32 v[156:157], v[136:137], v[178:179], v[156:157]
	v_pk_fma_f32 v[158:159], v[138:139], v[178:179], v[158:159]
	v_pk_fma_f32 v[160:161], v[140:141], v[178:179], v[160:161]
	v_pk_fma_f32 v[168:169], v[142:143], v[178:179], v[168:169]
	v_pk_fma_f32 v[170:171], v[144:145], v[178:179], v[170:171]
	v_pk_fma_f32 v[172:173], v[146:147], v[178:179], v[172:173]
	v_pk_fma_f32 v[174:175], v[148:149], v[178:179], v[174:175]
	v_pk_fma_f32 v[176:177], v[150:151], v[178:179], v[176:177]
	v_pk_fma_f32 v[178:179], v[186:187], v[178:179], v[118:119]
	s_waitcnt vmcnt(18)
; __device__ __forceinline__ f32x2 un2(unsigned u) { return (f32x2){bf_lo(u), bf_hi(u)}; }
; template <int NDEAD, int B>
; __device__ __forceinline__ void conv31_comp(const unsigned (&cv)[8], const f32x2 (&wk)[31], f32x2 (&acc)[TT]) {
; #pragma unroll
;     for (int q = 0; q < 8; ++q) { const int JJ = 8 * B + q; if (JJ >= NDEAD && JJ < CSTEPS) { const f32x2 v = un2(cv[q]);
; #pragma unroll
;         for (int i = 0; i < TT; ++i) { const int k = JJ - i; if (k >= 0 && k <= 30) acc[i] += wk[k] * v; } } }
; }
	v_lshlrev_b32_e32 v180, 16, v181
	v_and_b32_e32 v181, 0xffff0000, v181
	v_pk_fma_f32 v[120:121], v[126:127], v[180:181], v[120:121]
	v_pk_fma_f32 v[122:123], v[128:129], v[180:181], v[122:123]
	v_pk_fma_f32 v[152:153], v[130:131], v[180:181], v[152:153]
	v_pk_fma_f32 v[154:155], v[132:133], v[180:181], v[154:155]
	v_pk_fma_f32 v[156:157], v[134:135], v[180:181], v[156:157]
	v_pk_fma_f32 v[158:159], v[136:137], v[180:181], v[158:159]
	v_pk_fma_f32 v[160:161], v[138:139], v[180:181], v[160:161]
	v_pk_fma_f32 v[168:169], v[140:141], v[180:181], v[168:169]
	v_pk_fma_f32 v[170:171], v[142:143], v[180:181], v[170:171]
	v_pk_fma_f32 v[172:173], v[144:145], v[180:181], v[172:173]
	v_pk_fma_f32 v[174:175], v[146:147], v[180:181], v[174:175]
	v_pk_fma_f32 v[176:177], v[148:149], v[180:181], v[176:177]
	v_pk_fma_f32 v[178:179], v[150:151], v[180:181], v[178:179]
	v_pk_fma_f32 v[180:181], v[186:187], v[180:181], v[118:119]
	s_waitcnt vmcnt(17)
	v_lshlrev_b32_e32 v182, 16, v183
	v_and_b32_e32 v183, 0xffff0000, v183
	v_pk_fma_f32 v[120:121], v[124:125], v[182:183], v[120:121]
	v_pk_fma_f32 v[122:123], v[126:127], v[182:183], v[122:123]
	v_pk_fma_f32 v[152:153], v[128:129], v[182:183], v[152:153]
	v_pk_fma_f32 v[154:155], v[130:131], v[182:183], v[154:155]
	v_pk_fma_f32 v[156:157], v[132:133], v[182:183], v[156:157]
	v_pk_fma_f32 v[158:159], v[134:135], v[182:183], v[158:159]
	v_pk_fma_f32 v[160:161], v[136:137], v[182:183], v[160:161]
	v_pk_fma_f32 v[168:169], v[138:139], v[182:183], v[168:169]
	v_pk_fma_f32 v[170:171], v[140:141], v[182:183], v[170:171]
	v_pk_fma_f32 v[172:173], v[142:143], v[182:183], v[172:173]
	v_pk_fma_f32 v[174:175], v[144:145], v[182:183], v[174:175]
	v_pk_fma_f32 v[176:177], v[146:147], v[182:183], v[176:177]
	v_pk_fma_f32 v[178:179], v[148:149], v[182:183], v[178:179]
	v_pk_fma_f32 v[180:181], v[150:151], v[182:183], v[180:181]
	v_pk_fma_f32 v[182:183], v[186:187], v[182:183], v[118:119]
	s_waitcnt vmcnt(16)
	v_lshlrev_b32_e32 v184, 16, v185
	v_and_b32_e32 v185, 0xffff0000, v185
	v_pk_fma_f32 v[120:121], v[116:117], v[184:185], v[120:121]
	v_pk_fma_f32 v[122:123], v[124:125], v[184:185], v[122:123]
	v_pk_fma_f32 v[152:153], v[126:127], v[184:185], v[152:153]
	v_pk_fma_f32 v[154:155], v[128:129], v[184:185], v[154:155]
	v_pk_fma_f32 v[156:157], v[130:131], v[184:185], v[156:157]
	v_pk_fma_f32 v[158:159], v[132:133], v[184:185], v[158:159]
	v_pk_fma_f32 v[160:161], v[134:135], v[184:185], v[160:161]
	v_pk_fma_f32 v[168:169], v[136:137], v[184:185], v[168:169]
	v_pk_fma_f32 v[170:171], v[138:139], v[184:185], v[170:171]
	v_pk_fma_f32 v[172:173], v[140:141], v[184:185], v[172:173]
	v_pk_fma_f32 v[174:175], v[142:143], v[184:185], v[174:175]
	v_pk_fma_f32 v[176:177], v[144:145], v[184:185], v[176:177]
	v_pk_fma_f32 v[178:179], v[146:147], v[184:185], v[178:179]
	v_pk_fma_f32 v[180:181], v[148:149], v[184:185], v[180:181]
	v_pk_fma_f32 v[182:183], v[150:151], v[184:185], v[182:183]
	v_pk_fma_f32 v[184:185], v[186:187], v[184:185], v[118:119]
	s_waitcnt vmcnt(15)
	v_lshlrev_b32_e32 v210, 16, v209
	v_and_b32_e32 v211, 0xffff0000, v209
	v_pk_fma_f32 v[120:121], v[114:115], v[210:211], v[120:121]
	v_pk_fma_f32 v[122:123], v[116:117], v[210:211], v[122:123]
	v_pk_fma_f32 v[152:153], v[124:125], v[210:211], v[152:153]
	v_pk_fma_f32 v[154:155], v[126:127], v[210:211], v[154:155]
	v_pk_fma_f32 v[156:157], v[128:129], v[210:211], v[156:157]
	v_pk_fma_f32 v[158:159], v[130:131], v[210:211], v[158:159]
	v_pk_fma_f32 v[160:161], v[132:133], v[210:211], v[160:161]
	v_pk_fma_f32 v[168:169], v[134:135], v[210:211], v[168:169]
	v_pk_fma_f32 v[170:171], v[136:137], v[210:211], v[170:171]
	v_pk_fma_f32 v[172:173], v[138:139], v[210:211], v[172:173]
	v_pk_fma_f32 v[174:175], v[140:141], v[210:211], v[174:175]
	v_pk_fma_f32 v[176:177], v[142:143], v[210:211], v[176:177]
	v_pk_fma_f32 v[178:179], v[144:145], v[210:211], v[178:179]
	v_pk_fma_f32 v[180:181], v[146:147], v[210:211], v[180:181]
	v_pk_fma_f32 v[182:183], v[148:149], v[210:211], v[182:183]
	v_pk_fma_f32 v[184:185], v[150:151], v[210:211], v[184:185]
	s_waitcnt vmcnt(14)
	v_lshlrev_b32_e32 v210, 16, v212
	v_and_b32_e32 v211, 0xffff0000, v212
	v_pk_fma_f32 v[120:121], v[112:113], v[210:211], v[120:121]
	v_pk_fma_f32 v[122:123], v[114:115], v[210:211], v[122:123]
	v_pk_fma_f32 v[152:153], v[116:117], v[210:211], v[152:153]
	v_pk_fma_f32 v[154:155], v[124:125], v[210:211], v[154:155]
	v_pk_fma_f32 v[156:157], v[126:127], v[210:211], v[156:157]
	v_pk_fma_f32 v[158:159], v[128:129], v[210:211], v[158:159]
	v_pk_fma_f32 v[160:161], v[130:131], v[210:211], v[160:161]
	v_pk_fma_f32 v[168:169], v[132:133], v[210:211], v[168:169]
	v_pk_fma_f32 v[170:171], v[134:135], v[210:211], v[170:171]
	v_pk_fma_f32 v[172:173], v[136:137], v[210:211], v[172:173]
	v_pk_fma_f32 v[174:175], v[138:139], v[210:211], v[174:175]
	v_pk_fma_f32 v[176:177], v[140:141], v[210:211], v[176:177]
	v_pk_fma_f32 v[178:179], v[142:143], v[210:211], v[178:179]
	v_pk_fma_f32 v[180:181], v[144:145], v[210:211], v[180:181]
	v_pk_fma_f32 v[182:183], v[146:147], v[210:211], v[182:183]
	v_pk_fma_f32 v[184:185], v[148:149], v[210:211], v[184:185]
	s_waitcnt vmcnt(13)
; __device__ __forceinline__ f32x2 un2(unsigned u) { return (f32x2){bf_lo(u), bf_hi(u)}; }
; template <int NDEAD, int B>
; __device__ __forceinline__ void conv31_comp(const unsigned (&cv)[8], const f32x2 (&wk)[31], f32x2 (&acc)[TT]) {
; #pragma unroll
;     for (int q = 0; q < 8; ++q) { const int JJ = 8 * B + q; if (JJ >= NDEAD && JJ < CSTEPS) { const f32x2 v = un2(cv[q]);
; #pragma unroll
;         for (int i = 0; i < TT; ++i) { const int k = JJ - i; if (k >= 0 && k <= 30) acc[i] += wk[k] * v; } } }
; }
	v_lshlrev_b32_e32 v210, 16, v213
	v_and_b32_e32 v211, 0xffff0000, v213
	v_pk_fma_f32 v[120:121], v[110:111], v[210:211], v[120:121]
	v_pk_fma_f32 v[122:123], v[112:113], v[210:211], v[122:123]
	v_pk_fma_f32 v[152:153], v[114:115], v[210:211], v[152:153]
	v_pk_fma_f32 v[154:155], v[116:117], v[210:211], v[154:155]
	v_pk_fma_f32 v[156:157], v[124:125], v[210:211], v[156:157]
	v_pk_fma_f32 v[158:159], v[126:127], v[210:211], v[158:159]
	v_pk_fma_f32 v[160:161], v[128:129], v[210:211], v[160:161]
	v_pk_fma_f32 v[168:169], v[130:131], v[210:211], v[168:169]
	v_pk_fma_f32 v[170:171], v[132:133], v[210:211], v[170:171]
	v_pk_fma_f32 v[172:173], v[134:135], v[210:211], v[172:173]
	v_pk_fma_f32 v[174:175], v[136:137], v[210:211], v[174:175]
	v_pk_fma_f32 v[176:177], v[138:139], v[210:211], v[176:177]
	v_pk_fma_f32 v[178:179], v[140:141], v[210:211], v[178:179]
	v_pk_fma_f32 v[180:181], v[142:143], v[210:211], v[180:181]
	v_pk_fma_f32 v[182:183], v[144:145], v[210:211], v[182:183]
	v_pk_fma_f32 v[184:185], v[146:147], v[210:211], v[184:185]
	s_waitcnt vmcnt(12)
	v_lshlrev_b32_e32 v210, 16, v214
	v_and_b32_e32 v211, 0xffff0000, v214
	v_pk_fma_f32 v[120:121], v[108:109], v[210:211], v[120:121]
	v_pk_fma_f32 v[122:123], v[110:111], v[210:211], v[122:123]
	v_pk_fma_f32 v[152:153], v[112:113], v[210:211], v[152:153]
	v_pk_fma_f32 v[154:155], v[114:115], v[210:211], v[154:155]
	v_pk_fma_f32 v[156:157], v[116:117], v[210:211], v[156:157]
	v_pk_fma_f32 v[158:159], v[124:125], v[210:211], v[158:159]
	v_pk_fma_f32 v[160:161], v[126:127], v[210:211], v[160:161]
	v_pk_fma_f32 v[168:169], v[128:129], v[210:211], v[168:169]
	v_pk_fma_f32 v[170:171], v[130:131], v[210:211], v[170:171]
	v_pk_fma_f32 v[172:173], v[132:133], v[210:211], v[172:173]
	v_pk_fma_f32 v[174:175], v[134:135], v[210:211], v[174:175]
	v_pk_fma_f32 v[176:177], v[136:137], v[210:211], v[176:177]
	v_pk_fma_f32 v[178:179], v[138:139], v[210:211], v[178:179]
	v_pk_fma_f32 v[180:181], v[140:141], v[210:211], v[180:181]
	v_pk_fma_f32 v[182:183], v[142:143], v[210:211], v[182:183]
	v_pk_fma_f32 v[184:185], v[144:145], v[210:211], v[184:185]
	s_waitcnt vmcnt(11)
	v_lshlrev_b32_e32 v210, 16, v215
	v_and_b32_e32 v211, 0xffff0000, v215
	v_pk_fma_f32 v[120:121], v[106:107], v[210:211], v[120:121]
	v_pk_fma_f32 v[122:123], v[108:109], v[210:211], v[122:123]
	v_pk_fma_f32 v[152:153], v[110:111], v[210:211], v[152:153]
	v_pk_fma_f32 v[154:155], v[112:113], v[210:211], v[154:155]
	v_pk_fma_f32 v[156:157], v[114:115], v[210:211], v[156:157]
	v_pk_fma_f32 v[158:159], v[116:117], v[210:211], v[158:159]
	v_pk_fma_f32 v[160:161], v[124:125], v[210:211], v[160:161]
	v_pk_fma_f32 v[168:169], v[126:127], v[210:211], v[168:169]
	v_pk_fma_f32 v[170:171], v[128:129], v[210:211], v[170:171]
	v_pk_fma_f32 v[172:173], v[130:131], v[210:211], v[172:173]
	v_pk_fma_f32 v[174:175], v[132:133], v[210:211], v[174:175]
	v_pk_fma_f32 v[176:177], v[134:135], v[210:211], v[176:177]
	v_pk_fma_f32 v[178:179], v[136:137], v[210:211], v[178:179]
	v_pk_fma_f32 v[180:181], v[138:139], v[210:211], v[180:181]
	v_pk_fma_f32 v[182:183], v[140:141], v[210:211], v[182:183]
	v_pk_fma_f32 v[184:185], v[142:143], v[210:211], v[184:185]
	s_waitcnt vmcnt(10)
	v_lshlrev_b32_e32 v210, 16, v216
	v_and_b32_e32 v211, 0xffff0000, v216
	v_pk_fma_f32 v[120:121], v[104:105], v[210:211], v[120:121]
	v_pk_fma_f32 v[122:123], v[106:107], v[210:211], v[122:123]
	v_pk_fma_f32 v[152:153], v[108:109], v[210:211], v[152:153]
	v_pk_fma_f32 v[154:155], v[110:111], v[210:211], v[154:155]
	v_pk_fma_f32 v[156:157], v[112:113], v[210:211], v[156:157]
	v_pk_fma_f32 v[158:159], v[114:115], v[210:211], v[158:159]
	v_pk_fma_f32 v[160:161], v[116:117], v[210:211], v[160:161]
	v_pk_fma_f32 v[168:169], v[124:125], v[210:211], v[168:169]
	v_pk_fma_f32 v[170:171], v[126:127], v[210:211], v[170:171]
	v_pk_fma_f32 v[172:173], v[128:129], v[210:211], v[172:173]
	v_pk_fma_f32 v[174:175], v[130:131], v[210:211], v[174:175]
	v_pk_fma_f32 v[176:177], v[132:133], v[210:211], v[176:177]
	v_pk_fma_f32 v[178:179], v[134:135], v[210:211], v[178:179]
	v_pk_fma_f32 v[180:181], v[136:137], v[210:211], v[180:181]
	v_pk_fma_f32 v[182:183], v[138:139], v[210:211], v[182:183]
	v_pk_fma_f32 v[184:185], v[140:141], v[210:211], v[184:185]
	s_waitcnt vmcnt(9)
	v_lshlrev_b32_e32 v210, 16, v217
	v_and_b32_e32 v211, 0xffff0000, v217
	v_pk_fma_f32 v[120:121], v[102:103], v[210:211], v[120:121]
	v_pk_fma_f32 v[122:123], v[104:105], v[210:211], v[122:123]
	v_pk_fma_f32 v[152:153], v[106:107], v[210:211], v[152:153]
	v_pk_fma_f32 v[154:155], v[108:109], v[210:211], v[154:155]
	v_pk_fma_f32 v[156:157], v[110:111], v[210:211], v[156:157]
	v_pk_fma_f32 v[158:159], v[112:113], v[210:211], v[158:159]
	v_pk_fma_f32 v[160:161], v[114:115], v[210:211], v[160:161]
	v_pk_fma_f32 v[168:169], v[116:117], v[210:211], v[168:169]
	v_pk_fma_f32 v[170:171], v[124:125], v[210:211], v[170:171]
	v_pk_fma_f32 v[172:173], v[126:127], v[210:211], v[172:173]
	v_pk_fma_f32 v[174:175], v[128:129], v[210:211], v[174:175]
	v_pk_fma_f32 v[176:177], v[130:131], v[210:211], v[176:177]
	v_pk_fma_f32 v[178:179], v[132:133], v[210:211], v[178:179]
	v_pk_fma_f32 v[180:181], v[134:135], v[210:211], v[180:181]
	v_pk_fma_f32 v[182:183], v[136:137], v[210:211], v[182:183]
	v_pk_fma_f32 v[184:185], v[138:139], v[210:211], v[184:185]
	s_waitcnt vmcnt(8)
; __device__ __forceinline__ f32x2 un2(unsigned u) { return (f32x2){bf_lo(u), bf_hi(u)}; }
; template <int NDEAD, int B>
; __device__ __forceinline__ void conv31_load(const bf16_t* __restrict__ Pt, unsigned (&cv)[8]) {
; #pragma unroll
;     for (int q = 0; q < 8; ++q) { const int JJ = 8 * B + q; if (JJ >= NDEAD && JJ < CSTEPS) cv[q] = *(const unsigned*)(Pt + (ptrdiff_t)(JJ - 30) * NCO + OV); }
; }
; template <int NDEAD, int B>
; __device__ __forceinline__ void conv31_comp(const unsigned (&cv)[8], const f32x2 (&wk)[31], f32x2 (&acc)[TT]) {
; #pragma unroll
;     for (int q = 0; q < 8; ++q) { const int JJ = 8 * B + q; if (JJ >= NDEAD && JJ < CSTEPS) { const f32x2 v = un2(cv[q]);
; #pragma unroll
;         for (int i = 0; i < TT; ++i) { const int k = JJ - i; if (k >= 0 && k <= 30) acc[i] += wk[k] * v; } } }
; }
	v_lshlrev_b32_e32 v210, 16, v218
	v_and_b32_e32 v211, 0xffff0000, v218
	s_mov_b32 s4, 0xb000
	v_pk_fma_f32 v[120:121], v[100:101], v[210:211], v[120:121]
	v_pk_fma_f32 v[122:123], v[102:103], v[210:211], v[122:123]
	v_pk_fma_f32 v[152:153], v[104:105], v[210:211], v[152:153]
	v_pk_fma_f32 v[154:155], v[106:107], v[210:211], v[154:155]
	v_pk_fma_f32 v[156:157], v[108:109], v[210:211], v[156:157]
	v_pk_fma_f32 v[158:159], v[110:111], v[210:211], v[158:159]
	v_pk_fma_f32 v[160:161], v[112:113], v[210:211], v[160:161]
	v_pk_fma_f32 v[168:169], v[114:115], v[210:211], v[168:169]
	v_pk_fma_f32 v[170:171], v[116:117], v[210:211], v[170:171]
	v_pk_fma_f32 v[172:173], v[124:125], v[210:211], v[172:173]
	v_pk_fma_f32 v[174:175], v[126:127], v[210:211], v[174:175]
	v_pk_fma_f32 v[176:177], v[128:129], v[210:211], v[176:177]
	v_pk_fma_f32 v[178:179], v[130:131], v[210:211], v[178:179]
	v_pk_fma_f32 v[180:181], v[132:133], v[210:211], v[180:181]
	v_pk_fma_f32 v[182:183], v[134:135], v[210:211], v[182:183]
	v_pk_fma_f32 v[184:185], v[136:137], v[210:211], v[184:185]
	v_add_co_u32_e32 v210, vcc, s4, v2
	s_mov_b32 s4, 0xf000
	s_nop 0
	v_addc_co_u32_e32 v211, vcc, 0, v3, vcc
	v_add_co_u32_e32 v212, vcc, s4, v2
	s_mov_b32 s4, 0x14000
	s_nop 0
	v_addc_co_u32_e32 v213, vcc, 0, v3, vcc
	global_load_dword v211, v[210:211], off nt
	s_waitcnt vmcnt(8)
	v_lshlrev_b32_e32 v218, 16, v219
	global_load_dword v209, v[212:213], off offset:2048 nt
	v_add_co_u32_e32 v212, vcc, s4, v2
	s_mov_b32 s4, 0x18000
	s_nop 0
	v_addc_co_u32_e32 v213, vcc, 0, v3, vcc
	global_load_dword v210, v[212:213], off nt
	v_add_co_u32_e32 v212, vcc, s4, v2
	s_mov_b32 s4, 0x1d000
	s_nop 0
	v_addc_co_u32_e32 v213, vcc, 0, v3, vcc
	v_add_co_u32_e32 v214, vcc, s4, v2
	v_and_b32_e32 v219, 0xffff0000, v219
	s_nop 0
	v_addc_co_u32_e32 v215, vcc, 0, v3, vcc
	s_mov_b32 s4, 0x21000
	v_pk_fma_f32 v[120:121], v[98:99], v[218:219], v[120:121]
	v_pk_fma_f32 v[122:123], v[100:101], v[218:219], v[122:123]
	v_pk_fma_f32 v[152:153], v[102:103], v[218:219], v[152:153]
	v_pk_fma_f32 v[154:155], v[104:105], v[218:219], v[154:155]
	v_pk_fma_f32 v[156:157], v[106:107], v[218:219], v[156:157]
	v_pk_fma_f32 v[158:159], v[108:109], v[218:219], v[158:159]
	v_pk_fma_f32 v[160:161], v[110:111], v[218:219], v[160:161]
	v_pk_fma_f32 v[168:169], v[112:113], v[218:219], v[168:169]
	v_pk_fma_f32 v[170:171], v[114:115], v[218:219], v[170:171]
	v_pk_fma_f32 v[172:173], v[116:117], v[218:219], v[172:173]
	v_pk_fma_f32 v[174:175], v[124:125], v[218:219], v[174:175]
	v_pk_fma_f32 v[176:177], v[126:127], v[218:219], v[176:177]
	v_pk_fma_f32 v[178:179], v[128:129], v[218:219], v[178:179]
	v_pk_fma_f32 v[180:181], v[130:131], v[218:219], v[180:181]
	v_pk_fma_f32 v[182:183], v[132:133], v[218:219], v[182:183]
	v_pk_fma_f32 v[184:185], v[134:135], v[218:219], v[184:185]
	s_waitcnt vmcnt(9)
	v_lshlrev_b32_e32 v218, 16, v220
	v_and_b32_e32 v219, 0xffff0000, v220
	global_load_dword v212, v[212:213], off offset:2048 nt
	v_pk_fma_f32 v[120:121], v[96:97], v[218:219], v[120:121]
	global_load_dword v213, v[214:215], off nt
	v_add_co_u32_e32 v214, vcc, s4, v2
	v_pk_fma_f32 v[122:123], v[98:99], v[218:219], v[122:123]
	v_pk_fma_f32 v[152:153], v[100:101], v[218:219], v[152:153]
	v_pk_fma_f32 v[154:155], v[102:103], v[218:219], v[154:155]
	v_pk_fma_f32 v[156:157], v[104:105], v[218:219], v[156:157]
	v_pk_fma_f32 v[158:159], v[106:107], v[218:219], v[158:159]
	v_pk_fma_f32 v[160:161], v[108:109], v[218:219], v[160:161]
	v_pk_fma_f32 v[168:169], v[110:111], v[218:219], v[168:169]
	v_pk_fma_f32 v[170:171], v[112:113], v[218:219], v[170:171]
	v_pk_fma_f32 v[172:173], v[114:115], v[218:219], v[172:173]
	v_pk_fma_f32 v[174:175], v[116:117], v[218:219], v[174:175]
	v_pk_fma_f32 v[176:177], v[124:125], v[218:219], v[176:177]
	v_pk_fma_f32 v[178:179], v[126:127], v[218:219], v[178:179]
	v_pk_fma_f32 v[180:181], v[128:129], v[218:219], v[180:181]
	v_pk_fma_f32 v[182:183], v[130:131], v[218:219], v[182:183]
	v_pk_fma_f32 v[184:185], v[132:133], v[218:219], v[184:185]
	s_waitcnt vmcnt(10)
	v_lshlrev_b32_e32 v218, 16, v221
	v_and_b32_e32 v219, 0xffff0000, v221
	v_addc_co_u32_e32 v215, vcc, 0, v3, vcc
	s_mov_b32 s4, 0x26000
	v_pk_fma_f32 v[120:121], v[12:13], v[218:219], v[120:121]
	v_pk_fma_f32 v[122:123], v[96:97], v[218:219], v[122:123]
	v_pk_fma_f32 v[152:153], v[98:99], v[218:219], v[152:153]
	v_pk_fma_f32 v[154:155], v[100:101], v[218:219], v[154:155]
	v_pk_fma_f32 v[156:157], v[102:103], v[218:219], v[156:157]
	v_pk_fma_f32 v[158:159], v[104:105], v[218:219], v[158:159]
	v_pk_fma_f32 v[160:161], v[106:107], v[218:219], v[160:161]
	v_pk_fma_f32 v[168:169], v[108:109], v[218:219], v[168:169]
	v_pk_fma_f32 v[170:171], v[110:111], v[218:219], v[170:171]
	v_pk_fma_f32 v[172:173], v[112:113], v[218:219], v[172:173]
	v_pk_fma_f32 v[174:175], v[114:115], v[218:219], v[174:175]
	v_pk_fma_f32 v[176:177], v[116:117], v[218:219], v[176:177]
	v_pk_fma_f32 v[178:179], v[124:125], v[218:219], v[178:179]
	v_pk_fma_f32 v[180:181], v[126:127], v[218:219], v[180:181]
	v_pk_fma_f32 v[182:183], v[128:129], v[218:219], v[182:183]
	v_pk_fma_f32 v[184:185], v[130:131], v[218:219], v[184:185]
	s_waitcnt vmcnt(9)
; __device__ __forceinline__ f32x2 un2(unsigned u) { return (f32x2){bf_lo(u), bf_hi(u)}; }
; template <int NDEAD, int B>
; __device__ __forceinline__ void conv31_load(const bf16_t* __restrict__ Pt, unsigned (&cv)[8]) {
; #pragma unroll
;     for (int q = 0; q < 8; ++q) { const int JJ = 8 * B + q; if (JJ >= NDEAD && JJ < CSTEPS) cv[q] = *(const unsigned*)(Pt + (ptrdiff_t)(JJ - 30) * NCO + OV); }
; }
; template <int NDEAD, int B>
; __device__ __forceinline__ void conv31_comp(const unsigned (&cv)[8], const f32x2 (&wk)[31], f32x2 (&acc)[TT]) {
; #pragma unroll
;     for (int q = 0; q < 8; ++q) { const int JJ = 8 * B + q; if (JJ >= NDEAD && JJ < CSTEPS) { const f32x2 v = un2(cv[q]);
; #pragma unroll
;         for (int i = 0; i < TT; ++i) { const int k = JJ - i; if (k >= 0 && k <= 30) acc[i] += wk[k] * v; } } }
; }
	v_lshlrev_b32_e32 v218, 16, v222
	v_and_b32_e32 v219, 0xffff0000, v222
	v_add_co_u32_e32 v216, vcc, s4, v2
	v_pk_fma_f32 v[120:121], v[10:11], v[218:219], v[120:121]
	v_pk_fma_f32 v[122:123], v[12:13], v[218:219], v[122:123]
	v_pk_fma_f32 v[152:153], v[96:97], v[218:219], v[152:153]
	v_pk_fma_f32 v[154:155], v[98:99], v[218:219], v[154:155]
	v_pk_fma_f32 v[156:157], v[100:101], v[218:219], v[156:157]
	v_pk_fma_f32 v[158:159], v[102:103], v[218:219], v[158:159]
	v_pk_fma_f32 v[160:161], v[104:105], v[218:219], v[160:161]
	v_pk_fma_f32 v[168:169], v[106:107], v[218:219], v[168:169]
	v_pk_fma_f32 v[170:171], v[108:109], v[218:219], v[170:171]
	v_pk_fma_f32 v[172:173], v[110:111], v[218:219], v[172:173]
	v_pk_fma_f32 v[174:175], v[112:113], v[218:219], v[174:175]
	v_pk_fma_f32 v[176:177], v[114:115], v[218:219], v[176:177]
	v_pk_fma_f32 v[178:179], v[116:117], v[218:219], v[178:179]
	v_pk_fma_f32 v[180:181], v[124:125], v[218:219], v[180:181]
	v_pk_fma_f32 v[182:183], v[126:127], v[218:219], v[182:183]
	v_pk_fma_f32 v[184:185], v[128:129], v[218:219], v[184:185]
	s_waitcnt vmcnt(8)
	v_lshlrev_b32_e32 v218, 16, v223
	v_and_b32_e32 v219, 0xffff0000, v223
	v_addc_co_u32_e32 v217, vcc, 0, v3, vcc
	s_mov_b32 s4, 0x2a000
	v_pk_fma_f32 v[120:121], v[8:9], v[218:219], v[120:121]
	v_pk_fma_f32 v[122:123], v[10:11], v[218:219], v[122:123]
	v_pk_fma_f32 v[152:153], v[12:13], v[218:219], v[152:153]
	v_pk_fma_f32 v[154:155], v[96:97], v[218:219], v[154:155]
	v_pk_fma_f32 v[156:157], v[98:99], v[218:219], v[156:157]
	v_pk_fma_f32 v[158:159], v[100:101], v[218:219], v[158:159]
	v_pk_fma_f32 v[160:161], v[102:103], v[218:219], v[160:161]
	v_pk_fma_f32 v[168:169], v[104:105], v[218:219], v[168:169]
	v_pk_fma_f32 v[170:171], v[106:107], v[218:219], v[170:171]
	v_pk_fma_f32 v[172:173], v[108:109], v[218:219], v[172:173]
	v_pk_fma_f32 v[174:175], v[110:111], v[218:219], v[174:175]
	v_pk_fma_f32 v[176:177], v[112:113], v[218:219], v[176:177]
	v_pk_fma_f32 v[178:179], v[114:115], v[218:219], v[178:179]
	v_pk_fma_f32 v[180:181], v[116:117], v[218:219], v[180:181]
	v_pk_fma_f32 v[182:183], v[124:125], v[218:219], v[182:183]
	v_pk_fma_f32 v[184:185], v[126:127], v[218:219], v[184:185]
	s_waitcnt vmcnt(7)
	v_lshlrev_b32_e32 v218, 16, v224
	v_and_b32_e32 v219, 0xffff0000, v224
	global_load_dword v214, v[214:215], off offset:2048 nt
	v_pk_fma_f32 v[120:121], v[6:7], v[218:219], v[120:121]
	global_load_dword v215, v[216:217], off nt
	v_add_co_u32_e32 v216, vcc, s4, v2
	v_pk_fma_f32 v[220:221], v[8:9], v[218:219], v[122:123]
	v_pk_fma_f32 v[152:153], v[10:11], v[218:219], v[152:153]
	v_pk_fma_f32 v[154:155], v[12:13], v[218:219], v[154:155]
	v_pk_fma_f32 v[156:157], v[96:97], v[218:219], v[156:157]
	v_pk_fma_f32 v[158:159], v[98:99], v[218:219], v[158:159]
	v_pk_fma_f32 v[160:161], v[100:101], v[218:219], v[160:161]
	v_pk_fma_f32 v[168:169], v[102:103], v[218:219], v[168:169]
	v_pk_fma_f32 v[170:171], v[104:105], v[218:219], v[170:171]
	v_pk_fma_f32 v[172:173], v[106:107], v[218:219], v[172:173]
	v_pk_fma_f32 v[174:175], v[108:109], v[218:219], v[174:175]
	v_pk_fma_f32 v[176:177], v[110:111], v[218:219], v[176:177]
	v_pk_fma_f32 v[178:179], v[112:113], v[218:219], v[178:179]
	v_pk_fma_f32 v[180:181], v[114:115], v[218:219], v[180:181]
	v_pk_fma_f32 v[182:183], v[116:117], v[218:219], v[182:183]
	v_pk_fma_f32 v[184:185], v[124:125], v[218:219], v[184:185]
	s_waitcnt vmcnt(8)
	v_lshlrev_b32_e32 v218, 16, v225
	v_and_b32_e32 v219, 0xffff0000, v225
	v_addc_co_u32_e32 v217, vcc, 0, v3, vcc
	v_pk_fma_f32 v[122:123], v[4:5], v[218:219], v[120:121]
	v_pk_fma_f32 v[120:121], v[6:7], v[218:219], v[220:221]
	v_pk_fma_f32 v[152:153], v[8:9], v[218:219], v[152:153]
	v_pk_fma_f32 v[154:155], v[10:11], v[218:219], v[154:155]
	v_pk_fma_f32 v[156:157], v[12:13], v[218:219], v[156:157]
	v_pk_fma_f32 v[158:159], v[96:97], v[218:219], v[158:159]
	v_pk_fma_f32 v[160:161], v[98:99], v[218:219], v[160:161]
	v_pk_fma_f32 v[168:169], v[100:101], v[218:219], v[168:169]
	v_pk_fma_f32 v[170:171], v[102:103], v[218:219], v[170:171]
	v_pk_fma_f32 v[172:173], v[104:105], v[218:219], v[172:173]
	v_pk_fma_f32 v[174:175], v[106:107], v[218:219], v[174:175]
	v_pk_fma_f32 v[176:177], v[108:109], v[218:219], v[176:177]
	v_pk_fma_f32 v[178:179], v[110:111], v[218:219], v[178:179]
	v_pk_fma_f32 v[180:181], v[112:113], v[218:219], v[180:181]
	v_pk_fma_f32 v[182:183], v[114:115], v[218:219], v[182:183]
	v_pk_fma_f32 v[184:185], v[116:117], v[218:219], v[184:185]
	s_waitcnt vmcnt(7)
	v_lshlrev_b32_e32 v218, 16, v226
	v_and_b32_e32 v219, 0xffff0000, v226
	s_mov_b32 s4, 0x2f000
	v_pk_fma_f32 v[120:121], v[4:5], v[218:219], v[120:121]
	v_pk_fma_f32 v[152:153], v[6:7], v[218:219], v[152:153]
	v_pk_fma_f32 v[154:155], v[8:9], v[218:219], v[154:155]
	v_pk_fma_f32 v[156:157], v[10:11], v[218:219], v[156:157]
	v_pk_fma_f32 v[158:159], v[12:13], v[218:219], v[158:159]
	v_pk_fma_f32 v[160:161], v[96:97], v[218:219], v[160:161]
	v_pk_fma_f32 v[168:169], v[98:99], v[218:219], v[168:169]
	v_pk_fma_f32 v[170:171], v[100:101], v[218:219], v[170:171]
	v_pk_fma_f32 v[172:173], v[102:103], v[218:219], v[172:173]
	v_pk_fma_f32 v[174:175], v[104:105], v[218:219], v[174:175]
	v_pk_fma_f32 v[176:177], v[106:107], v[218:219], v[176:177]
	v_pk_fma_f32 v[178:179], v[108:109], v[218:219], v[178:179]
	v_pk_fma_f32 v[180:181], v[110:111], v[218:219], v[180:181]
	v_pk_fma_f32 v[182:183], v[112:113], v[218:219], v[182:183]
	v_pk_fma_f32 v[184:185], v[114:115], v[218:219], v[184:185]
	v_add_co_u32_e32 v218, vcc, s4, v2
	global_load_dword v216, v[216:217], off offset:2048 nt
	s_nop 0
	v_addc_co_u32_e32 v219, vcc, 0, v3, vcc
	s_mov_b32 s4, 0x33000
	global_load_dword v217, v[218:219], off nt
	v_add_co_u32_e32 v218, vcc, s4, v2
	s_mov_b32 s4, 0x38000
	s_nop 0
	v_addc_co_u32_e32 v219, vcc, 0, v3, vcc
	v_add_co_u32_e32 v220, vcc, s4, v2
	s_mov_b32 s4, 0x3c000
	s_nop 0
	v_addc_co_u32_e32 v221, vcc, 0, v3, vcc
	global_load_dword v218, v[218:219], off offset:2048 nt
	s_nop 0
	global_load_dword v219, v[220:221], off nt
	v_add_co_u32_e32 v220, vcc, s4, v2
	s_mov_b64 s[4:5], 0
	s_nop 0
	v_addc_co_u32_e32 v221, vcc, 0, v3, vcc
	v_add_co_u32_e32 v222, vcc, 0x41000, v2
	global_load_dword v220, v[220:221], off offset:2048 nt
	s_nop 0
	v_addc_co_u32_e32 v223, vcc, 0, v3, vcc
	global_load_dword v221, v[222:223], off nt
	v_add_co_u32_e32 v222, vcc, 0x45000, v2
	s_nop 1
	v_addc_co_u32_e32 v223, vcc, 0, v3, vcc
	global_load_dword v222, v[222:223], off offset:2048 nt
; __device__ __forceinline__ f32x2 un2(unsigned u) { return (f32x2){bf_lo(u), bf_hi(u)}; }
; #define MIX_ISSUED() asm volatile("" ::: "memory")
; template <int NDEAD, int B>
; __device__ __forceinline__ void conv31_load(const bf16_t* __restrict__ Pt, unsigned (&cv)[8]) {
; #pragma unroll
;     for (int q = 0; q < 8; ++q) { const int JJ = 8 * B + q; if (JJ >= NDEAD && JJ < CSTEPS) cv[q] = *(const unsigned*)(Pt + (ptrdiff_t)(JJ - 30) * NCO + OV); }
; }
; template <int NDEAD, int B>
; __device__ __forceinline__ void conv31_comp(const unsigned (&cv)[8], const f32x2 (&wk)[31], f32x2 (&acc)[TT]) {
; #pragma unroll
;     for (int q = 0; q < 8; ++q) { const int JJ = 8 * B + q; if (JJ >= NDEAD && JJ < CSTEPS) { const f32x2 v = un2(cv[q]);
; #pragma unroll
;         for (int i = 0; i < TT; ++i) { const int k = JJ - i; if (k >= 0 && k <= 30) acc[i] += wk[k] * v; } } }
; }
; template <int NDEAD>
; __device__ __forceinline__ void conv31_all(const bf16_t* __restrict__ Pt, const f32x2 (&wk)[31], f32x2 (&acc)[TT]) {
;     static_assert(CSTEPS <= 48, "six batches of eight steps");
;     unsigned cA[8], cB[8];
;     conv31_load<NDEAD, 0>(Pt, cA); conv31_load<NDEAD, 1>(Pt, cB); MIX_ISSUED();
;     conv31_comp<NDEAD, 0>(cA, wk, acc); conv31_load<NDEAD, 2>(Pt, cA); MIX_ISSUED();
;     conv31_comp<NDEAD, 1>(cB, wk, acc); conv31_load<NDEAD, 3>(Pt, cB); MIX_ISSUED();
;     conv31_comp<NDEAD, 2>(cA, wk, acc); conv31_load<NDEAD, 4>(Pt, cA); MIX_ISSUED();
;     conv31_comp<NDEAD, 3>(cB, wk, acc); conv31_load<NDEAD, 5>(Pt, cB); MIX_ISSUED();
;     conv31_comp<NDEAD, 4>(cA, wk, acc);
;     conv31_comp<NDEAD, 5>(cB, wk, acc);
; }
.LBB0_392:
	s_andn2_b64 vcc, exec, s[4:5]
	s_cbranch_vccnz .LBB0_394
	v_add_co_u32_e32 v120, vcc, 0xfffba000, v2
	s_mov_b32 s4, 0xfffe7000
	s_nop 0
	v_addc_co_u32_e32 v121, vcc, -1, v3, vcc
	global_load_dword v122, v[120:121], off nt
	v_add_co_u32_e32 v120, vcc, 0xfffbf000, v2
	s_nop 1
	v_addc_co_u32_e32 v121, vcc, -1, v3, vcc
	global_load_dword v185, v[120:121], off offset:-2048 nt
	v_add_co_u32_e32 v120, vcc, 0xfffc3000, v2
	s_waitcnt vmcnt(0)
	v_lshlrev_b32_e32 v184, 16, v185
	v_addc_co_u32_e32 v121, vcc, -1, v3, vcc
	global_load_dword v209, v[120:121], off nt
	v_add_co_u32_e32 v120, vcc, 0xfffc8000, v2
	v_and_b32_e32 v185, 0xffff0000, v185
	s_nop 0
	v_addc_co_u32_e32 v121, vcc, -1, v3, vcc
	global_load_dword v210, v[120:121], off offset:-2048 nt
	v_add_co_u32_e32 v120, vcc, 0xfffcc000, v2
	s_nop 1
	v_addc_co_u32_e32 v121, vcc, -1, v3, vcc
	global_load_dword v211, v[120:121], off nt
	v_add_co_u32_e32 v120, vcc, 0xfffd1000, v2
	s_nop 1
	v_addc_co_u32_e32 v121, vcc, -1, v3, vcc
	global_load_dword v212, v[120:121], off offset:-2048 nt
	v_add_co_u32_e32 v120, vcc, 0xfffd5000, v2
	s_nop 1
	v_addc_co_u32_e32 v121, vcc, -1, v3, vcc
	global_load_dword v213, v[120:121], off nt
	v_add_co_u32_e32 v120, vcc, 0xfffda000, v2
	s_nop 1
	v_addc_co_u32_e32 v121, vcc, -1, v3, vcc
	global_load_dword v214, v[120:121], off offset:-2048 nt
	v_add_co_u32_e32 v120, vcc, 0xfffde000, v2
	s_nop 1
	v_addc_co_u32_e32 v121, vcc, -1, v3, vcc
	global_load_dword v215, v[120:121], off nt
	v_add_co_u32_e32 v120, vcc, 0xfffe3000, v2
	s_nop 1
	v_addc_co_u32_e32 v121, vcc, -1, v3, vcc
	global_load_dword v216, v[120:121], off offset:-2048 nt
	v_lshlrev_b32_e32 v120, 16, v122
	v_and_b32_e32 v121, 0xffff0000, v122
	v_pk_fma_f32 v[122:123], v[124:125], v[120:121], v[118:119]
	v_pk_fma_f32 v[152:153], v[126:127], v[120:121], v[118:119]
	v_pk_fma_f32 v[154:155], v[128:129], v[120:121], v[118:119]
	v_pk_fma_f32 v[156:157], v[130:131], v[120:121], v[118:119]
	v_pk_fma_f32 v[158:159], v[132:133], v[120:121], v[118:119]
	v_pk_fma_f32 v[160:161], v[134:135], v[120:121], v[118:119]
	v_pk_fma_f32 v[168:169], v[136:137], v[120:121], v[118:119]
	v_pk_fma_f32 v[170:171], v[138:139], v[120:121], v[118:119]
	v_pk_fma_f32 v[172:173], v[140:141], v[120:121], v[118:119]
	v_pk_fma_f32 v[174:175], v[142:143], v[120:121], v[118:119]
	v_pk_fma_f32 v[176:177], v[144:145], v[120:121], v[118:119]
	v_pk_fma_f32 v[178:179], v[146:147], v[120:121], v[118:119]
	v_pk_fma_f32 v[180:181], v[148:149], v[120:121], v[118:119]
	v_pk_fma_f32 v[182:183], v[150:151], v[120:121], v[118:119]
	v_pk_fma_f32 v[120:121], v[186:187], v[120:121], v[118:119]
	v_pk_fma_f32 v[122:123], v[116:117], v[184:185], v[122:123]
	v_pk_fma_f32 v[152:153], v[124:125], v[184:185], v[152:153]
	v_pk_fma_f32 v[154:155], v[126:127], v[184:185], v[154:155]
	v_pk_fma_f32 v[156:157], v[128:129], v[184:185], v[156:157]
	v_pk_fma_f32 v[158:159], v[130:131], v[184:185], v[158:159]
	v_pk_fma_f32 v[160:161], v[132:133], v[184:185], v[160:161]
	v_pk_fma_f32 v[168:169], v[134:135], v[184:185], v[168:169]
	v_pk_fma_f32 v[170:171], v[136:137], v[184:185], v[170:171]
	v_pk_fma_f32 v[172:173], v[138:139], v[184:185], v[172:173]
	v_pk_fma_f32 v[174:175], v[140:141], v[184:185], v[174:175]
	v_pk_fma_f32 v[176:177], v[142:143], v[184:185], v[176:177]
	v_pk_fma_f32 v[178:179], v[144:145], v[184:185], v[178:179]
	v_pk_fma_f32 v[180:181], v[146:147], v[184:185], v[180:181]
	v_pk_fma_f32 v[182:183], v[148:149], v[184:185], v[182:183]
	v_pk_fma_f32 v[120:121], v[150:151], v[184:185], v[120:121]
	v_pk_fma_f32 v[184:185], v[186:187], v[184:185], v[118:119]
	v_add_co_u32_e32 v186, vcc, s4, v2
	s_mov_b32 s4, 0xfffec000
	s_nop 0
	v_addc_co_u32_e32 v187, vcc, -1, v3, vcc
	global_load_dword v217, v[186:187], off nt
	v_add_co_u32_e32 v186, vcc, s4, v2
	s_mov_b32 s4, 0xffff0000
	s_nop 0
	v_addc_co_u32_e32 v187, vcc, -1, v3, vcc
	global_load_dword v218, v[186:187], off offset:-2048 nt
	v_add_co_u32_e32 v186, vcc, s4, v2
	s_mov_b32 s4, 0xffff5000
	s_nop 0
	v_addc_co_u32_e32 v187, vcc, -1, v3, vcc
	global_load_dword v219, v[186:187], off nt
	v_add_co_u32_e32 v186, vcc, s4, v2
	s_movk_i32 s4, 0x9000
	s_nop 0
	v_addc_co_u32_e32 v187, vcc, -1, v3, vcc
	global_load_dword v220, v[186:187], off offset:-2048 nt
	v_add_co_u32_e32 v186, vcc, s4, v2
	s_movk_i32 s4, 0xe000
	s_nop 0
	v_addc_co_u32_e32 v187, vcc, -1, v3, vcc
	global_load_dword v221, v[186:187], off nt
	v_add_co_u32_e32 v186, vcc, s4, v2
	s_movk_i32 s4, 0x2000
	s_nop 0
	v_addc_co_u32_e32 v187, vcc, -1, v3, vcc
	global_load_dword v222, v[186:187], off offset:-2048 nt
	v_add_co_u32_e32 v186, vcc, s4, v2
	s_movk_i32 s4, 0x6000
	s_nop 0
	v_addc_co_u32_e32 v187, vcc, 0, v3, vcc
	global_load_dword v223, v[186:187], off nt
	v_add_co_u32_e32 v186, vcc, s4, v2
	s_mov_b32 s4, 0xb000
	s_nop 0
	v_addc_co_u32_e32 v187, vcc, 0, v3, vcc
	global_load_dword v224, v[186:187], off offset:2048 nt
	s_waitcnt vmcnt(15)
	v_lshlrev_b32_e32 v186, 16, v209
	v_and_b32_e32 v187, 0xffff0000, v209
	v_pk_fma_f32 v[150:151], v[150:151], v[186:187], v[184:185]
	s_waitcnt vmcnt(14)
	v_lshlrev_b32_e32 v184, 16, v210
	v_and_b32_e32 v185, 0xffff0000, v210
	v_pk_fma_f32 v[120:121], v[148:149], v[186:187], v[120:121]
	v_pk_fma_f32 v[148:149], v[148:149], v[184:185], v[150:151]
	s_waitcnt vmcnt(13)
; __device__ __forceinline__ f32x2 un2(unsigned u) { return (f32x2){bf_lo(u), bf_hi(u)}; }
; template <int NDEAD, int B>
; __device__ __forceinline__ void conv31_comp(const unsigned (&cv)[8], const f32x2 (&wk)[31], f32x2 (&acc)[TT]) {
; #pragma unroll
;     for (int q = 0; q < 8; ++q) { const int JJ = 8 * B + q; if (JJ >= NDEAD && JJ < CSTEPS) { const f32x2 v = un2(cv[q]);
; #pragma unroll
;         for (int i = 0; i < TT; ++i) { const int k = JJ - i; if (k >= 0 && k <= 30) acc[i] += wk[k] * v; } } }
; }
	v_lshlrev_b32_e32 v150, 16, v211
	v_and_b32_e32 v151, 0xffff0000, v211
	v_pk_fma_f32 v[152:153], v[116:117], v[186:187], v[152:153]
	v_pk_fma_f32 v[154:155], v[124:125], v[186:187], v[154:155]
	v_pk_fma_f32 v[156:157], v[126:127], v[186:187], v[156:157]
	v_pk_fma_f32 v[158:159], v[128:129], v[186:187], v[158:159]
	v_pk_fma_f32 v[160:161], v[130:131], v[186:187], v[160:161]
	v_pk_fma_f32 v[168:169], v[132:133], v[186:187], v[168:169]
	v_pk_fma_f32 v[170:171], v[134:135], v[186:187], v[170:171]
	v_pk_fma_f32 v[172:173], v[136:137], v[186:187], v[172:173]
	v_pk_fma_f32 v[174:175], v[138:139], v[186:187], v[174:175]
	v_pk_fma_f32 v[176:177], v[140:141], v[186:187], v[176:177]
	v_pk_fma_f32 v[178:179], v[142:143], v[186:187], v[178:179]
	v_pk_fma_f32 v[180:181], v[144:145], v[186:187], v[180:181]
	v_pk_fma_f32 v[182:183], v[146:147], v[186:187], v[182:183]
	v_pk_fma_f32 v[120:121], v[146:147], v[184:185], v[120:121]
	v_pk_fma_f32 v[146:147], v[146:147], v[150:151], v[148:149]
	s_waitcnt vmcnt(12)
	v_lshlrev_b32_e32 v148, 16, v212
	v_and_b32_e32 v149, 0xffff0000, v212
	v_pk_fma_f32 v[122:123], v[114:115], v[186:187], v[122:123]
	v_pk_fma_f32 v[152:153], v[114:115], v[184:185], v[152:153]
	v_pk_fma_f32 v[154:155], v[116:117], v[184:185], v[154:155]
	v_pk_fma_f32 v[156:157], v[124:125], v[184:185], v[156:157]
	v_pk_fma_f32 v[158:159], v[126:127], v[184:185], v[158:159]
	v_pk_fma_f32 v[160:161], v[128:129], v[184:185], v[160:161]
	v_pk_fma_f32 v[168:169], v[130:131], v[184:185], v[168:169]
	v_pk_fma_f32 v[170:171], v[132:133], v[184:185], v[170:171]
	v_pk_fma_f32 v[172:173], v[134:135], v[184:185], v[172:173]
	v_pk_fma_f32 v[174:175], v[136:137], v[184:185], v[174:175]
	v_pk_fma_f32 v[176:177], v[138:139], v[184:185], v[176:177]
	v_pk_fma_f32 v[178:179], v[140:141], v[184:185], v[178:179]
	v_pk_fma_f32 v[180:181], v[142:143], v[184:185], v[180:181]
	v_pk_fma_f32 v[182:183], v[144:145], v[184:185], v[182:183]
	v_pk_fma_f32 v[120:121], v[144:145], v[150:151], v[120:121]
	v_pk_fma_f32 v[144:145], v[144:145], v[148:149], v[146:147]
	s_waitcnt vmcnt(11)
	v_lshlrev_b32_e32 v146, 16, v213
	v_and_b32_e32 v147, 0xffff0000, v213
	v_pk_fma_f32 v[122:123], v[112:113], v[184:185], v[122:123]
	v_pk_fma_f32 v[152:153], v[112:113], v[150:151], v[152:153]
	v_pk_fma_f32 v[154:155], v[114:115], v[150:151], v[154:155]
	v_pk_fma_f32 v[156:157], v[116:117], v[150:151], v[156:157]
	v_pk_fma_f32 v[158:159], v[124:125], v[150:151], v[158:159]
	v_pk_fma_f32 v[160:161], v[126:127], v[150:151], v[160:161]
	v_pk_fma_f32 v[168:169], v[128:129], v[150:151], v[168:169]
	v_pk_fma_f32 v[170:171], v[130:131], v[150:151], v[170:171]
	v_pk_fma_f32 v[172:173], v[132:133], v[150:151], v[172:173]
	v_pk_fma_f32 v[174:175], v[134:135], v[150:151], v[174:175]
	v_pk_fma_f32 v[176:177], v[136:137], v[150:151], v[176:177]
	v_pk_fma_f32 v[178:179], v[138:139], v[150:151], v[178:179]
	v_pk_fma_f32 v[180:181], v[140:141], v[150:151], v[180:181]
	v_pk_fma_f32 v[182:183], v[142:143], v[150:151], v[182:183]
	v_pk_fma_f32 v[120:121], v[142:143], v[148:149], v[120:121]
	v_pk_fma_f32 v[142:143], v[142:143], v[146:147], v[144:145]
	s_waitcnt vmcnt(10)
	v_lshlrev_b32_e32 v144, 16, v214
	v_and_b32_e32 v145, 0xffff0000, v214
	v_pk_fma_f32 v[122:123], v[110:111], v[150:151], v[122:123]
	v_pk_fma_f32 v[150:151], v[110:111], v[148:149], v[152:153]
	v_pk_fma_f32 v[152:153], v[112:113], v[148:149], v[154:155]
	v_pk_fma_f32 v[154:155], v[114:115], v[148:149], v[156:157]
	v_pk_fma_f32 v[156:157], v[116:117], v[148:149], v[158:159]
	v_pk_fma_f32 v[158:159], v[124:125], v[148:149], v[160:161]
	v_pk_fma_f32 v[160:161], v[126:127], v[148:149], v[168:169]
	v_pk_fma_f32 v[168:169], v[128:129], v[148:149], v[170:171]
	v_pk_fma_f32 v[170:171], v[130:131], v[148:149], v[172:173]
	v_pk_fma_f32 v[172:173], v[132:133], v[148:149], v[174:175]
	v_pk_fma_f32 v[174:175], v[134:135], v[148:149], v[176:177]
	v_pk_fma_f32 v[176:177], v[136:137], v[148:149], v[178:179]
	v_pk_fma_f32 v[178:179], v[138:139], v[148:149], v[180:181]
	v_pk_fma_f32 v[180:181], v[140:141], v[148:149], v[182:183]
	v_pk_fma_f32 v[120:121], v[140:141], v[146:147], v[120:121]
	v_pk_fma_f32 v[140:141], v[140:141], v[144:145], v[142:143]
	s_waitcnt vmcnt(9)
	v_lshlrev_b32_e32 v142, 16, v215
	v_and_b32_e32 v143, 0xffff0000, v215
	v_pk_fma_f32 v[122:123], v[108:109], v[148:149], v[122:123]
	v_pk_fma_f32 v[148:149], v[108:109], v[146:147], v[150:151]
	v_pk_fma_f32 v[150:151], v[110:111], v[146:147], v[152:153]
	v_pk_fma_f32 v[152:153], v[112:113], v[146:147], v[154:155]
	v_pk_fma_f32 v[154:155], v[114:115], v[146:147], v[156:157]
	v_pk_fma_f32 v[156:157], v[116:117], v[146:147], v[158:159]
	v_pk_fma_f32 v[158:159], v[124:125], v[146:147], v[160:161]
	v_pk_fma_f32 v[160:161], v[126:127], v[146:147], v[168:169]
	v_pk_fma_f32 v[168:169], v[128:129], v[146:147], v[170:171]
	v_pk_fma_f32 v[170:171], v[130:131], v[146:147], v[172:173]
	v_pk_fma_f32 v[172:173], v[132:133], v[146:147], v[174:175]
	v_pk_fma_f32 v[174:175], v[134:135], v[146:147], v[176:177]
	v_pk_fma_f32 v[176:177], v[136:137], v[146:147], v[178:179]
	v_pk_fma_f32 v[178:179], v[138:139], v[146:147], v[180:181]
	v_pk_fma_f32 v[120:121], v[138:139], v[144:145], v[120:121]
	v_pk_fma_f32 v[138:139], v[138:139], v[142:143], v[140:141]
	s_waitcnt vmcnt(8)
; __device__ __forceinline__ f32x2 un2(unsigned u) { return (f32x2){bf_lo(u), bf_hi(u)}; }
; template <int NDEAD, int B>
; __device__ __forceinline__ void conv31_load(const bf16_t* __restrict__ Pt, unsigned (&cv)[8]) {
; #pragma unroll
;     for (int q = 0; q < 8; ++q) { const int JJ = 8 * B + q; if (JJ >= NDEAD && JJ < CSTEPS) cv[q] = *(const unsigned*)(Pt + (ptrdiff_t)(JJ - 30) * NCO + OV); }
; }
; template <int NDEAD, int B>
; __device__ __forceinline__ void conv31_comp(const unsigned (&cv)[8], const f32x2 (&wk)[31], f32x2 (&acc)[TT]) {
; #pragma unroll
;     for (int q = 0; q < 8; ++q) { const int JJ = 8 * B + q; if (JJ >= NDEAD && JJ < CSTEPS) { const f32x2 v = un2(cv[q]);
; #pragma unroll
;         for (int i = 0; i < TT; ++i) { const int k = JJ - i; if (k >= 0 && k <= 30) acc[i] += wk[k] * v; } } }
; }
	v_lshlrev_b32_e32 v140, 16, v216
	v_and_b32_e32 v141, 0xffff0000, v216
	v_pk_fma_f32 v[122:123], v[106:107], v[146:147], v[122:123]
	v_pk_fma_f32 v[146:147], v[106:107], v[144:145], v[148:149]
	v_pk_fma_f32 v[148:149], v[108:109], v[144:145], v[150:151]
	v_pk_fma_f32 v[150:151], v[110:111], v[144:145], v[152:153]
	v_pk_fma_f32 v[152:153], v[112:113], v[144:145], v[154:155]
	v_pk_fma_f32 v[154:155], v[114:115], v[144:145], v[156:157]
	v_pk_fma_f32 v[156:157], v[116:117], v[144:145], v[158:159]
	v_pk_fma_f32 v[158:159], v[124:125], v[144:145], v[160:161]
	v_pk_fma_f32 v[160:161], v[126:127], v[144:145], v[168:169]
	v_pk_fma_f32 v[168:169], v[128:129], v[144:145], v[170:171]
	v_pk_fma_f32 v[170:171], v[130:131], v[144:145], v[172:173]
	v_pk_fma_f32 v[172:173], v[132:133], v[144:145], v[174:175]
	v_pk_fma_f32 v[174:175], v[134:135], v[144:145], v[176:177]
	v_pk_fma_f32 v[176:177], v[136:137], v[144:145], v[178:179]
	v_pk_fma_f32 v[120:121], v[136:137], v[142:143], v[120:121]
	v_pk_fma_f32 v[136:137], v[136:137], v[140:141], v[138:139]
	v_add_co_u32_e32 v138, vcc, s4, v2
	s_mov_b32 s4, 0xf000
	s_nop 0
	v_addc_co_u32_e32 v139, vcc, 0, v3, vcc
	global_load_dword v211, v[138:139], off nt
	v_add_co_u32_e32 v138, vcc, s4, v2
	s_mov_b32 s4, 0x14000
	s_nop 0
	v_addc_co_u32_e32 v139, vcc, 0, v3, vcc
	global_load_dword v209, v[138:139], off offset:2048 nt
	v_add_co_u32_e32 v138, vcc, s4, v2
	s_mov_b32 s4, 0x18000
	s_nop 0
	v_addc_co_u32_e32 v139, vcc, 0, v3, vcc
	global_load_dword v210, v[138:139], off nt
	v_add_co_u32_e32 v138, vcc, s4, v2
	s_mov_b32 s4, 0x1d000
	s_nop 0
	v_addc_co_u32_e32 v139, vcc, 0, v3, vcc
	global_load_dword v212, v[138:139], off offset:2048 nt
	v_add_co_u32_e32 v138, vcc, s4, v2
	s_mov_b32 s4, 0x21000
	s_nop 0
	v_addc_co_u32_e32 v139, vcc, 0, v3, vcc
	global_load_dword v213, v[138:139], off nt
	v_add_co_u32_e32 v138, vcc, s4, v2
	s_mov_b32 s4, 0x26000
	s_nop 0
	v_addc_co_u32_e32 v139, vcc, 0, v3, vcc
	global_load_dword v214, v[138:139], off offset:2048 nt
	v_add_co_u32_e32 v138, vcc, s4, v2
	s_mov_b32 s4, 0x2a000
	s_nop 0
	v_addc_co_u32_e32 v139, vcc, 0, v3, vcc
	v_pk_fma_f32 v[122:123], v[104:105], v[144:145], v[122:123]
	global_load_dword v215, v[138:139], off nt
	v_add_co_u32_e32 v138, vcc, s4, v2
	v_pk_fma_f32 v[122:123], v[102:103], v[142:143], v[122:123]
	v_pk_fma_f32 v[144:145], v[104:105], v[142:143], v[146:147]
	v_pk_fma_f32 v[146:147], v[106:107], v[142:143], v[148:149]
	v_pk_fma_f32 v[148:149], v[108:109], v[142:143], v[150:151]
	v_pk_fma_f32 v[150:151], v[110:111], v[142:143], v[152:153]
	v_pk_fma_f32 v[152:153], v[112:113], v[142:143], v[154:155]
	v_pk_fma_f32 v[154:155], v[114:115], v[142:143], v[156:157]
	v_pk_fma_f32 v[156:157], v[116:117], v[142:143], v[158:159]
	v_pk_fma_f32 v[158:159], v[124:125], v[142:143], v[160:161]
	v_pk_fma_f32 v[160:161], v[126:127], v[142:143], v[168:169]
	v_pk_fma_f32 v[168:169], v[128:129], v[142:143], v[170:171]
	v_pk_fma_f32 v[170:171], v[130:131], v[142:143], v[172:173]
	v_pk_fma_f32 v[172:173], v[132:133], v[142:143], v[174:175]
	v_pk_fma_f32 v[174:175], v[134:135], v[142:143], v[176:177]
	v_addc_co_u32_e32 v139, vcc, 0, v3, vcc
	v_pk_fma_f32 v[122:123], v[100:101], v[140:141], v[122:123]
	v_pk_fma_f32 v[142:143], v[102:103], v[140:141], v[144:145]
	v_pk_fma_f32 v[144:145], v[104:105], v[140:141], v[146:147]
	v_pk_fma_f32 v[146:147], v[106:107], v[140:141], v[148:149]
	v_pk_fma_f32 v[148:149], v[108:109], v[140:141], v[150:151]
	v_pk_fma_f32 v[150:151], v[110:111], v[140:141], v[152:153]
	v_pk_fma_f32 v[152:153], v[112:113], v[140:141], v[154:155]
	v_pk_fma_f32 v[154:155], v[114:115], v[140:141], v[156:157]
	v_pk_fma_f32 v[156:157], v[116:117], v[140:141], v[158:159]
	v_pk_fma_f32 v[158:159], v[124:125], v[140:141], v[160:161]
	v_pk_fma_f32 v[160:161], v[126:127], v[140:141], v[168:169]
	v_pk_fma_f32 v[168:169], v[128:129], v[140:141], v[170:171]
	v_pk_fma_f32 v[170:171], v[130:131], v[140:141], v[172:173]
	v_pk_fma_f32 v[172:173], v[132:133], v[140:141], v[174:175]
	v_pk_fma_f32 v[120:121], v[134:135], v[140:141], v[120:121]
	global_load_dword v216, v[138:139], off offset:2048 nt
	s_waitcnt vmcnt(15)
	v_lshlrev_b32_e32 v138, 16, v217
	v_and_b32_e32 v139, 0xffff0000, v217
	v_pk_fma_f32 v[122:123], v[98:99], v[138:139], v[122:123]
	v_pk_fma_f32 v[140:141], v[100:101], v[138:139], v[142:143]
	v_pk_fma_f32 v[142:143], v[102:103], v[138:139], v[144:145]
	v_pk_fma_f32 v[144:145], v[104:105], v[138:139], v[146:147]
	v_pk_fma_f32 v[146:147], v[106:107], v[138:139], v[148:149]
	v_pk_fma_f32 v[148:149], v[108:109], v[138:139], v[150:151]
	v_pk_fma_f32 v[150:151], v[110:111], v[138:139], v[152:153]
	v_pk_fma_f32 v[152:153], v[112:113], v[138:139], v[154:155]
	v_pk_fma_f32 v[154:155], v[114:115], v[138:139], v[156:157]
	v_pk_fma_f32 v[156:157], v[116:117], v[138:139], v[158:159]
	v_pk_fma_f32 v[158:159], v[124:125], v[138:139], v[160:161]
	v_pk_fma_f32 v[160:161], v[126:127], v[138:139], v[168:169]
	v_pk_fma_f32 v[168:169], v[128:129], v[138:139], v[170:171]
	v_pk_fma_f32 v[170:171], v[130:131], v[138:139], v[172:173]
	v_pk_fma_f32 v[120:121], v[132:133], v[138:139], v[120:121]
	v_pk_fma_f32 v[134:135], v[134:135], v[138:139], v[136:137]
	s_waitcnt vmcnt(14)
; __device__ __forceinline__ f32x2 un2(unsigned u) { return (f32x2){bf_lo(u), bf_hi(u)}; }
; template <int NDEAD, int B>
; __device__ __forceinline__ void conv31_comp(const unsigned (&cv)[8], const f32x2 (&wk)[31], f32x2 (&acc)[TT]) {
; #pragma unroll
;     for (int q = 0; q < 8; ++q) { const int JJ = 8 * B + q; if (JJ >= NDEAD && JJ < CSTEPS) { const f32x2 v = un2(cv[q]);
; #pragma unroll
;         for (int i = 0; i < TT; ++i) { const int k = JJ - i; if (k >= 0 && k <= 30) acc[i] += wk[k] * v; } } }
; }
	v_lshlrev_b32_e32 v136, 16, v218
	v_and_b32_e32 v137, 0xffff0000, v218
	v_pk_fma_f32 v[122:123], v[96:97], v[136:137], v[122:123]
	v_pk_fma_f32 v[138:139], v[98:99], v[136:137], v[140:141]
	v_pk_fma_f32 v[140:141], v[100:101], v[136:137], v[142:143]
	v_pk_fma_f32 v[142:143], v[102:103], v[136:137], v[144:145]
	v_pk_fma_f32 v[144:145], v[104:105], v[136:137], v[146:147]
	v_pk_fma_f32 v[146:147], v[106:107], v[136:137], v[148:149]
	v_pk_fma_f32 v[148:149], v[108:109], v[136:137], v[150:151]
	v_pk_fma_f32 v[150:151], v[110:111], v[136:137], v[152:153]
	v_pk_fma_f32 v[152:153], v[112:113], v[136:137], v[154:155]
	v_pk_fma_f32 v[154:155], v[114:115], v[136:137], v[156:157]
	v_pk_fma_f32 v[156:157], v[116:117], v[136:137], v[158:159]
	v_pk_fma_f32 v[158:159], v[124:125], v[136:137], v[160:161]
	v_pk_fma_f32 v[160:161], v[126:127], v[136:137], v[168:169]
	v_pk_fma_f32 v[168:169], v[128:129], v[136:137], v[170:171]
	v_pk_fma_f32 v[120:121], v[130:131], v[136:137], v[120:121]
	v_pk_fma_f32 v[132:133], v[132:133], v[136:137], v[134:135]
	s_waitcnt vmcnt(13)
	v_lshlrev_b32_e32 v134, 16, v219
	v_and_b32_e32 v135, 0xffff0000, v219
	v_pk_fma_f32 v[122:123], v[12:13], v[134:135], v[122:123]
	v_pk_fma_f32 v[136:137], v[96:97], v[134:135], v[138:139]
	v_pk_fma_f32 v[138:139], v[98:99], v[134:135], v[140:141]
	v_pk_fma_f32 v[140:141], v[100:101], v[134:135], v[142:143]
	v_pk_fma_f32 v[142:143], v[102:103], v[134:135], v[144:145]
	v_pk_fma_f32 v[144:145], v[104:105], v[134:135], v[146:147]
	v_pk_fma_f32 v[146:147], v[106:107], v[134:135], v[148:149]
	v_pk_fma_f32 v[148:149], v[108:109], v[134:135], v[150:151]
	v_pk_fma_f32 v[150:151], v[110:111], v[134:135], v[152:153]
	v_pk_fma_f32 v[152:153], v[112:113], v[134:135], v[154:155]
	v_pk_fma_f32 v[154:155], v[114:115], v[134:135], v[156:157]
	v_pk_fma_f32 v[156:157], v[116:117], v[134:135], v[158:159]
	v_pk_fma_f32 v[158:159], v[124:125], v[134:135], v[160:161]
	v_pk_fma_f32 v[160:161], v[126:127], v[134:135], v[168:169]
	v_pk_fma_f32 v[120:121], v[128:129], v[134:135], v[120:121]
	v_pk_fma_f32 v[130:131], v[130:131], v[134:135], v[132:133]
	s_waitcnt vmcnt(12)
	v_lshlrev_b32_e32 v132, 16, v220
	v_and_b32_e32 v133, 0xffff0000, v220
	v_pk_fma_f32 v[122:123], v[10:11], v[132:133], v[122:123]
	v_pk_fma_f32 v[134:135], v[12:13], v[132:133], v[136:137]
	v_pk_fma_f32 v[136:137], v[96:97], v[132:133], v[138:139]
	v_pk_fma_f32 v[138:139], v[98:99], v[132:133], v[140:141]
	v_pk_fma_f32 v[140:141], v[100:101], v[132:133], v[142:143]
	v_pk_fma_f32 v[142:143], v[102:103], v[132:133], v[144:145]
	v_pk_fma_f32 v[144:145], v[104:105], v[132:133], v[146:147]
	v_pk_fma_f32 v[146:147], v[106:107], v[132:133], v[148:149]
	v_pk_fma_f32 v[148:149], v[108:109], v[132:133], v[150:151]
	v_pk_fma_f32 v[150:151], v[110:111], v[132:133], v[152:153]
	v_pk_fma_f32 v[152:153], v[112:113], v[132:133], v[154:155]
	v_pk_fma_f32 v[154:155], v[114:115], v[132:133], v[156:157]
	v_pk_fma_f32 v[156:157], v[116:117], v[132:133], v[158:159]
	v_pk_fma_f32 v[158:159], v[124:125], v[132:133], v[160:161]
	v_pk_fma_f32 v[120:121], v[126:127], v[132:133], v[120:121]
	v_pk_fma_f32 v[128:129], v[128:129], v[132:133], v[130:131]
	s_waitcnt vmcnt(11)
	v_lshlrev_b32_e32 v130, 16, v221
	v_and_b32_e32 v131, 0xffff0000, v221
	v_pk_fma_f32 v[122:123], v[8:9], v[130:131], v[122:123]
	v_pk_fma_f32 v[132:133], v[10:11], v[130:131], v[134:135]
	v_pk_fma_f32 v[134:135], v[12:13], v[130:131], v[136:137]
	v_pk_fma_f32 v[136:137], v[96:97], v[130:131], v[138:139]
	v_pk_fma_f32 v[138:139], v[98:99], v[130:131], v[140:141]
	v_pk_fma_f32 v[140:141], v[100:101], v[130:131], v[142:143]
	v_pk_fma_f32 v[142:143], v[102:103], v[130:131], v[144:145]
	v_pk_fma_f32 v[144:145], v[104:105], v[130:131], v[146:147]
	v_pk_fma_f32 v[146:147], v[106:107], v[130:131], v[148:149]
	v_pk_fma_f32 v[148:149], v[108:109], v[130:131], v[150:151]
	v_pk_fma_f32 v[150:151], v[110:111], v[130:131], v[152:153]
	v_pk_fma_f32 v[152:153], v[112:113], v[130:131], v[154:155]
	v_pk_fma_f32 v[154:155], v[114:115], v[130:131], v[156:157]
	v_pk_fma_f32 v[156:157], v[116:117], v[130:131], v[158:159]
	v_pk_fma_f32 v[120:121], v[124:125], v[130:131], v[120:121]
	v_pk_fma_f32 v[126:127], v[126:127], v[130:131], v[128:129]
	s_waitcnt vmcnt(10)
; __device__ __forceinline__ f32x2 un2(unsigned u) { return (f32x2){bf_lo(u), bf_hi(u)}; }
; template <int NDEAD, int B>
; __device__ __forceinline__ void conv31_load(const bf16_t* __restrict__ Pt, unsigned (&cv)[8]) {
; #pragma unroll
;     for (int q = 0; q < 8; ++q) { const int JJ = 8 * B + q; if (JJ >= NDEAD && JJ < CSTEPS) cv[q] = *(const unsigned*)(Pt + (ptrdiff_t)(JJ - 30) * NCO + OV); }
; }
; template <int NDEAD, int B>
; __device__ __forceinline__ void conv31_comp(const unsigned (&cv)[8], const f32x2 (&wk)[31], f32x2 (&acc)[TT]) {
; #pragma unroll
;     for (int q = 0; q < 8; ++q) { const int JJ = 8 * B + q; if (JJ >= NDEAD && JJ < CSTEPS) { const f32x2 v = un2(cv[q]);
; #pragma unroll
;         for (int i = 0; i < TT; ++i) { const int k = JJ - i; if (k >= 0 && k <= 30) acc[i] += wk[k] * v; } } }
; }
	v_lshlrev_b32_e32 v128, 16, v222
	v_and_b32_e32 v129, 0xffff0000, v222
	v_pk_fma_f32 v[122:123], v[6:7], v[128:129], v[122:123]
	v_pk_fma_f32 v[130:131], v[8:9], v[128:129], v[132:133]
	v_pk_fma_f32 v[132:133], v[10:11], v[128:129], v[134:135]
	v_pk_fma_f32 v[134:135], v[12:13], v[128:129], v[136:137]
	v_pk_fma_f32 v[136:137], v[96:97], v[128:129], v[138:139]
	v_pk_fma_f32 v[138:139], v[98:99], v[128:129], v[140:141]
	v_pk_fma_f32 v[140:141], v[100:101], v[128:129], v[142:143]
	v_pk_fma_f32 v[142:143], v[102:103], v[128:129], v[144:145]
	v_pk_fma_f32 v[144:145], v[104:105], v[128:129], v[146:147]
	v_pk_fma_f32 v[146:147], v[106:107], v[128:129], v[148:149]
	v_pk_fma_f32 v[148:149], v[108:109], v[128:129], v[150:151]
	v_pk_fma_f32 v[150:151], v[110:111], v[128:129], v[152:153]
	v_pk_fma_f32 v[152:153], v[112:113], v[128:129], v[154:155]
	v_pk_fma_f32 v[154:155], v[114:115], v[128:129], v[156:157]
	v_pk_fma_f32 v[120:121], v[116:117], v[128:129], v[120:121]
	v_pk_fma_f32 v[124:125], v[124:125], v[128:129], v[126:127]
	s_waitcnt vmcnt(9)
	v_lshlrev_b32_e32 v126, 16, v223
	v_and_b32_e32 v127, 0xffff0000, v223
	v_pk_fma_f32 v[122:123], v[4:5], v[126:127], v[122:123]
	v_pk_fma_f32 v[128:129], v[6:7], v[126:127], v[130:131]
	v_pk_fma_f32 v[130:131], v[8:9], v[126:127], v[132:133]
	v_pk_fma_f32 v[132:133], v[10:11], v[126:127], v[134:135]
	v_pk_fma_f32 v[134:135], v[12:13], v[126:127], v[136:137]
	v_pk_fma_f32 v[136:137], v[96:97], v[126:127], v[138:139]
	v_pk_fma_f32 v[138:139], v[98:99], v[126:127], v[140:141]
	v_pk_fma_f32 v[140:141], v[100:101], v[126:127], v[142:143]
	v_pk_fma_f32 v[142:143], v[102:103], v[126:127], v[144:145]
	v_pk_fma_f32 v[144:145], v[104:105], v[126:127], v[146:147]
	v_pk_fma_f32 v[146:147], v[106:107], v[126:127], v[148:149]
	v_pk_fma_f32 v[148:149], v[108:109], v[126:127], v[150:151]
	v_pk_fma_f32 v[150:151], v[110:111], v[126:127], v[152:153]
	v_pk_fma_f32 v[180:181], v[112:113], v[126:127], v[154:155]
	v_pk_fma_f32 v[182:183], v[114:115], v[126:127], v[120:121]
	v_pk_fma_f32 v[124:125], v[116:117], v[126:127], v[124:125]
	s_waitcnt vmcnt(8)
	v_lshlrev_b32_e32 v126, 16, v224
	v_and_b32_e32 v127, 0xffff0000, v224
	s_mov_b32 s4, 0x2f000
	v_pk_fma_f32 v[184:185], v[114:115], v[126:127], v[124:125]
	v_add_co_u32_e32 v124, vcc, s4, v2
	s_mov_b32 s4, 0x33000
	s_nop 0
	v_addc_co_u32_e32 v125, vcc, 0, v3, vcc
	global_load_dword v217, v[124:125], off nt
	v_add_co_u32_e32 v124, vcc, s4, v2
	s_mov_b32 s4, 0x38000
	s_nop 0
	v_addc_co_u32_e32 v125, vcc, 0, v3, vcc
	global_load_dword v218, v[124:125], off offset:2048 nt
	v_add_co_u32_e32 v124, vcc, s4, v2
	s_mov_b32 s4, 0x3c000
	s_nop 0
	v_addc_co_u32_e32 v125, vcc, 0, v3, vcc
	global_load_dword v219, v[124:125], off nt
	v_add_co_u32_e32 v124, vcc, s4, v2
	v_pk_fma_f32 v[120:121], v[4:5], v[126:127], v[128:129]
	s_nop 0
	v_addc_co_u32_e32 v125, vcc, 0, v3, vcc
	global_load_dword v220, v[124:125], off offset:2048 nt
	v_add_co_u32_e32 v124, vcc, 0x41000, v2
	v_pk_fma_f32 v[152:153], v[6:7], v[126:127], v[130:131]
	s_nop 0
	v_addc_co_u32_e32 v125, vcc, 0, v3, vcc
	global_load_dword v221, v[124:125], off nt
	v_add_co_u32_e32 v124, vcc, 0x45000, v2
	v_pk_fma_f32 v[154:155], v[8:9], v[126:127], v[132:133]
	s_nop 0
	v_addc_co_u32_e32 v125, vcc, 0, v3, vcc
	global_load_dword v222, v[124:125], off offset:2048 nt
	v_pk_fma_f32 v[156:157], v[10:11], v[126:127], v[134:135]
	v_pk_fma_f32 v[158:159], v[12:13], v[126:127], v[136:137]
	v_pk_fma_f32 v[160:161], v[96:97], v[126:127], v[138:139]
	v_pk_fma_f32 v[168:169], v[98:99], v[126:127], v[140:141]
	v_pk_fma_f32 v[170:171], v[100:101], v[126:127], v[142:143]
	v_pk_fma_f32 v[172:173], v[102:103], v[126:127], v[144:145]
	v_pk_fma_f32 v[174:175], v[104:105], v[126:127], v[146:147]
	v_pk_fma_f32 v[176:177], v[106:107], v[126:127], v[148:149]
	v_pk_fma_f32 v[178:179], v[108:109], v[126:127], v[150:151]
	v_pk_fma_f32 v[180:181], v[110:111], v[126:127], v[180:181]
	v_pk_fma_f32 v[182:183], v[112:113], v[126:127], v[182:183]

; __device__ __forceinline__ f32x2 un2(unsigned u) { return (f32x2){bf_lo(u), bf_hi(u)}; }
; #define MIX_ISSUED() asm volatile("" ::: "memory")
; template <int NDEAD, int B>
; __device__ __forceinline__ void conv31_load(const bf16_t* __restrict__ Pt, unsigned (&cv)[8]) {
; #pragma unroll
;     for (int q = 0; q < 8; ++q) { const int JJ = 8 * B + q; if (JJ >= NDEAD && JJ < CSTEPS) cv[q] = *(const unsigned*)(Pt + (ptrdiff_t)(JJ - 30) * NCO + OV); }
; }
; template <int NDEAD, int B>
; __device__ __forceinline__ void conv31_comp(const unsigned (&cv)[8], const f32x2 (&wk)[31], f32x2 (&acc)[TT]) {
; #pragma unroll
;     for (int q = 0; q < 8; ++q) { const int JJ = 8 * B + q; if (JJ >= NDEAD && JJ < CSTEPS) { const f32x2 v = un2(cv[q]);
; #pragma unroll
;         for (int i = 0; i < TT; ++i) { const int k = JJ - i; if (k >= 0 && k <= 30) acc[i] += wk[k] * v; } } }
; }
; template <int NDEAD>
; __device__ __forceinline__ void conv31_all(const bf16_t* __restrict__ Pt, const f32x2 (&wk)[31], f32x2 (&acc)[TT]) {
;     static_assert(CSTEPS <= 48, "six batches of eight steps");
;     unsigned cA[8], cB[8];
;     conv31_load<NDEAD, 0>(Pt, cA); conv31_load<NDEAD, 1>(Pt, cB); MIX_ISSUED();
;     conv31_comp<NDEAD, 0>(cA, wk, acc); conv31_load<NDEAD, 2>(Pt, cA); MIX_ISSUED();
;     conv31_comp<NDEAD, 1>(cB, wk, acc); conv31_load<NDEAD, 3>(Pt, cB); MIX_ISSUED();
;     conv31_comp<NDEAD, 2>(cA, wk, acc); conv31_load<NDEAD, 4>(Pt, cA); MIX_ISSUED();
;     conv31_comp<NDEAD, 3>(cB, wk, acc); conv31_load<NDEAD, 5>(Pt, cB); MIX_ISSUED();
;     conv31_comp<NDEAD, 4>(cA, wk, acc);
;     conv31_comp<NDEAD, 5>(cB, wk, acc);
; }
.LBB0_395:
	s_andn2_b64 vcc, exec, s[4:5]
	s_cbranch_vccnz .LBB0_397
	v_add_co_u32_e32 v120, vcc, 0x2000, v2
	s_mov_b32 s4, 0x14000
	s_nop 0
	v_addc_co_u32_e32 v121, vcc, 0, v3, vcc
	global_load_dword v122, v[120:121], off nt
	v_add_co_u32_e32 v120, vcc, 0x6000, v2
	s_nop 1
	v_addc_co_u32_e32 v121, vcc, 0, v3, vcc
	global_load_dword v152, v[120:121], off offset:2048 nt
	v_add_co_u32_e32 v120, vcc, 0xb000, v2
	s_nop 1
	v_addc_co_u32_e32 v121, vcc, 0, v3, vcc
	global_load_dword v211, v[120:121], off nt
	v_add_co_u32_e32 v120, vcc, 0xf000, v2
	s_nop 1
	v_addc_co_u32_e32 v121, vcc, 0, v3, vcc
	global_load_dword v209, v[120:121], off offset:2048 nt
	v_add_co_u32_e32 v120, vcc, s4, v2
	s_mov_b32 s4, 0x18000
	s_nop 0
	v_addc_co_u32_e32 v121, vcc, 0, v3, vcc
	global_load_dword v210, v[120:121], off nt
	v_add_co_u32_e32 v120, vcc, s4, v2
	s_mov_b32 s4, 0x2f000
	s_nop 0
	v_addc_co_u32_e32 v121, vcc, 0, v3, vcc
	global_load_dword v212, v[120:121], off offset:2048 nt
	v_add_co_u32_e32 v120, vcc, 0x1d000, v2
	s_nop 1
	v_addc_co_u32_e32 v121, vcc, 0, v3, vcc
	global_load_dword v213, v[120:121], off nt
	v_add_co_u32_e32 v120, vcc, 0x21000, v2
	s_nop 1
	v_addc_co_u32_e32 v121, vcc, 0, v3, vcc
	global_load_dword v214, v[120:121], off offset:2048 nt
	v_add_co_u32_e32 v120, vcc, 0x26000, v2
	s_nop 1
	v_addc_co_u32_e32 v121, vcc, 0, v3, vcc
	global_load_dword v215, v[120:121], off nt
	v_add_co_u32_e32 v120, vcc, 0x2a000, v2
	s_nop 1
	v_addc_co_u32_e32 v121, vcc, 0, v3, vcc
	global_load_dword v216, v[120:121], off offset:2048 nt
	s_waitcnt vmcnt(9)
	v_lshlrev_b32_e32 v120, 16, v122
	v_and_b32_e32 v121, 0xffff0000, v122
	v_pk_fma_f32 v[122:123], v[4:5], v[120:121], v[118:119]
	v_pk_fma_f32 v[124:125], v[6:7], v[120:121], v[118:119]
	v_pk_fma_f32 v[126:127], v[8:9], v[120:121], v[118:119]
	v_pk_fma_f32 v[128:129], v[10:11], v[120:121], v[118:119]
	v_pk_fma_f32 v[130:131], v[12:13], v[120:121], v[118:119]
	v_pk_fma_f32 v[132:133], v[96:97], v[120:121], v[118:119]
	v_pk_fma_f32 v[134:135], v[98:99], v[120:121], v[118:119]
	v_pk_fma_f32 v[136:137], v[100:101], v[120:121], v[118:119]
	v_pk_fma_f32 v[138:139], v[102:103], v[120:121], v[118:119]
	v_pk_fma_f32 v[140:141], v[104:105], v[120:121], v[118:119]
	v_pk_fma_f32 v[142:143], v[106:107], v[120:121], v[118:119]
	v_pk_fma_f32 v[144:145], v[108:109], v[120:121], v[118:119]
	v_pk_fma_f32 v[146:147], v[110:111], v[120:121], v[118:119]
	v_pk_fma_f32 v[148:149], v[112:113], v[120:121], v[118:119]
	v_pk_fma_f32 v[150:151], v[114:115], v[120:121], v[118:119]
	v_pk_fma_f32 v[116:117], v[116:117], v[120:121], v[118:119]
	s_waitcnt vmcnt(8)
	v_lshlrev_b32_e32 v118, 16, v152
	v_and_b32_e32 v119, 0xffff0000, v152
	v_pk_fma_f32 v[184:185], v[114:115], v[118:119], v[116:117]
	v_add_co_u32_e32 v114, vcc, s4, v2
	s_mov_b32 s4, 0x33000
	s_nop 0
	v_addc_co_u32_e32 v115, vcc, 0, v3, vcc
	global_load_dword v217, v[114:115], off nt
	v_add_co_u32_e32 v114, vcc, s4, v2
	s_mov_b32 s4, 0x38000
	s_nop 0
	v_addc_co_u32_e32 v115, vcc, 0, v3, vcc
	global_load_dword v218, v[114:115], off offset:2048 nt
	v_add_co_u32_e32 v114, vcc, s4, v2
	s_mov_b32 s4, 0x3c000
	s_nop 0
	v_addc_co_u32_e32 v115, vcc, 0, v3, vcc
	global_load_dword v219, v[114:115], off nt
	v_add_co_u32_e32 v114, vcc, s4, v2
	v_pk_fma_f32 v[120:121], v[4:5], v[118:119], v[124:125]
	s_nop 0
	v_addc_co_u32_e32 v115, vcc, 0, v3, vcc
	global_load_dword v220, v[114:115], off offset:2048 nt
	v_add_co_u32_e32 v114, vcc, 0x41000, v2
	v_pk_fma_f32 v[152:153], v[6:7], v[118:119], v[126:127]
	s_nop 0
	v_addc_co_u32_e32 v115, vcc, 0, v3, vcc
	global_load_dword v221, v[114:115], off nt
	v_add_co_u32_e32 v114, vcc, 0x45000, v2
	v_pk_fma_f32 v[154:155], v[8:9], v[118:119], v[128:129]
	s_nop 0
	v_addc_co_u32_e32 v115, vcc, 0, v3, vcc
	global_load_dword v222, v[114:115], off offset:2048 nt
	v_pk_fma_f32 v[156:157], v[10:11], v[118:119], v[130:131]
	v_pk_fma_f32 v[158:159], v[12:13], v[118:119], v[132:133]
	v_pk_fma_f32 v[160:161], v[96:97], v[118:119], v[134:135]
	v_pk_fma_f32 v[168:169], v[98:99], v[118:119], v[136:137]
	v_pk_fma_f32 v[170:171], v[100:101], v[118:119], v[138:139]
	v_pk_fma_f32 v[172:173], v[102:103], v[118:119], v[140:141]
	v_pk_fma_f32 v[174:175], v[104:105], v[118:119], v[142:143]
	v_pk_fma_f32 v[176:177], v[106:107], v[118:119], v[144:145]
	v_pk_fma_f32 v[178:179], v[108:109], v[118:119], v[146:147]
	v_pk_fma_f32 v[180:181], v[110:111], v[118:119], v[148:149]
	v_pk_fma_f32 v[182:183], v[112:113], v[118:119], v[150:151]

; __device__ __forceinline__ f32x2 un2(unsigned u) { return (f32x2){bf_lo(u), bf_hi(u)}; }
; __device__ __forceinline__ void st2(bf16_t* p, f32x2 v) { *(unsigned*)p = cvt_pk_bf16(v.x, v.y); }
; template <int W>
; __device__ __forceinline__ void pool_branch(const bf16_t* __restrict__ Pb, bf16_t* __restrict__ out, bool first) {
;     unsigned raw[W - 1 + TT];
; #pragma unroll
;     for (int j = 0; j < W - 1 + TT; ++j) { const int off = j - (W - 1); const int offc = (off < 0 && first) ? 0 : off;
;         unsigned r = *(const unsigned*)(Pb + (ptrdiff_t)offc * NCO); if (off < 0 && first) r = 0u; raw[j] = r; }
;     asm volatile("" ::: "memory");
;     f32x2 S = (f32x2){0.f, 0.f};
; #pragma unroll
;     for (int j = 0; j < W - 1; ++j) S += un2(raw[j]);
; #pragma unroll
;     for (int i = 0; i < TT; ++i) {
;         const f32x2 ui = un2(raw[i + W - 1]);
;         S += ui;
;         const float inv = (first && (i + 1 < W)) ? 1.0f / (float)(i + 1) : 1.0f / (float)W;
;         st2(out + (size_t)i * EW, S * inv - ui);
;         S -= un2(raw[i]);
;     }
.LBB0_401:
	s_cmp_eq_u32 s8, 2
	s_mov_b64 s[4:5], -1
	s_cbranch_scc0 .LBB0_403
	s_and_b64 s[4:5], exec, s[54:55]
	s_cselect_b32 s5, 0, -1
	s_cselect_b32 s4, 0, 0xfffe0800
	s_cselect_b32 s6, 0, 0xfffe9800
	s_mov_b32 s7, s5
	v_lshl_add_u64 v[104:105], v[6:7], 0, s[4:5]
	s_cselect_b32 s4, 0, 0xffff2800
	v_lshl_add_u64 v[108:109], v[6:7], 0, s[6:7]
	s_cselect_b32 s6, 0, 0xfffee000
	v_lshl_add_u64 v[106:107], s[4:5], 1, v[6:7]
	v_lshl_add_u64 v[110:111], v[6:7], 0, s[6:7]
	v_lshl_add_u64 v[112:113], v[6:7], 0, s[4:5]
	global_load_dword v118, v[104:105], off nt
	global_load_dword v119, v[106:107], off nt
	global_load_dword v120, v[108:109], off nt
	global_load_dword v121, v[110:111], off nt
	global_load_dword v122, v[112:113], off nt
	s_cselect_b32 s4, 0, 0xffffb800
	v_lshl_add_u64 v[104:105], s[4:5], 1, v[6:7]
	v_lshl_add_u64 v[106:107], v[6:7], 0, s[4:5]
	global_load_dword v123, v[104:105], off nt
	s_nop 0
	global_load_dword v107, v[106:107], off nt
	s_nop 0
	global_load_dword v124, v[6:7], off nt
	s_movk_i32 s5, 0x5000
	v_add_co_u32_e32 v104, vcc, s5, v2
	s_mov_b32 s4, 0xa000
	s_nop 0
	v_addc_co_u32_e32 v105, vcc, 0, v3, vcc
	global_load_dword v126, v[104:105], off offset:2048 nt
	v_add_co_u32_e32 v104, vcc, s4, v2
	s_mov_b32 s4, 0x13000
	s_nop 0
	v_addc_co_u32_e32 v105, vcc, 0, v3, vcc
	global_load_dword v128, v[8:9], off offset:2048 nt
	global_load_dword v127, v[104:105], off nt
	v_add_co_u32_e32 v104, vcc, s4, v2
	s_mov_b32 s4, 0x1c000
	s_nop 0
	v_addc_co_u32_e32 v105, vcc, 0, v3, vcc
	v_add_co_u32_e32 v108, vcc, s4, v2
	s_mov_b32 s4, 0x25000
	s_nop 0
	v_addc_co_u32_e32 v109, vcc, 0, v3, vcc
	v_add_co_u32_e32 v110, vcc, s4, v2
	s_mov_b32 s4, 0x2e000
	s_nop 0
	v_addc_co_u32_e32 v111, vcc, 0, v3, vcc
	v_add_co_u32_e32 v112, vcc, s4, v2
	s_mov_b32 s4, 0x37000
	s_nop 0
	v_addc_co_u32_e32 v113, vcc, 0, v3, vcc
	v_add_co_u32_e32 v114, vcc, s4, v2
	s_mov_b32 s4, 0x40000
	s_nop 0
	v_addc_co_u32_e32 v115, vcc, 0, v3, vcc
	v_add_co_u32_e32 v116, vcc, s4, v2
	s_movk_i32 s4, 0x2000
	s_nop 0
	v_addc_co_u32_e32 v117, vcc, 0, v3, vcc
	global_load_dword v130, v[104:105], off nt
	global_load_dword v131, v[12:13], off offset:2048 nt
	global_load_dword v132, v[10:11], off offset:2048 nt
	global_load_dword v133, v[96:97], off offset:2048 nt
	global_load_dword v134, v[98:99], off offset:2048 nt
	global_load_dword v135, v[100:101], off offset:2048 nt
	global_load_dword v106, v[102:103], off offset:2048 nt
	global_load_dword v136, v[108:109], off nt
	global_load_dword v137, v[110:111], off nt
	global_load_dword v138, v[112:113], off nt
	global_load_dword v139, v[114:115], off nt
	global_load_dword v140, v[116:117], off nt
	s_mov_b32 s6, 0x3e000000
	s_waitcnt vmcnt(22)
	v_cndmask_b32_e64 v105, v118, 0, s[54:55]
	s_waitcnt vmcnt(21)
	v_cndmask_b32_e64 v111, v119, 0, s[54:55]
	v_lshlrev_b32_e32 v104, 16, v105
	v_and_b32_e32 v105, 0xffff0000, v105
	s_waitcnt vmcnt(20)
	v_cndmask_b32_e64 v113, v120, 0, s[54:55]
	v_pk_add_f32 v[108:109], v[104:105], 0 op_sel_hi:[1,0]
	v_lshlrev_b32_e32 v110, 16, v111
	v_and_b32_e32 v111, 0xffff0000, v111
	s_waitcnt vmcnt(19)
	v_cndmask_b32_e64 v115, v121, 0, s[54:55]
	v_lshlrev_b32_e32 v112, 16, v113
	v_and_b32_e32 v113, 0xffff0000, v113
	v_pk_add_f32 v[108:109], v[108:109], v[110:111]
	s_waitcnt vmcnt(18)
	v_cndmask_b32_e64 v117, v122, 0, s[54:55]
	v_pk_add_f32 v[108:109], v[108:109], v[112:113]
	v_lshlrev_b32_e32 v114, 16, v115
	v_and_b32_e32 v115, 0xffff0000, v115
	s_waitcnt vmcnt(17)
	v_cndmask_b32_e64 v119, v123, 0, s[54:55]
	v_pk_add_f32 v[108:109], v[108:109], v[114:115]
	v_lshlrev_b32_e32 v116, 16, v117
	v_and_b32_e32 v117, 0xffff0000, v117
	s_waitcnt vmcnt(16)
	v_cndmask_b32_e64 v107, v107, 0, s[54:55]
	v_pk_add_f32 v[108:109], v[108:109], v[116:117]
	v_lshlrev_b32_e32 v118, 16, v119
	v_and_b32_e32 v119, 0xffff0000, v119
	v_pk_add_f32 v[108:109], v[108:109], v[118:119]
	v_lshlrev_b32_e32 v120, 16, v107
	v_and_b32_e32 v121, 0xffff0000, v107
	v_pk_add_f32 v[108:109], v[108:109], v[120:121]
	s_waitcnt vmcnt(15)
	v_lshlrev_b32_e32 v122, 16, v124
	v_and_b32_e32 v123, 0xffff0000, v124
	v_pk_add_f32 v[108:109], v[108:109], v[122:123]
	v_cndmask_b32_e64 v124, v194, 1.0, s[54:55]
	v_pk_fma_f32 v[124:125], v[124:125], v[108:109], v[122:123] op_sel_hi:[0,1,1] neg_lo:[0,0,1] neg_hi:[0,0,1]
	v_pk_add_f32 v[104:105], v[108:109], v[104:105] neg_lo:[0,1] neg_hi:[0,1]
	s_waitcnt vmcnt(14)
	v_lshlrev_b32_e32 v108, 16, v126
	v_and_b32_e32 v109, 0xffff0000, v126
	v_cvt_pk_bf16_f32 v107, v124, v125
	v_pk_add_f32 v[104:105], v[104:105], v[108:109]
	v_cndmask_b32_e64 v124, v194, 0.5, s[54:55]
	v_pk_fma_f32 v[124:125], v[124:125], v[104:105], v[108:109] op_sel_hi:[0,1,1] neg_lo:[0,0,1] neg_hi:[0,0,1]
	v_pk_add_f32 v[104:105], v[104:105], v[110:111] neg_lo:[0,1] neg_hi:[0,1]
	s_waitcnt vmcnt(12)
	v_lshlrev_b32_e32 v110, 16, v127
	v_and_b32_e32 v111, 0xffff0000, v127
	global_store_dword v[4:5], v107, off
	v_cvt_pk_bf16_f32 v107, v124, v125
	v_pk_add_f32 v[104:105], v[104:105], v[110:111]
	v_cndmask_b32_e64 v124, v194, v195, s[54:55]
	v_pk_fma_f32 v[124:125], v[124:125], v[104:105], v[110:111] op_sel_hi:[0,1,1] neg_lo:[0,0,1] neg_hi:[0,0,1]
	global_store_dword v[4:5], v107, off offset:2048
	v_cvt_pk_bf16_f32 v107, v124, v125
	v_add_co_u32_e32 v124, vcc, s14, v4
	v_pk_add_f32 v[104:105], v[104:105], v[112:113] neg_lo:[0,1] neg_hi:[0,1]
	s_nop 0
	v_addc_co_u32_e32 v125, vcc, 0, v5, vcc
	v_lshlrev_b32_e32 v112, 16, v128
	v_and_b32_e32 v113, 0xffff0000, v128
	v_add_co_u32_e32 v126, vcc, s4, v4
	v_pk_add_f32 v[104:105], v[104:105], v[112:113]
	v_cndmask_b32_e64 v128, v194, v196, s[54:55]
	v_addc_co_u32_e32 v127, vcc, 0, v5, vcc
	v_pk_fma_f32 v[128:129], v[128:129], v[104:105], v[112:113] op_sel_hi:[0,1,1] neg_lo:[0,0,1] neg_hi:[0,0,1]
	global_store_dword v[126:127], v107, off offset:-4096
	v_cvt_pk_bf16_f32 v107, v128, v129
	v_pk_add_f32 v[104:105], v[104:105], v[114:115] neg_lo:[0,1] neg_hi:[0,1]
	s_waitcnt vmcnt(14)
; __device__ __forceinline__ f32x2 un2(unsigned u) { return (f32x2){bf_lo(u), bf_hi(u)}; }
; __device__ __forceinline__ void st2(bf16_t* p, f32x2 v) { *(unsigned*)p = cvt_pk_bf16(v.x, v.y); }
; template <int W>
; __device__ __forceinline__ void pool_branch(const bf16_t* __restrict__ Pb, bf16_t* __restrict__ out, bool first) {
;     ...
;     f32x2 S = (f32x2){0.f, 0.f};
; #pragma unroll
;     for (int j = 0; j < W - 1; ++j) S += un2(raw[j]);
; #pragma unroll
;     for (int i = 0; i < TT; ++i) {
;         const f32x2 ui = un2(raw[i + W - 1]);
;         S += ui;
;         const float inv = (first && (i + 1 < W)) ? 1.0f / (float)(i + 1) : 1.0f / (float)W;
;         st2(out + (size_t)i * EW, S * inv - ui);
;         S -= un2(raw[i]);
;     }
	v_lshlrev_b32_e32 v114, 16, v130
	v_and_b32_e32 v115, 0xffff0000, v130
	global_store_dword v[124:125], v107, off offset:2048
	v_pk_add_f32 v[104:105], v[104:105], v[114:115]
	v_cndmask_b32_e64 v124, v194, v197, s[54:55]
	v_pk_fma_f32 v[124:125], v[124:125], v[104:105], v[114:115] op_sel_hi:[0,1,1] neg_lo:[0,0,1] neg_hi:[0,0,1]
	v_pk_add_f32 v[104:105], v[104:105], v[116:117] neg_lo:[0,1] neg_hi:[0,1]
	s_waitcnt vmcnt(14)
	v_lshlrev_b32_e32 v116, 16, v131
	v_and_b32_e32 v117, 0xffff0000, v131
	v_cvt_pk_bf16_f32 v107, v124, v125
	v_pk_add_f32 v[104:105], v[104:105], v[116:117]
	v_cndmask_b32_e64 v124, v194, v198, s[54:55]
	v_pk_fma_f32 v[124:125], v[124:125], v[104:105], v[116:117] op_sel_hi:[0,1,1] neg_lo:[0,0,1] neg_hi:[0,0,1]
	v_pk_add_f32 v[104:105], v[104:105], v[118:119] neg_lo:[0,1] neg_hi:[0,1]
	s_waitcnt vmcnt(8)
	v_lshlrev_b32_e32 v118, 16, v136
	v_and_b32_e32 v119, 0xffff0000, v136
	global_store_dword v[126:127], v107, off
	v_cvt_pk_bf16_f32 v107, v124, v125
	v_pk_add_f32 v[104:105], v[104:105], v[118:119]
	v_cndmask_b32_e64 v124, v194, v199, s[54:55]
	v_pk_fma_f32 v[124:125], v[124:125], v[104:105], v[118:119] op_sel_hi:[0,1,1] neg_lo:[0,0,1] neg_hi:[0,0,1]
	global_store_dword v[126:127], v107, off offset:2048
	v_cvt_pk_bf16_f32 v107, v124, v125
	v_add_co_u32_e32 v124, vcc, s12, v4
	s_movk_i32 s4, 0x4000
	s_nop 0
	v_addc_co_u32_e32 v125, vcc, 0, v5, vcc
	v_lshlrev_b32_e32 v128, 16, v132
	v_and_b32_e32 v129, 0xffff0000, v132
	v_pk_add_f32 v[104:105], v[104:105], v[120:121] neg_lo:[0,1] neg_hi:[0,1]
	v_add_co_u32_e32 v126, vcc, s4, v4
	v_pk_add_f32 v[104:105], v[104:105], v[128:129]
	s_nop 0
	v_addc_co_u32_e32 v127, vcc, 0, v5, vcc
	v_pk_fma_f32 v[120:121], v[104:105], s[6:7], v[128:129] op_sel_hi:[1,0,1] neg_lo:[0,0,1] neg_hi:[0,0,1]
	global_store_dword v[126:127], v107, off offset:-4096
	v_cvt_pk_bf16_f32 v107, v120, v121
	v_pk_add_f32 v[104:105], v[104:105], v[122:123] neg_lo:[0,1] neg_hi:[0,1]
	s_waitcnt vmcnt(10)
	v_lshlrev_b32_e32 v120, 16, v137
	v_and_b32_e32 v121, 0xffff0000, v137
	v_pk_add_f32 v[104:105], v[104:105], v[120:121]
	global_store_dword v[124:125], v107, off offset:2048
	v_pk_fma_f32 v[120:121], v[104:105], s[6:7], v[120:121] op_sel_hi:[1,0,1] neg_lo:[0,0,1] neg_hi:[0,0,1]
	v_pk_add_f32 v[104:105], v[104:105], v[108:109] neg_lo:[0,1] neg_hi:[0,1]
	v_lshlrev_b32_e32 v108, 16, v133
	v_and_b32_e32 v109, 0xffff0000, v133
	v_pk_add_f32 v[104:105], v[104:105], v[108:109]
	v_cvt_pk_bf16_f32 v107, v120, v121
	v_pk_fma_f32 v[108:109], v[104:105], s[6:7], v[108:109] op_sel_hi:[1,0,1] neg_lo:[0,0,1] neg_hi:[0,0,1]
	global_store_dword v[126:127], v107, off
	v_cvt_pk_bf16_f32 v107, v108, v109
	v_pk_add_f32 v[104:105], v[104:105], v[110:111] neg_lo:[0,1] neg_hi:[0,1]
	s_waitcnt vmcnt(11)
	v_lshlrev_b32_e32 v108, 16, v138
	v_and_b32_e32 v109, 0xffff0000, v138
	v_pk_add_f32 v[104:105], v[104:105], v[108:109]
	global_store_dword v[126:127], v107, off offset:2048
	v_pk_fma_f32 v[108:109], v[104:105], s[6:7], v[108:109] op_sel_hi:[1,0,1] neg_lo:[0,0,1] neg_hi:[0,0,1]
	s_movk_i32 s4, 0x6000
	v_cvt_pk_bf16_f32 v107, v108, v109
	v_add_co_u32_e32 v108, vcc, s5, v4
	v_pk_add_f32 v[104:105], v[104:105], v[112:113] neg_lo:[0,1] neg_hi:[0,1]
	s_nop 0
	v_addc_co_u32_e32 v109, vcc, 0, v5, vcc
	v_lshlrev_b32_e32 v112, 16, v134
	v_and_b32_e32 v113, 0xffff0000, v134
	v_add_co_u32_e32 v110, vcc, s4, v4
	v_pk_add_f32 v[104:105], v[104:105], v[112:113]
	s_nop 0
	v_addc_co_u32_e32 v111, vcc, 0, v5, vcc
	v_pk_fma_f32 v[112:113], v[104:105], s[6:7], v[112:113] op_sel_hi:[1,0,1] neg_lo:[0,0,1] neg_hi:[0,0,1]
	global_store_dword v[110:111], v107, off offset:-4096
	v_cvt_pk_bf16_f32 v107, v112, v113
	global_store_dword v[108:109], v107, off offset:2048
	v_pk_add_f32 v[104:105], v[104:105], v[114:115] neg_lo:[0,1] neg_hi:[0,1]
	s_waitcnt vmcnt(13)
	v_lshlrev_b32_e32 v108, 16, v139
	v_and_b32_e32 v109, 0xffff0000, v139
	v_pk_add_f32 v[104:105], v[104:105], v[108:109]
	s_mov_b64 s[4:5], 0
	v_pk_fma_f32 v[108:109], v[104:105], s[6:7], v[108:109] op_sel_hi:[1,0,1] neg_lo:[0,0,1] neg_hi:[0,0,1]
	v_pk_add_f32 v[104:105], v[104:105], v[116:117] neg_lo:[0,1] neg_hi:[0,1]
	v_cvt_pk_bf16_f32 v107, v108, v109
	v_lshlrev_b32_e32 v108, 16, v135
	v_and_b32_e32 v109, 0xffff0000, v135
	v_pk_add_f32 v[104:105], v[104:105], v[108:109]
	global_store_dword v[110:111], v107, off
	v_pk_fma_f32 v[108:109], v[104:105], s[6:7], v[108:109] op_sel_hi:[1,0,1] neg_lo:[0,0,1] neg_hi:[0,0,1]
	v_pk_add_f32 v[104:105], v[104:105], v[118:119] neg_lo:[0,1] neg_hi:[0,1]
	v_cvt_pk_bf16_f32 v107, v108, v109
	s_waitcnt vmcnt(13)
	v_lshlrev_b32_e32 v108, 16, v140
	v_and_b32_e32 v109, 0xffff0000, v140
	v_pk_add_f32 v[104:105], v[104:105], v[108:109]
	global_store_dword v[110:111], v107, off offset:2048
	v_pk_fma_f32 v[108:109], v[104:105], s[6:7], v[108:109] op_sel_hi:[1,0,1] neg_lo:[0,0,1] neg_hi:[0,0,1]
	v_pk_add_f32 v[104:105], v[104:105], v[128:129] neg_lo:[0,1] neg_hi:[0,1]
	v_cvt_pk_bf16_f32 v107, v108, v109
	v_add_co_u32_e32 v108, vcc, 0x7000, v4
	s_nop 1
	v_addc_co_u32_e32 v109, vcc, 0, v5, vcc
	global_store_dword v[108:109], v107, off

; __device__ __forceinline__ f32x2 un2(unsigned u) { return (f32x2){bf_lo(u), bf_hi(u)}; }
; __device__ __forceinline__ void st2(bf16_t* p, f32x2 v) { *(unsigned*)p = cvt_pk_bf16(v.x, v.y); }
; template <int W>
; __device__ __forceinline__ void pool_branch(const bf16_t* __restrict__ Pb, bf16_t* __restrict__ out, bool first) {
;     unsigned raw[W - 1 + TT];
; #pragma unroll
;     for (int j = 0; j < W - 1 + TT; ++j) { const int off = j - (W - 1); const int offc = (off < 0 && first) ? 0 : off;
;         unsigned r = *(const unsigned*)(Pb + (ptrdiff_t)offc * NCO); if (off < 0 && first) r = 0u; raw[j] = r; }
;     asm volatile("" ::: "memory");
;     f32x2 S = (f32x2){0.f, 0.f};
; #pragma unroll
;     for (int j = 0; j < W - 1; ++j) S += un2(raw[j]);
; #pragma unroll
;     for (int i = 0; i < TT; ++i) {
;         const f32x2 ui = un2(raw[i + W - 1]);
;         S += ui;
;         const float inv = (first && (i + 1 < W)) ? 1.0f / (float)(i + 1) : 1.0f / (float)W;
;         st2(out + (size_t)i * EW, S * inv - ui);
;         S -= un2(raw[i]);
;     }
.LBB0_405:
	s_and_b64 s[4:5], exec, s[54:55]
	s_cselect_b32 s5, 0, -1
	s_cselect_b32 s6, 0, 0xfffc5800
	s_mov_b32 s7, s5
	s_cselect_b32 s4, 0, 0xfffbc800
	v_lshl_add_u64 v[108:109], v[6:7], 0, s[6:7]
	s_cselect_b32 s6, 0, 0xfffca000
	v_lshl_add_u64 v[104:105], v[6:7], 0, s[4:5]
	s_cselect_b32 s4, 0, 0xfffe0800
	v_lshl_add_u64 v[110:111], v[6:7], 0, s[6:7]
	s_cselect_b32 s6, 0, 0xfffce800
	v_lshl_add_u64 v[106:107], s[4:5], 1, v[6:7]
	v_lshl_add_u64 v[112:113], v[6:7], 0, s[6:7]
	s_cselect_b32 s6, 0, 0xfffe9800
	s_cselect_b32 s24, 0, 0xfffd7800
	s_mov_b32 s25, s5
	v_lshl_add_u64 v[114:115], s[6:7], 1, v[6:7]
	v_lshl_add_u64 v[116:117], v[6:7], 0, s[24:25]
	global_load_dword v120, v[104:105], off nt
	global_load_dword v121, v[106:107], off nt
	global_load_dword v122, v[108:109], off nt
	global_load_dword v123, v[110:111], off nt
	global_load_dword v124, v[112:113], off nt
	global_load_dword v125, v[114:115], off nt
	global_load_dword v126, v[116:117], off nt
	v_lshl_add_u64 v[106:107], v[6:7], 0, s[4:5]
	s_cselect_b32 s4, 0, 0xffff2800
	s_cselect_b32 s24, 0, 0xfffee000
	v_lshl_add_u64 v[108:109], s[4:5], 1, v[6:7]
	v_lshl_add_u64 v[114:115], v[6:7], 0, s[4:5]
	s_cselect_b32 s4, 0, 0xffffb800
	v_lshl_add_u64 v[104:105], s[24:25], 1, v[6:7]
	v_lshl_add_u64 v[116:117], s[4:5], 1, v[6:7]
	v_lshl_add_u64 v[110:111], v[6:7], 0, s[6:7]
	v_lshl_add_u64 v[112:113], v[6:7], 0, s[24:25]
	v_lshl_add_u64 v[118:119], v[6:7], 0, s[4:5]
	global_load_dword v127, v[104:105], off nt
	global_load_dword v128, v[106:107], off nt
	global_load_dword v129, v[108:109], off nt
	global_load_dword v130, v[110:111], off nt
	global_load_dword v131, v[112:113], off nt
	s_nop 0
	global_load_dword v114, v[114:115], off nt
	s_nop 0
	global_load_dword v115, v[116:117], off nt
	s_nop 0
	global_load_dword v116, v[118:119], off nt
	s_movk_i32 s5, 0x5000
	v_add_co_u32_e32 v104, vcc, s5, v2
	global_load_dword v139, v[6:7], off nt
	s_nop 0
	v_addc_co_u32_e32 v105, vcc, 0, v3, vcc
	s_mov_b32 s4, 0xa000
	v_add_co_u32_e32 v106, vcc, s4, v2
	s_mov_b32 s4, 0x13000
	s_nop 0
	v_addc_co_u32_e32 v107, vcc, 0, v3, vcc
	v_add_co_u32_e32 v108, vcc, s4, v2
	s_mov_b32 s4, 0x1c000
	s_nop 0
	v_addc_co_u32_e32 v109, vcc, 0, v3, vcc
	v_add_co_u32_e32 v110, vcc, s4, v2
	s_mov_b32 s4, 0x25000
	s_nop 0
	v_addc_co_u32_e32 v111, vcc, 0, v3, vcc
	v_add_co_u32_e32 v112, vcc, s4, v2
	s_mov_b32 s4, 0x2e000
	s_nop 0
	v_addc_co_u32_e32 v113, vcc, 0, v3, vcc
	global_load_dword v141, v[104:105], off offset:2048 nt
	global_load_dword v142, v[106:107], off nt
	global_load_dword v143, v[8:9], off offset:2048 nt
	global_load_dword v144, v[108:109], off nt
	global_load_dword v145, v[12:13], off offset:2048 nt
	global_load_dword v146, v[110:111], off nt
	global_load_dword v147, v[10:11], off offset:2048 nt
	global_load_dword v148, v[112:113], off nt
	v_add_co_u32_e32 v104, vcc, s4, v2
	s_mov_b32 s4, 0x37000
	s_nop 0
	v_addc_co_u32_e32 v105, vcc, 0, v3, vcc
	v_add_co_u32_e32 v106, vcc, s4, v2
	s_mov_b32 s4, 0x40000
	s_nop 0
	v_addc_co_u32_e32 v107, vcc, 0, v3, vcc
	v_add_co_u32_e32 v108, vcc, s4, v2
	v_cndmask_b32_e64 v140, v200, 1.0, s[54:55]
	s_nop 0
	v_addc_co_u32_e32 v109, vcc, 0, v3, vcc
	global_load_dword v149, v[96:97], off offset:2048 nt
	global_load_dword v150, v[104:105], off nt
	global_load_dword v151, v[98:99], off offset:2048 nt
	s_nop 0
	global_load_dword v107, v[106:107], off nt
	s_nop 0
	global_load_dword v152, v[100:101], off offset:2048 nt
	global_load_dword v153, v[108:109], off nt
	global_load_dword v106, v[102:103], off offset:2048 nt
	s_movk_i32 s4, 0x2000
	s_mov_b32 s56, 0x3d800000
	s_waitcnt vmcnt(30)
	v_cndmask_b32_e64 v117, v120, 0, s[54:55]
	s_waitcnt vmcnt(29)
	v_cndmask_b32_e64 v118, v121, 0, s[54:55]
	v_lshlrev_b32_e32 v104, 16, v117
	v_and_b32_e32 v105, 0xffff0000, v117
	s_waitcnt vmcnt(28)
	v_cndmask_b32_e64 v119, v122, 0, s[54:55]
	v_pk_add_f32 v[108:109], v[104:105], 0 op_sel_hi:[1,0]
	v_lshlrev_b32_e32 v110, 16, v118
	v_and_b32_e32 v111, 0xffff0000, v118
	s_waitcnt vmcnt(27)
	v_cndmask_b32_e64 v120, v123, 0, s[54:55]
	v_pk_add_f32 v[108:109], v[108:109], v[110:111]
	v_lshlrev_b32_e32 v112, 16, v119
	v_and_b32_e32 v113, 0xffff0000, v119
	s_waitcnt vmcnt(26)
	v_cndmask_b32_e64 v121, v124, 0, s[54:55]
	v_pk_add_f32 v[108:109], v[108:109], v[112:113]
	s_waitcnt vmcnt(25)
	v_cndmask_b32_e64 v122, v125, 0, s[54:55]
	v_and_b32_e32 v117, 0xffff0000, v121
	s_waitcnt vmcnt(18)
	v_cndmask_b32_e64 v133, v114, 0, s[54:55]
	s_waitcnt vmcnt(17)
	v_cndmask_b32_e64 v135, v115, 0, s[54:55]
	v_lshlrev_b32_e32 v114, 16, v120
	v_and_b32_e32 v115, 0xffff0000, v120
	s_waitcnt vmcnt(16)
	v_cndmask_b32_e64 v137, v116, 0, s[54:55]
	v_pk_add_f32 v[108:109], v[108:109], v[114:115]
	v_lshlrev_b32_e32 v116, 16, v121
	v_cndmask_b32_e64 v123, v126, 0, s[54:55]
	v_pk_add_f32 v[108:109], v[108:109], v[116:117]
	v_lshlrev_b32_e32 v118, 16, v122
	v_and_b32_e32 v119, 0xffff0000, v122
	v_cndmask_b32_e64 v124, v127, 0, s[54:55]
	v_pk_add_f32 v[108:109], v[108:109], v[118:119]
	v_lshlrev_b32_e32 v120, 16, v123
	v_and_b32_e32 v121, 0xffff0000, v123
	v_cndmask_b32_e64 v125, v128, 0, s[54:55]
	v_pk_add_f32 v[108:109], v[108:109], v[120:121]
	v_lshlrev_b32_e32 v122, 16, v124
	v_and_b32_e32 v123, 0xffff0000, v124
	v_cndmask_b32_e64 v127, v129, 0, s[54:55]
	v_pk_add_f32 v[108:109], v[108:109], v[122:123]
	v_lshlrev_b32_e32 v124, 16, v125
	v_and_b32_e32 v125, 0xffff0000, v125
	v_cndmask_b32_e64 v129, v130, 0, s[54:55]
	v_pk_add_f32 v[108:109], v[108:109], v[124:125]
	v_lshlrev_b32_e32 v126, 16, v127
	v_and_b32_e32 v127, 0xffff0000, v127
	v_cndmask_b32_e64 v131, v131, 0, s[54:55]
	v_pk_add_f32 v[108:109], v[108:109], v[126:127]
	v_lshlrev_b32_e32 v128, 16, v129
	v_and_b32_e32 v129, 0xffff0000, v129
	v_pk_add_f32 v[108:109], v[108:109], v[128:129]
	v_lshlrev_b32_e32 v130, 16, v131
	v_and_b32_e32 v131, 0xffff0000, v131
	v_pk_add_f32 v[108:109], v[108:109], v[130:131]
	v_lshlrev_b32_e32 v132, 16, v133
	v_and_b32_e32 v133, 0xffff0000, v133
	v_pk_add_f32 v[108:109], v[108:109], v[132:133]
	v_lshlrev_b32_e32 v134, 16, v135
	v_and_b32_e32 v135, 0xffff0000, v135
	v_pk_add_f32 v[108:109], v[108:109], v[134:135]
	v_lshlrev_b32_e32 v136, 16, v137
	v_and_b32_e32 v137, 0xffff0000, v137
	v_pk_add_f32 v[108:109], v[108:109], v[136:137]
	s_waitcnt vmcnt(15)
; __device__ __forceinline__ f32x2 un2(unsigned u) { return (f32x2){bf_lo(u), bf_hi(u)}; }
; __device__ __forceinline__ void st2(bf16_t* p, f32x2 v) { *(unsigned*)p = cvt_pk_bf16(v.x, v.y); }
; template <int W>
; __device__ __forceinline__ void pool_branch(const bf16_t* __restrict__ Pb, bf16_t* __restrict__ out, bool first) {
;     ...
;     f32x2 S = (f32x2){0.f, 0.f};
; #pragma unroll
;     for (int j = 0; j < W - 1; ++j) S += un2(raw[j]);
; #pragma unroll
;     for (int i = 0; i < TT; ++i) {
;         const f32x2 ui = un2(raw[i + W - 1]);
;         S += ui;
;         const float inv = (first && (i + 1 < W)) ? 1.0f / (float)(i + 1) : 1.0f / (float)W;
;         st2(out + (size_t)i * EW, S * inv - ui);
;         S -= un2(raw[i]);
;     }
	v_lshlrev_b32_e32 v138, 16, v139
	v_and_b32_e32 v139, 0xffff0000, v139
	v_pk_add_f32 v[108:109], v[108:109], v[138:139]
	s_waitcnt vmcnt(14)
	v_pk_fma_f32 v[138:139], v[140:141], v[108:109], v[138:139] op_sel_hi:[0,1,1] neg_lo:[0,0,1] neg_hi:[0,0,1]
	v_cvt_pk_bf16_f32 v138, v138, v139
	v_pk_add_f32 v[104:105], v[108:109], v[104:105] neg_lo:[0,1] neg_hi:[0,1]
	v_lshlrev_b32_e32 v108, 16, v141
	v_and_b32_e32 v109, 0xffff0000, v141
	global_store_dword v[4:5], v138, off
	v_pk_add_f32 v[104:105], v[104:105], v[108:109]
	v_cndmask_b32_e64 v138, v200, 0.5, s[54:55]
	v_pk_fma_f32 v[108:109], v[138:139], v[104:105], v[108:109] op_sel_hi:[0,1,1] neg_lo:[0,0,1] neg_hi:[0,0,1]
	v_cvt_pk_bf16_f32 v108, v108, v109
	global_store_dword v[4:5], v108, off offset:2048
	v_pk_add_f32 v[104:105], v[104:105], v[110:111] neg_lo:[0,1] neg_hi:[0,1]
	s_waitcnt vmcnt(15)
	v_lshlrev_b32_e32 v108, 16, v142
	v_and_b32_e32 v109, 0xffff0000, v142
	v_pk_add_f32 v[104:105], v[104:105], v[108:109]
	v_cndmask_b32_e64 v110, v200, v195, s[54:55]
	v_pk_fma_f32 v[108:109], v[110:111], v[104:105], v[108:109] op_sel_hi:[0,1,1] neg_lo:[0,0,1] neg_hi:[0,0,1]
	v_cvt_pk_bf16_f32 v138, v108, v109
	v_add_co_u32_e32 v108, vcc, s14, v4
	v_pk_add_f32 v[104:105], v[104:105], v[112:113] neg_lo:[0,1] neg_hi:[0,1]
	s_nop 0
	v_addc_co_u32_e32 v109, vcc, 0, v5, vcc
	v_add_co_u32_e32 v110, vcc, s4, v4
	s_waitcnt vmcnt(14)
	v_lshlrev_b32_e32 v112, 16, v143
	v_addc_co_u32_e32 v111, vcc, 0, v5, vcc
	v_and_b32_e32 v113, 0xffff0000, v143
	global_store_dword v[110:111], v138, off offset:-4096
	v_pk_add_f32 v[104:105], v[104:105], v[112:113]
	v_cndmask_b32_e64 v138, v200, v196, s[54:55]
	v_pk_fma_f32 v[112:113], v[138:139], v[104:105], v[112:113] op_sel_hi:[0,1,1] neg_lo:[0,0,1] neg_hi:[0,0,1]
	v_cvt_pk_bf16_f32 v112, v112, v113
	global_store_dword v[108:109], v112, off offset:2048
	v_pk_add_f32 v[104:105], v[104:105], v[114:115] neg_lo:[0,1] neg_hi:[0,1]
	s_waitcnt vmcnt(15)
	v_lshlrev_b32_e32 v108, 16, v144
	v_and_b32_e32 v109, 0xffff0000, v144
	v_pk_add_f32 v[104:105], v[104:105], v[108:109]
	v_cndmask_b32_e64 v112, v200, v197, s[54:55]
	v_pk_fma_f32 v[108:109], v[112:113], v[104:105], v[108:109] op_sel_hi:[0,1,1] neg_lo:[0,0,1] neg_hi:[0,0,1]
	v_cvt_pk_bf16_f32 v108, v108, v109
	global_store_dword v[110:111], v108, off
	v_pk_add_f32 v[104:105], v[104:105], v[116:117] neg_lo:[0,1] neg_hi:[0,1]
	s_waitcnt vmcnt(15)
	v_lshlrev_b32_e32 v108, 16, v145
	v_and_b32_e32 v109, 0xffff0000, v145
	v_pk_add_f32 v[104:105], v[104:105], v[108:109]
	v_cndmask_b32_e64 v112, v200, v198, s[54:55]
	v_pk_fma_f32 v[108:109], v[112:113], v[104:105], v[108:109] op_sel_hi:[0,1,1] neg_lo:[0,0,1] neg_hi:[0,0,1]
	v_cvt_pk_bf16_f32 v108, v108, v109
	global_store_dword v[110:111], v108, off offset:2048
	v_pk_add_f32 v[104:105], v[104:105], v[118:119] neg_lo:[0,1] neg_hi:[0,1]
	s_waitcnt vmcnt(15)
	v_lshlrev_b32_e32 v108, 16, v146
	v_and_b32_e32 v109, 0xffff0000, v146
	v_pk_add_f32 v[104:105], v[104:105], v[108:109]
	v_cndmask_b32_e64 v110, v200, v199, s[54:55]
	v_pk_fma_f32 v[108:109], v[110:111], v[104:105], v[108:109] op_sel_hi:[0,1,1] neg_lo:[0,0,1] neg_hi:[0,0,1]
	v_cvt_pk_bf16_f32 v112, v108, v109
	v_add_co_u32_e32 v108, vcc, s12, v4
	s_movk_i32 s4, 0x4000
	s_nop 0
	v_addc_co_u32_e32 v109, vcc, 0, v5, vcc
	v_add_co_u32_e32 v110, vcc, s4, v4
	v_pk_add_f32 v[104:105], v[104:105], v[120:121] neg_lo:[0,1] neg_hi:[0,1]
	s_nop 0
	v_addc_co_u32_e32 v111, vcc, 0, v5, vcc
	global_store_dword v[110:111], v112, off offset:-4096
	s_waitcnt vmcnt(15)
; __device__ __forceinline__ f32x2 un2(unsigned u) { return (f32x2){bf_lo(u), bf_hi(u)}; }
; __device__ __forceinline__ void st2(bf16_t* p, f32x2 v) { *(unsigned*)p = cvt_pk_bf16(v.x, v.y); }
; template <int W>
; __device__ __forceinline__ void pool_branch(const bf16_t* __restrict__ Pb, bf16_t* __restrict__ out, bool first) {
;     ...
;     f32x2 S = (f32x2){0.f, 0.f};
; #pragma unroll
;     for (int j = 0; j < W - 1; ++j) S += un2(raw[j]);
; #pragma unroll
;     for (int i = 0; i < TT; ++i) {
;         const f32x2 ui = un2(raw[i + W - 1]);
;         S += ui;
;         const float inv = (first && (i + 1 < W)) ? 1.0f / (float)(i + 1) : 1.0f / (float)W;
;         st2(out + (size_t)i * EW, S * inv - ui);
;         S -= un2(raw[i]);
;     }
	v_lshlrev_b32_e32 v112, 16, v147
	v_and_b32_e32 v113, 0xffff0000, v147
	v_pk_add_f32 v[104:105], v[104:105], v[112:113]
	v_cndmask_b32_e64 v114, v200, v194, s[54:55]
	v_pk_fma_f32 v[112:113], v[114:115], v[104:105], v[112:113] op_sel_hi:[0,1,1] neg_lo:[0,0,1] neg_hi:[0,0,1]
	v_cvt_pk_bf16_f32 v112, v112, v113
	global_store_dword v[108:109], v112, off offset:2048
	v_pk_add_f32 v[104:105], v[104:105], v[122:123] neg_lo:[0,1] neg_hi:[0,1]
	s_waitcnt vmcnt(15)
	v_lshlrev_b32_e32 v108, 16, v148
	v_and_b32_e32 v109, 0xffff0000, v148
	v_pk_add_f32 v[104:105], v[104:105], v[108:109]
	v_cndmask_b32_e64 v112, v200, v201, s[54:55]
	v_pk_fma_f32 v[108:109], v[112:113], v[104:105], v[108:109] op_sel_hi:[0,1,1] neg_lo:[0,0,1] neg_hi:[0,0,1]
	v_cvt_pk_bf16_f32 v108, v108, v109
	global_store_dword v[110:111], v108, off
	v_pk_add_f32 v[104:105], v[104:105], v[124:125] neg_lo:[0,1] neg_hi:[0,1]
	s_waitcnt vmcnt(15)
	v_lshlrev_b32_e32 v108, 16, v149
	v_and_b32_e32 v109, 0xffff0000, v149
	v_pk_add_f32 v[104:105], v[104:105], v[108:109]
	v_cndmask_b32_e64 v112, v200, v202, s[54:55]
	v_pk_fma_f32 v[108:109], v[112:113], v[104:105], v[108:109] op_sel_hi:[0,1,1] neg_lo:[0,0,1] neg_hi:[0,0,1]
	v_cvt_pk_bf16_f32 v108, v108, v109
	global_store_dword v[110:111], v108, off offset:2048
	v_pk_add_f32 v[104:105], v[104:105], v[126:127] neg_lo:[0,1] neg_hi:[0,1]
	s_waitcnt vmcnt(15)
	v_lshlrev_b32_e32 v108, 16, v150
	v_and_b32_e32 v109, 0xffff0000, v150
	v_pk_add_f32 v[104:105], v[104:105], v[108:109]
	v_cndmask_b32_e64 v110, v200, v203, s[54:55]
	v_pk_fma_f32 v[108:109], v[110:111], v[104:105], v[108:109] op_sel_hi:[0,1,1] neg_lo:[0,0,1] neg_hi:[0,0,1]
	v_cvt_pk_bf16_f32 v112, v108, v109
	v_add_co_u32_e32 v108, vcc, s5, v4
	s_movk_i32 s4, 0x6000
	s_nop 0
	v_addc_co_u32_e32 v109, vcc, 0, v5, vcc
	v_add_co_u32_e32 v110, vcc, s4, v4
	v_pk_add_f32 v[104:105], v[104:105], v[128:129] neg_lo:[0,1] neg_hi:[0,1]
	s_nop 0
	v_addc_co_u32_e32 v111, vcc, 0, v5, vcc
	global_store_dword v[110:111], v112, off offset:-4096
	s_waitcnt vmcnt(15)
	v_lshlrev_b32_e32 v112, 16, v151
	v_and_b32_e32 v113, 0xffff0000, v151
	v_pk_add_f32 v[104:105], v[104:105], v[112:113]
	v_cndmask_b32_e64 v114, v200, v204, s[54:55]
	v_pk_fma_f32 v[112:113], v[114:115], v[104:105], v[112:113] op_sel_hi:[0,1,1] neg_lo:[0,0,1] neg_hi:[0,0,1]
	v_cvt_pk_bf16_f32 v112, v112, v113
	global_store_dword v[108:109], v112, off offset:2048
	v_pk_add_f32 v[104:105], v[104:105], v[130:131] neg_lo:[0,1] neg_hi:[0,1]
	s_waitcnt vmcnt(15)
	v_lshlrev_b32_e32 v108, 16, v107
	v_and_b32_e32 v109, 0xffff0000, v107
	v_pk_add_f32 v[104:105], v[104:105], v[108:109]
	v_cndmask_b32_e64 v112, v200, v205, s[54:55]
	v_pk_fma_f32 v[108:109], v[112:113], v[104:105], v[108:109] op_sel_hi:[0,1,1] neg_lo:[0,0,1] neg_hi:[0,0,1]
	v_cvt_pk_bf16_f32 v107, v108, v109
	v_pk_add_f32 v[104:105], v[104:105], v[132:133] neg_lo:[0,1] neg_hi:[0,1]
	s_waitcnt vmcnt(14)
	v_lshlrev_b32_e32 v108, 16, v152
	v_and_b32_e32 v109, 0xffff0000, v152
	v_pk_add_f32 v[104:105], v[104:105], v[108:109]
	v_cndmask_b32_e64 v112, v200, v206, s[54:55]
	v_pk_fma_f32 v[108:109], v[112:113], v[104:105], v[108:109] op_sel_hi:[0,1,1] neg_lo:[0,0,1] neg_hi:[0,0,1]
	global_store_dword v[110:111], v107, off
	v_cvt_pk_bf16_f32 v107, v108, v109
	v_pk_add_f32 v[104:105], v[104:105], v[134:135] neg_lo:[0,1] neg_hi:[0,1]
	s_waitcnt vmcnt(14)
	v_lshlrev_b32_e32 v108, 16, v153
	v_and_b32_e32 v109, 0xffff0000, v153
	global_store_dword v[110:111], v107, off offset:2048
	v_pk_add_f32 v[104:105], v[104:105], v[108:109]
	v_cndmask_b32_e64 v110, v200, v207, s[54:55]
	v_pk_fma_f32 v[108:109], v[110:111], v[104:105], v[108:109] op_sel_hi:[0,1,1] neg_lo:[0,0,1] neg_hi:[0,0,1]
	v_cvt_pk_bf16_f32 v107, v108, v109
	v_add_co_u32_e32 v108, vcc, 0x7000, v4
	v_pk_add_f32 v[104:105], v[104:105], v[136:137] neg_lo:[0,1] neg_hi:[0,1]
	s_nop 0
	v_addc_co_u32_e32 v109, vcc, 0, v5, vcc
	global_store_dword v[108:109], v107, off
	s_cbranch_execz .LBB0_385
	s_branch .LBB0_386
